# S5 phases: state loads of the sample step hoisted (one wait instead of 16), block-loop waits no longer cover prefetch/stores, chunk-prefix loads batched, decode wave no longer takes S5 units; skinny G
# speedup vs baseline: 1.0766x; 1.0155x over previous
; __global__ void __launch_bounds__(512, 2) fwd(Params P) {
;     ...
;         for (int r2 = 0; r2 < NREP(15); ++r2) for (int id = blockIdx.x * 8 + wave; id < 4672; id += gridDim.x * 8) {
;             if (id < 2048 && (id & 7) == 0) { mlstm_decode_wave(P, shm + wave * S5_WL, id >> 3); continue; }
;             const int sidx = id < 2048 ? id - (id >> 3) - 1 : 1792 + (id - 2048);
;             if (sidx < 3904) s5_unit<0>(P, shm + wave * S5_WL, sidx); else s5_unit<2>(P, shm + wave * S5_WL, sidx - 3904); }
.LBB0_343:
	v_lshl_add_u32 v151, s94, 3, v215
	s_lshl_b32 s1, s96, 3
	s_cmpk_eq_i32 s96, 0x100
	s_cselect_b32 s0, 0x700, s1
	v_mov_b32_e32 v242, s0
	v_mov_b32_e32 v240, s94
	v_sub_u32_e32 v240, 0x7ff, v240
	v_mov_b32_e32 v241, 0x4000
	v_cmp_eq_u32_e32 vcc, 0, v215
	s_nop 1
	v_cndmask_b32_e32 v240, v240, v241, vcc
	v_mov_b32_e32 v241, s1
	s_cselect_b64 vcc, -1, 0
	s_nop 1
	v_cndmask_b32_e32 v240, v241, v240, vcc
	s_movk_i32 s0, 0x1240
	v_cmp_gt_i32_e32 vcc, s0, v151
	s_barrier
	s_and_saveexec_b64 s[16:17], vcc
	s_cbranch_execz .LBB0_376
	s_movk_i32 s0, 0x4200
	v_mad_u32_u24 v153, v215, s0, 0
	v_add_u32_e32 v0, 0x1000, v153
	v_cndmask_b32_e64 v2, v0, v153, s[4:5]
	v_lshrrev_b32_e32 v0, 1, v146
	v_and_b32_e32 v150, 8, v0
	v_lshrrev_b32_e32 v1, 4, v146
	v_lshl_add_u32 v2, v150, 1, v2
	v_lshlrev_b32_e32 v3, 5, v147
	v_mov_b32_e32 v0, 0
	v_add_u32_e32 v183, v2, v3
	v_mul_u32_u24_e32 v2, 0x820, v1
	v_add3_u32 v212, v153, v2, v64
	v_and_b32_e32 v2, 48, v146
	v_lshlrev_b32_e32 v4, 3, v146
	v_mov_b32_e32 v5, v0
	v_readlane_b32 s52, v245, 34
	v_add3_u32 v213, v153, v3, v2
	v_mul_u32_u24_e32 v3, 0x110, v147
	v_add_u32_e32 v218, v153, v4
	v_lshl_add_u64 v[4:5], s[12:13], 0, v[4:5]
	s_mov_b64 s[0:1], 0x1e5cb000
	v_lshlrev_b32_e32 v158, 4, v146
	v_mov_b32_e32 v159, v0
	v_readlane_b32 s56, v245, 38
	v_readlane_b32 s57, v245, 39
	v_readlane_b32 s58, v245, 40
	v_readlane_b32 s59, v245, 41
	v_readlane_b32 s60, v245, 42
	v_readlane_b32 s61, v245, 43
	v_readlane_b32 s62, v245, 44
	v_readlane_b32 s63, v245, 45
	v_readlane_b32 s64, v245, 46
	v_readlane_b32 s65, v245, 47
	v_readlane_b32 s66, v245, 48
	v_readlane_b32 s67, v245, 49
	v_add3_u32 v216, v153, v3, v2
	v_lshl_add_u64 v[156:157], v[4:5], 0, s[0:1]
	v_readlane_b32 s72, v245, 18
	v_lshl_add_u64 v[4:5], s[66:67], 0, v[158:159]
	v_and_b32_e32 v3, 0x1c0, v214
	v_readlane_b32 s56, v245, 2
	s_add_u32 s18, s12, 0x2100000
	v_readlane_b32 s73, v245, 19
	v_cmp_eq_u32_e64 s[6:7], 0, v3
	v_mov_b32_e32 v3, v0
	v_readlane_b32 s70, v245, 16
	v_readlane_b32 s71, v245, 17
	v_lshlrev_b32_e32 v152, 2, v1
	s_addc_u32 s19, s13, 0
	v_lshlrev_b32_e32 v1, 7, v1
	v_lshlrev_b32_e32 v154, 2, v146
	s_mov_b64 s[0:1], 0xc924040
	v_lshl_add_u64 v[166:167], s[70:71], 0, v[2:3]
	v_lshl_add_u64 v[168:169], s[72:73], 0, v[2:3]
	v_and_b32_e32 v2, 16, v146
	v_lshlrev_b32_e32 v6, 6, v147
	v_add3_u32 v217, v153, v1, v148
	v_sub_u32_e32 v1, 0, v154
	v_readlane_b32 s82, v245, 28
	v_readlane_b32 s83, v245, 29
	s_add_u32 s20, s12, 0x12dc2000
	v_readlane_b32 s53, v245, 35
	v_readlane_b32 s54, v245, 36
	v_readlane_b32 s55, v245, 37
	v_lshl_add_u64 v[164:165], v[4:5], 0, s[0:1]
	v_lshl_add_u64 v[2:3], s[12:13], 0, v[2:3]
	s_mov_b64 s[0:1], 0x458a000
	s_movk_i32 s25, 0x1000
	v_lshl_add_u32 v155, v146, 6, v153
	v_lshl_add_u64 v[160:161], s[46:47], 0, v[158:159]
	v_add_u32_e32 v219, v153, v158
	v_lshl_add_u64 v[162:163], s[82:83], 0, v[158:159]
	s_addc_u32 s21, s13, 0
	s_lshl_b32 s54, s96, 3
	v_lshl_add_u64 v[170:171], v[2:3], 0, s[0:1]
	s_mov_b64 s[22:23], 0
	s_mov_b32 s33, 0x3fb8aa3b
	s_mov_b32 s55, 0xc2ce8ed0
	s_mov_b32 s50, 0x42b17218
	s_brev_b32 s51, 18
	s_mov_b32 s93, 0xfe5163ab
	v_mov_b32_e32 v220, 0x3c0881c4
	v_mov_b32_e32 v221, 0xbab64f3b
	s_movk_i32 s89, 0x1f8
	v_lshlrev_b32_e32 v222, 2, v6
	s_movk_i32 s90, 0x4800
	s_movk_i32 s91, 0x7fff
	s_mov_b32 s92, 0x4524000
	s_mov_b32 s52, 0x4724000
	v_add_u32_e32 v223, v218, v1
	s_mov_b32 s53, 0x7060302
	s_mov_b32 s88, 0x88888889
	s_mov_b32 s24, 0x3d800000
	v_mov_b32_e32 v224, 0x3ecc95a3
	s_mov_b64 s[26:27], 0x8000
	v_mov_b32_e32 v225, 0x3727c5ac
	v_mov_b32_e32 v226, 0xffffff00
	v_mov_b32_e32 v227, 0x7f800000
	v_not_b32_e32 v228, 63
	v_not_b32_e32 v229, 31
	v_mov_b32_e32 v230, 0x7fc00000
	v_mov_b32_e32 v172, 0x3f317218
	v_mov_b32_e32 v231, 0xff800000
	v_readlane_b32 s74, v245, 20
	v_readlane_b32 s75, v245, 21
	v_readlane_b32 s76, v245, 22
	v_readlane_b32 s77, v245, 23
	v_readlane_b32 s78, v245, 24
	v_readlane_b32 s79, v245, 25
	v_readlane_b32 s80, v245, 26
	v_readlane_b32 s81, v245, 27
	v_readlane_b32 s84, v245, 30
	v_readlane_b32 s85, v245, 31
	v_readlane_b32 s86, v245, 32
	v_readlane_b32 s87, v245, 33
	v_readlane_b32 s57, v245, 3
	v_readlane_b32 s58, v245, 4
	v_readlane_b32 s59, v245, 5
	v_readlane_b32 s60, v245, 6
	v_readlane_b32 s61, v245, 7
	v_readlane_b32 s62, v245, 8
	v_readlane_b32 s63, v245, 9
	v_readlane_b32 s64, v245, 10
	v_readlane_b32 s65, v245, 11
	v_readlane_b32 s66, v245, 12
	v_readlane_b32 s67, v245, 13
	v_readlane_b32 s68, v245, 14
	v_readlane_b32 s69, v245, 15
	s_branch .LBB0_347

; __global__ void __launch_bounds__(512, 2) fwd(Params P) {
;     ...
;         for (int r2 = 0; r2 < NREP(15); ++r2) for (int id = blockIdx.x * 8 + wave; id < 4672; id += gridDim.x * 8) {
.LBB0_346:
	s_or_b64 exec, exec, s[0:1]
	v_cmp_gt_i32_e32 vcc, 0x800, v151
	s_nop 1
	v_cndmask_b32_e32 v241, v242, v240, vcc
	v_add_u32_e32 v151, v241, v151
	s_movk_i32 s0, 0x123f
	v_cmp_lt_i32_e32 vcc, s0, v151
	s_or_b64 s[22:23], vcc, s[22:23]
	s_andn2_b64 exec, exec, s[22:23]
	s_cbranch_execz .LBB0_376

; __device__ __forceinline__ void s5_setup(const Params& P, int g, int p, float& ar, float& ai, float (&Br)[16], float (&Bi)[16]) {
;     const int gp = g * 64 + p;
;     const float lre = P.in[10][gp], lim = P.in[11][gp], dt = expf(P.in[12][gp]);
;     const float zr = lre * dt, zi = lim * dt; const float er = expf(zr); float sn, cs; sincosf(zi, &sn, &cs);
;     ar = er * cs; ai = er * sn;
;     const float nr = ar - 1.0f, ni = ai, den = 1.0f / (lre * lre + lim * lim);
;     const float cr = (nr * lre + ni * lim) * den, ci = (ni * lre - nr * lim) * den;
;     const f32x4* bre = (const f32x4*)(P.in[13] + (size_t)gp * 16); const f32x4* bim = (const f32x4*)(P.in[14] + (size_t)gp * 16);
; #pragma unroll
;     for (int c4 = 0; c4 < 4; ++c4) { const f32x4 x = bre[c4], y = bim[c4];
; #pragma unroll
;         for (int e = 0; e < 4; ++e) { Br[c4 * 4 + e] = cr * x[e] - ci * y[e]; Bi[c4 * 4 + e] = cr * y[e] + ci * x[e]; } }
; }
.LBB0_353:
	s_or_b64 exec, exec, s[0:1]
	v_add_u32_e32 v3, 0xfffff0c0, v3
	v_lshrrev_b32_e32 v40, 2, v3
	s_waitcnt vmcnt(0)
	v_mul_f32_e32 v3, v34, v6
	v_mul_f32_e32 v6, 0x3fb8aa3b, v3
	v_fma_f32 v9, v3, s33, -v6
	v_rndne_f32_e32 v10, v6
	v_fmac_f32_e32 v9, 0x32a5705f, v3
	v_sub_f32_e32 v6, v6, v10
	v_add_f32_e32 v6, v6, v9
	v_exp_f32_e32 v6, v6
	v_cvt_i32_f32_e32 v9, v10
	v_cmp_ngt_f32_e32 vcc, s55, v3
	v_xor_b32_e32 v5, v5, v4
	s_brev_b32 s0, 1
	v_ldexp_f32 v6, v6, v9
	v_cndmask_b32_e32 v6, 0, v6, vcc
	v_cmp_nlt_f32_e32 vcc, s50, v3
	v_mul_f32_e32 v3, v7, v7
	v_readlane_b32 s56, v245, 2
	v_cndmask_b32_e32 v42, v227, v6, vcc
	v_fmamk_f32 v6, v3, 0xb94c1982, v220
	v_fmaak_f32 v6, v3, v6, 0xbe2aaa9d
	v_mul_f32_e32 v6, v3, v6
	v_fmac_f32_e32 v7, v7, v6
	v_fmamk_f32 v6, v3, 0x37d75334, v221
	v_fmaak_f32 v6, v3, v6, 0x3d2aabf7
	v_fmaak_f32 v6, v3, v6, 0xbf000004
	v_fma_f32 v3, v3, v6, 1.0
	v_lshlrev_b32_e32 v6, 30, v8
	v_and_b32_e32 v8, 1, v8
	v_cmp_eq_u32_e32 vcc, 0, v8
	v_and_b32_e32 v9, 0x80000000, v6
	v_lshlrev_b32_e32 v30, 6, v2
	v_cndmask_b32_e32 v8, v3, v7, vcc
	v_xor_b32_e32 v7, 0x80000000, v7
	v_xor_b32_e32 v5, v5, v8
	v_cndmask_b32_e32 v3, v7, v3, vcc
	v_xor_b32_e32 v5, v5, v9
	v_bitop3_b32 v3, v3, v6, s0 bitop3:0x78
	v_cmp_class_f32_e64 vcc, v4, s89
	v_readlane_b32 s66, v245, 12
	v_readlane_b32 s67, v245, 13
	v_cndmask_b32_e32 v43, v230, v3, vcc
	v_cndmask_b32_e32 v3, v230, v5, vcc
	v_pk_mul_f32 v[4:5], v[34:35], v[34:35]
	v_mul_f32_e32 v38, v42, v3
	v_add_f32_e32 v3, v4, v5
	v_div_scale_f32 v4, s[0:1], v3, v3, 1.0
	v_rcp_f32_e32 v5, v4
	v_readlane_b32 s68, v245, 14
	v_readlane_b32 s69, v245, 15
	v_fma_f32 v39, v42, v43, -1.0
	v_fma_f32 v6, -v4, v5, 1.0
	v_fmac_f32_e32 v5, v6, v5
	v_div_scale_f32 v6, vcc, 1.0, v3, 1.0
	v_mul_f32_e32 v7, v6, v5
	v_fma_f32 v8, -v4, v7, v6
	v_fmac_f32_e32 v7, v8, v5
	v_fma_f32 v4, -v4, v7, v6
	v_div_fmas_f32 v4, v4, v5, v7
	v_div_fixup_f32 v36, v4, v3, 1.0
	global_load_dwordx4 v[2:5], v30, s[66:67] offset:48
	global_load_dwordx4 v[10:13], v30, s[66:67] offset:32
	global_load_dwordx4 v[18:21], v30, s[66:67] offset:16
	global_load_dwordx4 v[26:29], v30, s[66:67]
	global_load_dwordx4 v[6:9], v30, s[68:69] offset:48
	global_load_dwordx4 v[14:17], v30, s[68:69] offset:32
	global_load_dwordx4 v[22:25], v30, s[68:69] offset:16
	s_nop 0
	global_load_dwordx4 v[30:33], v30, s[68:69]
	v_mov_b32_e32 v46, v35
	v_pk_mul_f32 v[46:47], v[46:47], v[38:39] op_sel:[0,1] op_sel_hi:[0,0]
	v_pk_fma_f32 v[48:49], v[34:35], v[38:39], v[46:47] neg_lo:[0,0,1] neg_hi:[0,0,1]
	v_pk_fma_f32 v[34:35], v[34:35], v[38:39], v[46:47] op_sel_hi:[0,1,1]
	v_mov_b32_e32 v49, v35
	v_pk_mul_f32 v[34:35], v[36:37], v[48:49] op_sel_hi:[0,1]
	v_readlane_b32 s57, v245, 3
	v_readlane_b32 s58, v245, 4
	v_readlane_b32 s59, v245, 5
	v_readlane_b32 s60, v245, 6
	v_readlane_b32 s61, v245, 7
	v_readlane_b32 s62, v245, 8
	v_readlane_b32 s63, v245, 9
	v_readlane_b32 s64, v245, 10
	v_readlane_b32 s65, v245, 11
	v_readlane_b32 s70, v245, 16
	v_readlane_b32 s71, v245, 17
	v_and_b32_e32 v44, 0x3fffff0, v40
	v_readlane_b32 s56, v245, 18
	v_readlane_b32 s0, v245, 54
	v_add_u32_e32 v41, 0x2000, v44
	v_readlane_b32 s58, v245, 20
	v_readlane_b32 s59, v245, 21
	v_readlane_b32 s1, v245, 55
	v_readlane_b32 s57, v245, 19
	v_readlane_b32 s60, v245, 22
	v_readlane_b32 s61, v245, 23
	v_readlane_b32 s62, v245, 24
	v_readlane_b32 s63, v245, 25
	v_readlane_b32 s64, v245, 26
	v_readlane_b32 s65, v245, 27
	v_readlane_b32 s66, v245, 28
	v_readlane_b32 s67, v245, 29
	v_readlane_b32 s68, v245, 30
	v_readlane_b32 s69, v245, 31
	v_readlane_b32 s70, v245, 32
	v_readlane_b32 s71, v245, 33
	s_waitcnt vmcnt(4)
	v_mov_b32_e32 v37, v26
	s_waitcnt vmcnt(0)
	v_mov_b32_e32 v36, v30
	v_pk_mul_f32 v[36:37], v[36:37], v[34:35]
	s_nop 0
	v_sub_f32_e32 v39, v37, v36
	v_mov_b32_e32 v36, v26
	v_mov_b32_e32 v37, v30
	v_pk_mul_f32 v[36:37], v[36:37], v[34:35]
	v_mov_b32_e32 v26, v31
	v_mov_b32_e32 v30, v27
	v_add_f32_e32 v45, v37, v36
	v_pk_mul_f32 v[36:37], v[26:27], v[34:35]
	v_pk_mul_f32 v[26:27], v[30:31], v[34:35]
	v_sub_f32_e32 v36, v37, v36
	v_add_f32_e32 v30, v27, v26
	v_mov_b32_e32 v26, v32
	v_mov_b32_e32 v27, v28
	v_pk_mul_f32 v[26:27], v[26:27], v[34:35]
	s_nop 0
	v_sub_f32_e32 v31, v27, v26
	v_mov_b32_e32 v26, v28
	v_mov_b32_e32 v27, v32
	v_pk_mul_f32 v[26:27], v[26:27], v[34:35]
	v_mov_b32_e32 v28, v33
	v_add_f32_e32 v37, v27, v26
	v_pk_mul_f32 v[26:27], v[28:29], v[34:35]
	v_mov_b32_e32 v32, v29
	v_sub_f32_e32 v28, v27, v26
	v_pk_mul_f32 v[26:27], v[32:33], v[34:35]
	s_nop 0
	v_add_f32_e32 v29, v27, v26
	v_mov_b32_e32 v26, v22
	v_mov_b32_e32 v27, v18
	v_pk_mul_f32 v[26:27], v[26:27], v[34:35]
	s_nop 0
	v_sub_f32_e32 v32, v27, v26
	v_mov_b32_e32 v26, v18
	v_mov_b32_e32 v27, v22
	v_pk_mul_f32 v[26:27], v[26:27], v[34:35]
	v_mov_b32_e32 v18, v23
	v_mov_b32_e32 v22, v19
	v_add_f32_e32 v33, v26, v27
	v_pk_mul_f32 v[26:27], v[18:19], v[34:35]
	v_pk_mul_f32 v[18:19], v[22:23], v[34:35]
	v_sub_f32_e32 v26, v27, v26
	v_add_f32_e32 v27, v18, v19
	v_mov_b32_e32 v18, v24
	v_mov_b32_e32 v19, v20
	v_pk_mul_f32 v[18:19], v[18:19], v[34:35]
	s_nop 0
	v_sub_f32_e32 v22, v19, v18
	v_mov_b32_e32 v18, v20
	v_mov_b32_e32 v19, v24
	v_pk_mul_f32 v[18:19], v[18:19], v[34:35]
	v_mov_b32_e32 v20, v25
	v_add_f32_e32 v46, v18, v19
	v_pk_mul_f32 v[18:19], v[20:21], v[34:35]
	v_mov_b32_e32 v24, v21
	v_sub_f32_e32 v20, v19, v18
	v_pk_mul_f32 v[18:19], v[24:25], v[34:35]
	s_nop 0
	v_add_f32_e32 v25, v18, v19
	v_mov_b32_e32 v18, v14
	v_mov_b32_e32 v19, v10
	v_pk_mul_f32 v[18:19], v[18:19], v[34:35]
	s_nop 0
	v_sub_f32_e32 v21, v19, v18
	v_mov_b32_e32 v18, v10
	v_mov_b32_e32 v19, v14
	v_pk_mul_f32 v[18:19], v[18:19], v[34:35]
; __device__ __forceinline__ unsigned cvt_pk_bf16(float lo, float hi) { unsigned r; asm volatile("v_cvt_pk_bf16_f32 %0, %1, %2" : "=v"(r) : "v"(lo), "v"(hi)); return r; }
; __device__ __forceinline__ float bflo(unsigned w) { return __uint_as_float(w << 16); }
; __device__ __forceinline__ float bfhi(unsigned w) { return __uint_as_float(w & 0xffff0000u); }
; template <int MODE>
; __device__ __forceinline__ void s5_unit(const Params& P, unsigned char* wl, const int id) {
;     ...
;     { s5_setup(P, g, lane, ar, ai, Br, Bi);
;       u32x4 w[4], v[4];
; #pragma unroll
;       for (int i = 0; i < 4; ++i) { unsigned hw[4], lw[4];
; #pragma unroll
;           for (int e = 0; e < 4; ++e) { const int c0 = (i & 1) * 8 + 2 * e; const float x0 = (i < 2) ? Br[c0] : Bi[c0], x1 = (i < 2) ? Br[c0 + 1] : Bi[c0 + 1];
;               const unsigned h = cvt_pk_bf16(x0, x1); hw[e] = h; lw[e] = cvt_pk_bf16(x0 - bflo(h), x1 - bfhi(h)); }
;           w[i] = (u32x4){hw[0], hw[1], hw[2], hw[3]}; v[i] = (u32x4){lw[0], lw[1], lw[2], lw[3]}; }
;       u32x4* bt = (u32x4*)(Btab + lane * 32); bt[0] = w[0]; bt[1] = w[1]; bt[2] = w[2]; bt[3] = w[3];
;       u32x4* lt = (u32x4*)((bf16_t*)buf + lane * 32); lt[0] = v[0]; lt[1] = v[1]; lt[2] = v[2]; lt[3] = v[3]; }
;     asm volatile("s_waitcnt lgkmcnt(0)" ::: "memory");
;     const bf16x8 zf = (bf16x8){0, 0, 0, 0, 0, 0, 0, 0};
;     bf16x8 bfr[8];
; #pragma unroll
;     for (int nn = 0; nn < 8; ++nn) bfr[nn] = *(const bf16x8*)((q < 2 ? Btab : (const bf16_t*)buf) + (16 * nn + l16) * 16 + 8 * (q & 1));
	v_mov_b32_e32 v10, v15
	v_mov_b32_e32 v14, v11
	v_add_f32_e32 v47, v18, v19
	v_pk_mul_f32 v[18:19], v[10:11], v[34:35]
	v_pk_mul_f32 v[10:11], v[14:15], v[34:35]
	v_sub_f32_e32 v18, v19, v18
	v_add_f32_e32 v48, v10, v11
	v_mov_b32_e32 v10, v16
	v_mov_b32_e32 v11, v12
	v_pk_mul_f32 v[10:11], v[10:11], v[34:35]
	s_nop 0
	v_sub_f32_e32 v15, v11, v10
	v_mov_b32_e32 v10, v12
	v_mov_b32_e32 v11, v16
	v_pk_mul_f32 v[10:11], v[10:11], v[34:35]
	v_mov_b32_e32 v12, v17
	v_add_f32_e32 v49, v10, v11
	v_pk_mul_f32 v[10:11], v[12:13], v[34:35]
	v_mov_b32_e32 v16, v13
	v_sub_f32_e32 v12, v11, v10
	v_pk_mul_f32 v[10:11], v[16:17], v[34:35]
	s_nop 0
	v_add_f32_e32 v50, v10, v11
	v_mov_b32_e32 v10, v6
	v_mov_b32_e32 v11, v2
	v_pk_mul_f32 v[10:11], v[10:11], v[34:35]
	s_nop 0
	v_sub_f32_e32 v13, v11, v10
	v_mov_b32_e32 v10, v2
	v_mov_b32_e32 v11, v6
	v_pk_mul_f32 v[10:11], v[10:11], v[34:35]
	v_mov_b32_e32 v2, v7
	v_mov_b32_e32 v6, v3
	v_add_f32_e32 v51, v10, v11
	v_pk_mul_f32 v[10:11], v[2:3], v[34:35]
	v_pk_mul_f32 v[2:3], v[6:7], v[34:35]
	v_sub_f32_e32 v16, v11, v10
	v_add_f32_e32 v52, v2, v3
	v_mov_b32_e32 v2, v8
	v_mov_b32_e32 v3, v4
	v_pk_mul_f32 v[2:3], v[2:3], v[34:35]
	s_nop 0
	v_sub_f32_e32 v17, v3, v2
	v_mov_b32_e32 v2, v4
	v_mov_b32_e32 v3, v8
	v_pk_mul_f32 v[2:3], v[2:3], v[34:35]
	v_mov_b32_e32 v4, v9
	v_add_f32_e32 v53, v2, v3
	v_pk_mul_f32 v[2:3], v[4:5], v[34:35]
	v_mov_b32_e32 v8, v5
	v_sub_f32_e32 v19, v3, v2
	v_pk_mul_f32 v[2:3], v[8:9], v[34:35]
	s_nop 0
	v_add_f32_e32 v34, v2, v3
	v_cvt_pk_bf16_f32 v2, v39, v36
	s_nop 0
	v_lshlrev_b32_e32 v3, 16, v2
	v_and_b32_e32 v4, 0xffff0000, v2
	v_sub_f32_e32 v3, v39, v3
	v_sub_f32_e32 v4, v36, v4
	v_cvt_pk_bf16_f32 v6, v3, v4
	v_cvt_pk_bf16_f32 v3, v31, v28
	v_or_b32_e32 v36, v41, v147
	v_lshlrev_b32_e32 v4, 16, v3
	v_and_b32_e32 v5, 0xffff0000, v3
	v_sub_f32_e32 v4, v31, v4
	v_sub_f32_e32 v5, v28, v5
	v_cvt_pk_bf16_f32 v7, v4, v5
	v_cvt_pk_bf16_f32 v4, v32, v26
	s_nop 0
	v_lshlrev_b32_e32 v5, 16, v4
	v_and_b32_e32 v8, 0xffff0000, v4
	v_sub_f32_e32 v5, v32, v5
	v_sub_f32_e32 v8, v26, v8
	v_cvt_pk_bf16_f32 v8, v5, v8
	v_cvt_pk_bf16_f32 v5, v22, v20
	s_nop 0
	v_lshlrev_b32_e32 v9, 16, v5
	v_and_b32_e32 v10, 0xffff0000, v5
	v_sub_f32_e32 v9, v22, v9
	v_sub_f32_e32 v10, v20, v10
	v_cvt_pk_bf16_f32 v9, v9, v10
	v_cvt_pk_bf16_f32 v10, v21, v18
	s_nop 0
	v_lshlrev_b32_e32 v11, 16, v10
	v_and_b32_e32 v14, 0xffff0000, v10
	v_sub_f32_e32 v11, v21, v11
	v_sub_f32_e32 v14, v18, v14
	v_cvt_pk_bf16_f32 v14, v11, v14
	v_cvt_pk_bf16_f32 v11, v15, v12
	s_nop 0
	v_lshlrev_b32_e32 v18, 16, v11
	v_sub_f32_e32 v15, v15, v18
	v_and_b32_e32 v18, 0xffff0000, v11
	v_sub_f32_e32 v12, v12, v18
	v_cvt_pk_bf16_f32 v15, v15, v12
	v_cvt_pk_bf16_f32 v12, v13, v16
	s_nop 0
	v_lshlrev_b32_e32 v18, 16, v12
	v_sub_f32_e32 v13, v13, v18
	v_and_b32_e32 v18, 0xffff0000, v12
	v_sub_f32_e32 v16, v16, v18
	v_cvt_pk_bf16_f32 v16, v13, v16
	v_cvt_pk_bf16_f32 v13, v17, v19
	s_nop 0
	v_lshlrev_b32_e32 v18, 16, v13
	v_sub_f32_e32 v17, v17, v18
	v_and_b32_e32 v18, 0xffff0000, v13
	v_sub_f32_e32 v18, v19, v18
	v_cvt_pk_bf16_f32 v17, v17, v18
	v_cvt_pk_bf16_f32 v18, v45, v30
	s_nop 0
	v_lshlrev_b32_e32 v19, 16, v18
	v_and_b32_e32 v20, 0xffff0000, v18
	v_sub_f32_e32 v19, v45, v19
	v_sub_f32_e32 v20, v30, v20
	v_cvt_pk_bf16_f32 v22, v19, v20
	v_cvt_pk_bf16_f32 v19, v37, v29
	v_lshlrev_b32_e32 v45, 4, v1
	v_lshlrev_b32_e32 v20, 16, v19
	v_and_b32_e32 v21, 0xffff0000, v19
	v_sub_f32_e32 v20, v37, v20
	v_sub_f32_e32 v21, v29, v21
	v_cvt_pk_bf16_f32 v23, v20, v21
	v_cvt_pk_bf16_f32 v20, v33, v27
	v_mov_b32_e32 v37, v0
	v_lshlrev_b32_e32 v21, 16, v20
	v_and_b32_e32 v24, 0xffff0000, v20
	v_sub_f32_e32 v21, v33, v21
	v_sub_f32_e32 v24, v27, v24
	v_cvt_pk_bf16_f32 v24, v21, v24
	v_cvt_pk_bf16_f32 v21, v46, v25
	s_nop 0
	v_lshlrev_b32_e32 v26, 16, v21
	v_and_b32_e32 v27, 0xffff0000, v21
	v_sub_f32_e32 v26, v46, v26
	v_sub_f32_e32 v25, v25, v27
	v_cvt_pk_bf16_f32 v25, v26, v25
	v_cvt_pk_bf16_f32 v26, v47, v48
	s_nop 0
	v_lshlrev_b32_e32 v27, 16, v26
	v_and_b32_e32 v28, 0xffff0000, v26
	v_sub_f32_e32 v27, v47, v27
	v_sub_f32_e32 v28, v48, v28
	v_cvt_pk_bf16_f32 v30, v27, v28
	v_cvt_pk_bf16_f32 v27, v49, v50
	s_nop 0
	v_lshlrev_b32_e32 v28, 16, v27
	v_and_b32_e32 v29, 0xffff0000, v27
	v_sub_f32_e32 v28, v49, v28
	v_sub_f32_e32 v29, v50, v29
	v_cvt_pk_bf16_f32 v31, v28, v29
	v_cvt_pk_bf16_f32 v28, v51, v52
	s_nop 0
	v_lshlrev_b32_e32 v29, 16, v28
	v_and_b32_e32 v32, 0xffff0000, v28
	v_sub_f32_e32 v29, v51, v29
	v_sub_f32_e32 v32, v52, v32
	v_cvt_pk_bf16_f32 v32, v29, v32
	v_cvt_pk_bf16_f32 v29, v53, v34
	s_nop 0
	v_lshlrev_b32_e32 v33, 16, v29
	v_sub_f32_e32 v33, v53, v33
	v_and_b32_e32 v35, 0xffff0000, v29
	v_sub_f32_e32 v34, v34, v35
	v_cvt_pk_bf16_f32 v33, v33, v34
	ds_write_b128 v155, v[2:5]
	ds_write_b128 v155, v[10:13] offset:16
	ds_write_b128 v155, v[18:21] offset:32
	ds_write_b128 v155, v[26:29] offset:48
	ds_write_b128 v155, v[6:9] offset:4096
	ds_write_b128 v155, v[14:17] offset:4112
	ds_write_b128 v155, v[22:25] offset:4128
	ds_write_b128 v155, v[30:33] offset:4144
	s_waitcnt lgkmcnt(0)
	v_lshl_or_b32 v6, v1, 12, v222
	v_mov_b32_e32 v7, v0
	v_or_b32_e32 v34, v45, v147
	ds_read_b128 v[46:49], v183
	ds_read_b128 v[50:53], v183 offset:512
	ds_read_b128 v[54:57], v183 offset:1024
	ds_read_b128 v[58:61], v183 offset:1536
	ds_read_b128 v[62:65], v183 offset:2048
	ds_read_b128 v[66:69], v183 offset:2560
	ds_read_b128 v[70:73], v183 offset:3072
	ds_read_b128 v[74:77], v183 offset:3584
	s_waitcnt lgkmcnt(0)
; __device__ __forceinline__ bf16_t f2bf(float f) { unsigned u = __float_as_uint(f); u += 0x7FFFu + ((u >> 16) & 1u); return (bf16_t)(u >> 16); }
; __device__ __forceinline__ f32x4 mfma16(bf16x8 a, bf16x8 b, f32x4 c) { return __builtin_amdgcn_mfma_f32_16x16x32_bf16(a, b, c, 0, 0, 0); }
; template <int MODE>
; __device__ __forceinline__ void s5_unit(const Params& P, unsigned char* wl, const int id) {
;     ...
;     bf16x8 cf[4]; float dsk = 0.f;
;     if (MODE >= 1) {
; #pragma unroll
;         for (int ks = 0; ks < 4; ++ks) { const int p0 = 16 * ks + 4 * q; const f32x4 cr = *(const f32x4*)(P.in[15] + (size_t)(g * 16 + l16) * 64 + p0), ci = *(const f32x4*)(P.in[16] + (size_t)(g * 16 + l16) * 64 + p0);
;             bf16x8 f; f[0] = (short)f2bf(cr[0]); f[1] = (short)f2bf(-ci[0]); f[2] = (short)f2bf(cr[1]); f[3] = (short)f2bf(-ci[1]); f[4] = (short)f2bf(cr[2]); f[5] = (short)f2bf(-ci[2]); f[6] = (short)f2bf(cr[3]); f[7] = (short)f2bf(-ci[3]); cf[ks] = f; }
;         dsk = P.in[17][g * 16 + l16]; }
;     const bf16_t* arow = PROJ + (size_t)(row0 + l16) * NPROJ + C_U + g * 16 + 8 * (q & 1);
;     bf16x8 a_cur = *(const bf16x8*)arow;
;     for (int blk = 0; blk < nblk; ++blk) {
;         bf16x8 a_nxt = zf; if (blk + 1 < nblk) a_nxt = *(const bf16x8*)(arow + (size_t)(blk + 1) * 16 * NPROJ);
;         { float* bp = buf + (4 * q) * 130 + l16; f32x4 d[8];
; #pragma unroll
;           for (int nn = 0; nn < 8; ++nn) d[nn] = mfma16(a_cur, bfr[nn], (f32x4){0.f, 0.f, 0.f, 0.f});
;           __builtin_amdgcn_sched_barrier(0); asm volatile("s_nop 15\n\ts_nop 15" ::: "memory"); __builtin_amdgcn_sched_barrier(0);
; #pragma unroll
;           for (int nn = 0; nn < 8; ++nn) { bp[16 * nn] = d[nn][0]; bp[130 + 16 * nn] = d[nn][1]; bp[260 + 16 * nn] = d[nn][2]; bp[390 + 16 * nn] = d[nn][3]; } }
;         if (MODE >= 1 && q < 2) *(bf16x8*)(Ub + l16 * 16 + 8 * q) = a_cur;
	v_lshl_add_u64 v[26:27], v[166:167], 0, v[6:7]
	v_lshl_add_u64 v[30:31], v[168:169], 0, v[6:7]
	v_lshlrev_b32_e32 v34, 2, v34
	global_load_dwordx4 v[2:5], v[26:27], off
	global_load_dwordx4 v[6:9], v[30:31], off
	global_load_dwordx4 v[10:13], v[26:27], off offset:64
	global_load_dwordx4 v[14:17], v[30:31], off offset:64
	global_load_dwordx4 v[18:21], v[26:27], off offset:128
	global_load_dwordx4 v[22:25], v[30:31], off offset:128
	s_nop 0
	global_load_dwordx4 v[26:29], v[26:27], off offset:192
	s_nop 0
	global_load_dwordx4 v[30:33], v[30:31], off offset:192
	s_nop 0
	global_load_dword v39, v34, s[58:59]
	v_mov_b64_e32 v[34:35], s[0:1]
	v_mad_u64_u32 v[34:35], s[0:1], v36, s90, v[34:35]
	v_lshlrev_b32_e32 v36, 5, v1
	v_lshl_add_u64 v[34:35], v[34:35], 0, v[36:37]
	v_lshlrev_b32_e32 v36, 1, v150
	v_lshl_add_u64 v[34:35], v[34:35], 0, v[36:37]
	global_load_dwordx4 v[34:37], v[34:35], off
	s_waitcnt vmcnt(0) lgkmcnt(7)
	v_mfma_f32_16x16x32_bf16 v[46:49], v[34:37], v[46:49], 0
	s_waitcnt lgkmcnt(6)
	v_mfma_f32_16x16x32_bf16 v[50:53], v[34:37], v[50:53], 0
	s_waitcnt lgkmcnt(5)
	v_mfma_f32_16x16x32_bf16 v[54:57], v[34:37], v[54:57], 0
	s_waitcnt lgkmcnt(4)
	v_mfma_f32_16x16x32_bf16 v[58:61], v[34:37], v[58:61], 0
	s_waitcnt lgkmcnt(3)
	v_mfma_f32_16x16x32_bf16 v[62:65], v[34:37], v[62:65], 0
	s_waitcnt lgkmcnt(2)
	v_mfma_f32_16x16x32_bf16 v[66:69], v[34:37], v[66:69], 0
	s_waitcnt lgkmcnt(1)
	v_mfma_f32_16x16x32_bf16 v[70:73], v[34:37], v[70:73], 0
	s_waitcnt lgkmcnt(0)
	v_mfma_f32_16x16x32_bf16 v[74:77], v[34:37], v[74:77], 0
	s_nop 15
	s_nop 15
	v_add_u32_e32 v78, 0x1000, v212
	ds_write2_b32 v78, v46, v50 offset1:16
	ds_write2_b32 v78, v47, v51 offset0:130 offset1:146
	v_add_u32_e32 v46, 0x1400, v212
	ds_write2_b32 v46, v48, v52 offset0:4 offset1:20
	ds_write2_b32 v46, v49, v53 offset0:134 offset1:150
	ds_write2_b32 v78, v54, v58 offset0:32 offset1:48
	ds_write2_b32 v78, v55, v59 offset0:162 offset1:178
	ds_write2_b32 v46, v56, v60 offset0:36 offset1:52
	ds_write2_b32 v46, v57, v61 offset0:166 offset1:182
	ds_write2_b32 v78, v62, v66 offset0:64 offset1:80
	ds_write2_b32 v78, v63, v67 offset0:194 offset1:210
	ds_write2_b32 v46, v64, v68 offset0:68 offset1:84
	ds_write2_b32 v46, v65, v69 offset0:198 offset1:214
	ds_write2_b32 v78, v70, v74 offset0:96 offset1:112
	ds_write2_b32 v78, v71, v75 offset0:226 offset1:242
	ds_write2_b32 v46, v72, v76 offset0:100 offset1:116
	ds_write2_b32 v46, v73, v77 offset0:230 offset1:246
	s_and_saveexec_b64 s[0:1], s[4:5]
	ds_write_b128 v213, v[34:37]
	s_or_b64 exec, exec, s[0:1]
	v_lshlrev_b32_e32 v34, 1, v45
	v_mov_b32_e32 v35, v0
	v_or_b32_e32 v36, v41, v152
	v_mov_b32_e32 v37, v0
	v_lshl_add_u64 v[34:35], s[18:19], 0, v[34:35]
	v_lshlrev_b64 v[36:37], 11, v[36:37]
	v_xor_b32_e32 v31, 0x80000000, v31
	v_xor_b32_e32 v32, 0x80000000, v32
	v_xor_b32_e32 v33, 0x80000000, v33
	v_lshl_add_u64 v[34:35], v[34:35], 0, v[36:37]
	v_xor_b32_e32 v30, 0x80000000, v30
	v_bfe_u32 v36, v33, 16, 1
	v_bfe_u32 v37, v32, 16, 1
	v_bfe_u32 v41, v31, 16, 1
	v_xor_b32_e32 v23, 0x80000000, v23
	v_xor_b32_e32 v24, 0x80000000, v24
	v_xor_b32_e32 v25, 0x80000000, v25
	v_mul_f32_e32 v43, v42, v43
	v_bfe_u32 v42, v30, 16, 1
	v_bfe_u32 v46, v28, 16, 1
	v_bfe_u32 v47, v27, 16, 1
	v_bfe_u32 v48, v26, 16, 1
	v_add3_u32 v31, v31, v41, s91
	v_add3_u32 v32, v32, v37, s91
	v_add3_u32 v33, v33, v36, s91
	v_xor_b32_e32 v22, 0x80000000, v22
	v_bfe_u32 v36, v25, 16, 1
	v_bfe_u32 v37, v24, 16, 1
	v_bfe_u32 v41, v23, 16, 1
	v_xor_b32_e32 v15, 0x80000000, v15
	v_xor_b32_e32 v16, 0x80000000, v16
	v_xor_b32_e32 v17, 0x80000000, v17
	v_add3_u32 v26, v26, v48, s91
	v_add3_u32 v30, v30, v42, s91
	v_add3_u32 v27, v27, v47, s91
	v_add3_u32 v28, v28, v46, s91
	v_bfe_u32 v42, v22, 16, 1
	v_bfe_u32 v46, v20, 16, 1
	v_bfe_u32 v47, v19, 16, 1
	v_bfe_u32 v48, v18, 16, 1
	v_add3_u32 v23, v23, v41, s91
	v_add3_u32 v24, v24, v37, s91
	v_add3_u32 v25, v25, v36, s91
	v_xor_b32_e32 v14, 0x80000000, v14
	v_bfe_u32 v36, v17, 16, 1
	v_bfe_u32 v37, v16, 16, 1
	v_bfe_u32 v41, v15, 16, 1
	v_bfe_u32 v45, v29, 16, 1
	v_add3_u32 v18, v18, v48, s91
	v_add3_u32 v22, v22, v42, s91
	v_add3_u32 v19, v19, v47, s91
	v_add3_u32 v20, v20, v46, s91
	v_bfe_u32 v42, v14, 16, 1
	v_bfe_u32 v46, v12, 16, 1
	v_bfe_u32 v47, v11, 16, 1
	v_bfe_u32 v48, v10, 16, 1
	v_add3_u32 v15, v15, v41, s91
	v_add3_u32 v16, v16, v37, s91
	v_add3_u32 v17, v17, v36, s91
	v_xor_b32_e32 v36, 0x80000000, v6
	v_xor_b32_e32 v37, 0x80000000, v7
	v_xor_b32_e32 v41, 0x80000000, v8
	v_bfe_u32 v8, v3, 16, 1
	v_bfe_u32 v6, v2, 16, 1
	v_add3_u32 v29, v29, v45, s91
	v_bfe_u32 v45, v21, 16, 1
	v_add3_u32 v10, v10, v48, s91
	v_add3_u32 v14, v14, v42, s91
	v_add3_u32 v11, v11, v47, s91
	v_add3_u32 v12, v12, v46, s91
	v_xor_b32_e32 v42, 0x80000000, v9
	v_bfe_u32 v46, v41, 16, 1
	v_bfe_u32 v9, v37, 16, 1
	v_bfe_u32 v7, v36, 16, 1
	v_bfe_u32 v47, v5, 16, 1
	v_bfe_u32 v48, v4, 16, 1
	v_add3_u32 v6, v2, v6, s91
	v_add3_u32 v8, v3, v8, s91
	v_lshl_or_b32 v2, v44, 6, v1
	v_mov_b32_e32 v3, v0
	v_add3_u32 v21, v21, v45, s91
	v_bfe_u32 v45, v13, 16, 1
	v_add3_u32 v7, v36, v7, s91
	v_add3_u32 v9, v37, v9, s91
	v_add3_u32 v36, v4, v48, s91
	v_add3_u32 v37, v41, v46, s91
	v_add3_u32 v41, v5, v47, s91
	v_lshlrev_b64 v[4:5], 8, v[2:3]
	v_lshlrev_b32_e32 v3, 2, v146
	v_add3_u32 v13, v13, v45, s91
	v_bfe_u32 v45, v42, 16, 1
	v_or_b32_e32 v4, v4, v3
	v_add3_u32 v42, v42, v45, s91
	s_waitcnt lgkmcnt(0)
; __device__ __forceinline__ unsigned cvt_pk_bf16(float lo, float hi) { unsigned r; asm volatile("v_cvt_pk_bf16_f32 %0, %1, %2" : "=v"(r) : "v"(lo), "v"(hi)); return r; }
; template <int MODE>
; __device__ __forceinline__ void s5_unit(const Params& P, unsigned char* wl, const int id) {
;     ...
;         if (MODE == 2) {
; #pragma unroll
;             for (int t = 0; t < 16; ++t) { const size_t si = (size_t)((sb * 16 + t) * 64 + g) * 64 + lane; const float h0r = P.in[2][si], h0i = P.in[3][si];
;                 const f32x2 bb = *(const f32x2*)(buf + t * 130 + 2 * lane);
;                 const float nr_ = ar * h0r - ai * h0i + bb.x, ni_ = ar * h0i + ai * h0r + bb.y; P.out[OUT_SRE + si] = nr_; P.out[OUT_SIM + si] = ni_; Hw[t * 68 + lane] = cvt_pk_bf16(nr_, ni_); }
	v_lshl_add_u64 v[128:129], s[40:41], 0, v[4:5]
	v_lshl_add_u64 v[130:131], s[42:43], 0, v[4:5]
	global_load_dword v96, v[128:129], off
	global_load_dword v97, v[130:131], off
	v_add_co_u32_e32 v128, vcc, 0x4000, v128
	s_nop 1
	v_addc_co_u32_e32 v129, vcc, 0, v129, vcc
	v_add_co_u32_e32 v130, vcc, 0x4000, v130
	s_nop 1
	v_addc_co_u32_e32 v131, vcc, 0, v131, vcc
	global_load_dword v98, v[128:129], off
	global_load_dword v99, v[130:131], off
	v_add_co_u32_e32 v128, vcc, 0x4000, v128
	s_nop 1
	v_addc_co_u32_e32 v129, vcc, 0, v129, vcc
	v_add_co_u32_e32 v130, vcc, 0x4000, v130
	s_nop 1
	v_addc_co_u32_e32 v131, vcc, 0, v131, vcc
	global_load_dword v100, v[128:129], off
	global_load_dword v101, v[130:131], off
	v_add_co_u32_e32 v128, vcc, 0x4000, v128
	s_nop 1
	v_addc_co_u32_e32 v129, vcc, 0, v129, vcc
	v_add_co_u32_e32 v130, vcc, 0x4000, v130
	s_nop 1
	v_addc_co_u32_e32 v131, vcc, 0, v131, vcc
	global_load_dword v102, v[128:129], off
	global_load_dword v103, v[130:131], off
	v_add_co_u32_e32 v128, vcc, 0x4000, v128
	s_nop 1
	v_addc_co_u32_e32 v129, vcc, 0, v129, vcc
	v_add_co_u32_e32 v130, vcc, 0x4000, v130
	s_nop 1
	v_addc_co_u32_e32 v131, vcc, 0, v131, vcc
	global_load_dword v104, v[128:129], off
	global_load_dword v105, v[130:131], off
	v_add_co_u32_e32 v128, vcc, 0x4000, v128
	s_nop 1
	v_addc_co_u32_e32 v129, vcc, 0, v129, vcc
	v_add_co_u32_e32 v130, vcc, 0x4000, v130
	s_nop 1
	v_addc_co_u32_e32 v131, vcc, 0, v131, vcc
	global_load_dword v106, v[128:129], off
	global_load_dword v107, v[130:131], off
	v_add_co_u32_e32 v128, vcc, 0x4000, v128
	s_nop 1
	v_addc_co_u32_e32 v129, vcc, 0, v129, vcc
	v_add_co_u32_e32 v130, vcc, 0x4000, v130
	s_nop 1
	v_addc_co_u32_e32 v131, vcc, 0, v131, vcc
	global_load_dword v108, v[128:129], off
	global_load_dword v109, v[130:131], off
	v_add_co_u32_e32 v128, vcc, 0x4000, v128
	s_nop 1
	v_addc_co_u32_e32 v129, vcc, 0, v129, vcc
	v_add_co_u32_e32 v130, vcc, 0x4000, v130
	s_nop 1
	v_addc_co_u32_e32 v131, vcc, 0, v131, vcc
	global_load_dword v110, v[128:129], off
	global_load_dword v111, v[130:131], off
	v_add_co_u32_e32 v128, vcc, 0x4000, v128
	s_nop 1
	v_addc_co_u32_e32 v129, vcc, 0, v129, vcc
	v_add_co_u32_e32 v130, vcc, 0x4000, v130
	s_nop 1
	v_addc_co_u32_e32 v131, vcc, 0, v131, vcc
	global_load_dword v112, v[128:129], off
	global_load_dword v113, v[130:131], off
	v_add_co_u32_e32 v128, vcc, 0x4000, v128
	s_nop 1
	v_addc_co_u32_e32 v129, vcc, 0, v129, vcc
	v_add_co_u32_e32 v130, vcc, 0x4000, v130
	s_nop 1
	v_addc_co_u32_e32 v131, vcc, 0, v131, vcc
	global_load_dword v114, v[128:129], off
	global_load_dword v115, v[130:131], off
	v_add_co_u32_e32 v128, vcc, 0x4000, v128
	s_nop 1
	v_addc_co_u32_e32 v129, vcc, 0, v129, vcc
	v_add_co_u32_e32 v130, vcc, 0x4000, v130
	s_nop 1
	v_addc_co_u32_e32 v131, vcc, 0, v131, vcc
	global_load_dword v116, v[128:129], off
	global_load_dword v117, v[130:131], off
	v_add_co_u32_e32 v128, vcc, 0x4000, v128
	s_nop 1
	v_addc_co_u32_e32 v129, vcc, 0, v129, vcc
	v_add_co_u32_e32 v130, vcc, 0x4000, v130
	s_nop 1
	v_addc_co_u32_e32 v131, vcc, 0, v131, vcc
	global_load_dword v118, v[128:129], off
	global_load_dword v119, v[130:131], off
	v_add_co_u32_e32 v128, vcc, 0x4000, v128
	s_nop 1
	v_addc_co_u32_e32 v129, vcc, 0, v129, vcc
	v_add_co_u32_e32 v130, vcc, 0x4000, v130
	s_nop 1
	v_addc_co_u32_e32 v131, vcc, 0, v131, vcc
	global_load_dword v120, v[128:129], off
	global_load_dword v121, v[130:131], off
	v_add_co_u32_e32 v128, vcc, 0x4000, v128
	s_nop 1
	v_addc_co_u32_e32 v129, vcc, 0, v129, vcc
	v_add_co_u32_e32 v130, vcc, 0x4000, v130
	s_nop 1
	v_addc_co_u32_e32 v131, vcc, 0, v131, vcc
	global_load_dword v122, v[128:129], off
	global_load_dword v123, v[130:131], off
	v_add_co_u32_e32 v128, vcc, 0x4000, v128
	s_nop 1
	v_addc_co_u32_e32 v129, vcc, 0, v129, vcc
	v_add_co_u32_e32 v130, vcc, 0x4000, v130
	s_nop 1
	v_addc_co_u32_e32 v131, vcc, 0, v131, vcc
	global_load_dword v124, v[128:129], off
	global_load_dword v125, v[130:131], off
	v_add_co_u32_e32 v128, vcc, 0x4000, v128
	s_nop 1
	v_addc_co_u32_e32 v129, vcc, 0, v129, vcc
	v_add_co_u32_e32 v130, vcc, 0x4000, v130
	s_nop 1
	v_addc_co_u32_e32 v131, vcc, 0, v131, vcc
	global_load_dword v126, v[128:129], off
	global_load_dword v127, v[130:131], off
	v_lshl_add_u64 v[44:45], s[40:41], 0, v[4:5]
	v_lshl_add_u64 v[44:45], s[42:43], 0, v[4:5]
	ds_read_b64 v[44:45], v218 offset:4096
	v_readlane_b32 s72, v245, 34
	v_readlane_b32 s86, v245, 48
	v_readlane_b32 s87, v245, 49
	s_movk_i32 s0, 0x3c0
	v_perm_b32 v13, v17, v13, s53
	v_lshl_add_u64 v[4:5], s[86:87], 0, v[4:5]
	v_perm_b32 v12, v16, v12, s53
	v_perm_b32 v11, v15, v11, s53
	v_perm_b32 v10, v14, v10, s53
	v_mov_b32_e32 v149, v0
	v_lshl_add_u64 v[34:35], v[34:35], 0, v[148:149]
	v_readlane_b32 s73, v245, 35
	v_readlane_b32 s74, v245, 36
	v_readlane_b32 s75, v245, 37
	v_readlane_b32 s76, v245, 38
	v_readlane_b32 s77, v245, 39
	v_readlane_b32 s78, v245, 40
	v_readlane_b32 s79, v245, 41
	v_readlane_b32 s80, v245, 42
	v_readlane_b32 s81, v245, 43
	v_readlane_b32 s82, v245, 44
	v_readlane_b32 s83, v245, 45
	v_readlane_b32 s84, v245, 46
	v_readlane_b32 s85, v245, 47
	s_waitcnt vmcnt(0)
	v_mov_b32_e32 v46, v96
	v_mov_b32_e32 v47, v97
	v_mul_f32_e32 v48, v38, v47
	v_fma_f32 v48, v43, v46, -v48
	s_waitcnt lgkmcnt(0)
; __device__ __forceinline__ unsigned cvt_pk_bf16(float lo, float hi) { unsigned r; asm volatile("v_cvt_pk_bf16_f32 %0, %1, %2" : "=v"(r) : "v"(lo), "v"(hi)); return r; }
; template <int MODE>
; __device__ __forceinline__ void s5_unit(const Params& P, unsigned char* wl, const int id) {
;     ...
;             for (int t = 0; t < 16; ++t) { const size_t si = (size_t)((sb * 16 + t) * 64 + g) * 64 + lane; const float h0r = P.in[2][si], h0i = P.in[3][si];
;                 const f32x2 bb = *(const f32x2*)(buf + t * 130 + 2 * lane);
;                 const float nr_ = ar * h0r - ai * h0i + bb.x, ni_ = ar * h0i + ai * h0r + bb.y; P.out[OUT_SRE + si] = nr_; P.out[OUT_SIM + si] = ni_; Hw[t * 68 + lane] = cvt_pk_bf16(nr_, ni_); }
	v_add_f32_e32 v48, v48, v44
	v_mul_f32_e32 v44, v43, v47
	v_fmac_f32_e32 v44, v38, v46
	v_add_f32_e32 v46, v44, v45
	v_add_co_u32_e32 v44, vcc, s92, v4
	s_nop 1
	v_addc_co_u32_e32 v45, vcc, 0, v5, vcc
	v_add_co_u32_e32 v4, vcc, s52, v4
	global_store_dword v[44:45], v48, off offset:64
	s_nop 0
	v_addc_co_u32_e32 v5, vcc, 0, v5, vcc
	global_store_dword v[4:5], v46, off offset:64
	v_cvt_pk_bf16_f32 v4, v48, v46
	ds_write_b32 v223, v4 offset:12416
	v_or_b32_e32 v4, 64, v2
	v_mov_b32_e32 v5, v0
	v_lshlrev_b64 v[4:5], 8, v[4:5]
	v_or_b32_e32 v4, v4, v3
	v_lshl_add_u64 v[44:45], s[40:41], 0, v[4:5]
	v_mov_b32_e32 v46, v98
	v_lshl_add_u64 v[44:45], s[42:43], 0, v[4:5]
	v_mov_b32_e32 v47, v99
	ds_read_b64 v[44:45], v218 offset:4616
	v_lshl_add_u64 v[4:5], s[86:87], 0, v[4:5]
	v_mul_f32_e32 v48, v38, v47
	v_fma_f32 v48, v43, v46, -v48
	s_waitcnt lgkmcnt(0)
	v_add_f32_e32 v48, v48, v44
	v_mul_f32_e32 v44, v43, v47
	v_fmac_f32_e32 v44, v38, v46
	v_add_f32_e32 v46, v44, v45
	v_add_co_u32_e32 v44, vcc, s92, v4
	s_nop 1
	v_addc_co_u32_e32 v45, vcc, 0, v5, vcc
	v_add_co_u32_e32 v4, vcc, s52, v4
	global_store_dword v[44:45], v48, off offset:64
	s_nop 0
	v_addc_co_u32_e32 v5, vcc, 0, v5, vcc
	global_store_dword v[4:5], v46, off offset:64
	v_cvt_pk_bf16_f32 v4, v48, v46
	ds_write_b32 v223, v4 offset:12688
	v_or_b32_e32 v4, 0x80, v2
	v_mov_b32_e32 v5, v0
	v_lshlrev_b64 v[4:5], 8, v[4:5]
	v_or_b32_e32 v4, v4, v3
	v_lshl_add_u64 v[44:45], s[40:41], 0, v[4:5]
	v_mov_b32_e32 v46, v100
	v_lshl_add_u64 v[44:45], s[42:43], 0, v[4:5]
	v_mov_b32_e32 v47, v101
	ds_read_b64 v[44:45], v218 offset:5136
	v_lshl_add_u64 v[4:5], s[86:87], 0, v[4:5]
	v_mul_f32_e32 v48, v38, v47
	v_fma_f32 v48, v43, v46, -v48
	s_waitcnt lgkmcnt(0)
	v_add_f32_e32 v48, v48, v44
	v_mul_f32_e32 v44, v43, v47
	v_fmac_f32_e32 v44, v38, v46
	v_add_f32_e32 v46, v44, v45
	v_add_co_u32_e32 v44, vcc, s92, v4
	s_nop 1
	v_addc_co_u32_e32 v45, vcc, 0, v5, vcc
	v_add_co_u32_e32 v4, vcc, s52, v4
	global_store_dword v[44:45], v48, off offset:64
	s_nop 0
	v_addc_co_u32_e32 v5, vcc, 0, v5, vcc
	global_store_dword v[4:5], v46, off offset:64
	v_cvt_pk_bf16_f32 v4, v48, v46
	ds_write_b32 v223, v4 offset:12960
	v_or_b32_e32 v4, 0xc0, v2
	v_mov_b32_e32 v5, v0
	v_lshlrev_b64 v[4:5], 8, v[4:5]
	v_or_b32_e32 v4, v4, v3
	v_lshl_add_u64 v[44:45], s[40:41], 0, v[4:5]
	v_mov_b32_e32 v46, v102
	v_lshl_add_u64 v[44:45], s[42:43], 0, v[4:5]
	v_mov_b32_e32 v47, v103
	ds_read_b64 v[44:45], v218 offset:5656
	v_lshl_add_u64 v[4:5], s[86:87], 0, v[4:5]
	v_mul_f32_e32 v48, v38, v47
	v_fma_f32 v48, v43, v46, -v48
	s_waitcnt lgkmcnt(0)
	v_add_f32_e32 v48, v48, v44
	v_mul_f32_e32 v44, v43, v47
	v_fmac_f32_e32 v44, v38, v46
	v_add_f32_e32 v46, v44, v45
	v_add_co_u32_e32 v44, vcc, s92, v4
	s_nop 1
	v_addc_co_u32_e32 v45, vcc, 0, v5, vcc
	v_add_co_u32_e32 v4, vcc, s52, v4
	global_store_dword v[44:45], v48, off offset:64
	s_nop 0
	v_addc_co_u32_e32 v5, vcc, 0, v5, vcc
	global_store_dword v[4:5], v46, off offset:64
	v_cvt_pk_bf16_f32 v4, v48, v46
	ds_write_b32 v223, v4 offset:13232
	v_or_b32_e32 v4, 0x100, v2
	v_mov_b32_e32 v5, v0
	v_lshlrev_b64 v[4:5], 8, v[4:5]
	v_or_b32_e32 v4, v4, v3
	v_lshl_add_u64 v[44:45], s[40:41], 0, v[4:5]
	v_mov_b32_e32 v46, v104
	v_lshl_add_u64 v[44:45], s[42:43], 0, v[4:5]
	v_mov_b32_e32 v47, v105
	ds_read_b64 v[44:45], v218 offset:6176
	v_lshl_add_u64 v[4:5], s[86:87], 0, v[4:5]
	v_mul_f32_e32 v48, v38, v47
	v_fma_f32 v48, v43, v46, -v48
	s_waitcnt lgkmcnt(0)
	v_add_f32_e32 v48, v48, v44
	v_mul_f32_e32 v44, v43, v47
	v_fmac_f32_e32 v44, v38, v46
	v_add_f32_e32 v46, v44, v45
	v_add_co_u32_e32 v44, vcc, s92, v4
	s_nop 1
	v_addc_co_u32_e32 v45, vcc, 0, v5, vcc
	v_add_co_u32_e32 v4, vcc, s52, v4
	global_store_dword v[44:45], v48, off offset:64
	s_nop 0
	v_addc_co_u32_e32 v5, vcc, 0, v5, vcc
	global_store_dword v[4:5], v46, off offset:64
	v_cvt_pk_bf16_f32 v4, v48, v46
	ds_write_b32 v223, v4 offset:13504
	v_or_b32_e32 v4, 0x140, v2
	v_mov_b32_e32 v5, v0
	v_lshlrev_b64 v[4:5], 8, v[4:5]
	v_or_b32_e32 v4, v4, v3
	v_lshl_add_u64 v[44:45], s[40:41], 0, v[4:5]
	v_mov_b32_e32 v46, v106
	v_lshl_add_u64 v[44:45], s[42:43], 0, v[4:5]
	v_mov_b32_e32 v47, v107
	ds_read_b64 v[44:45], v218 offset:6696
	v_lshl_add_u64 v[4:5], s[86:87], 0, v[4:5]
	v_mul_f32_e32 v48, v38, v47
	v_fma_f32 v48, v43, v46, -v48
	s_waitcnt lgkmcnt(0)
	v_add_f32_e32 v48, v48, v44
	v_mul_f32_e32 v44, v43, v47
	v_fmac_f32_e32 v44, v38, v46
	v_add_f32_e32 v46, v44, v45
	v_add_co_u32_e32 v44, vcc, s92, v4
	s_nop 1
	v_addc_co_u32_e32 v45, vcc, 0, v5, vcc
	v_add_co_u32_e32 v4, vcc, s52, v4
	global_store_dword v[44:45], v48, off offset:64
	s_nop 0
	v_addc_co_u32_e32 v5, vcc, 0, v5, vcc
	global_store_dword v[4:5], v46, off offset:64
	v_cvt_pk_bf16_f32 v4, v48, v46
	ds_write_b32 v223, v4 offset:13776
	v_or_b32_e32 v4, 0x180, v2
	v_mov_b32_e32 v5, v0
	v_lshlrev_b64 v[4:5], 8, v[4:5]
	v_or_b32_e32 v4, v4, v3
	v_lshl_add_u64 v[44:45], s[40:41], 0, v[4:5]
	v_mov_b32_e32 v46, v108
	v_lshl_add_u64 v[44:45], s[42:43], 0, v[4:5]
	v_mov_b32_e32 v47, v109
	ds_read_b64 v[44:45], v218 offset:7216
	v_lshl_add_u64 v[4:5], s[86:87], 0, v[4:5]
	v_mul_f32_e32 v48, v38, v47
	v_fma_f32 v48, v43, v46, -v48
	s_waitcnt lgkmcnt(0)
	v_add_f32_e32 v48, v48, v44
	v_mul_f32_e32 v44, v43, v47
	v_fmac_f32_e32 v44, v38, v46
	v_add_f32_e32 v46, v44, v45
	v_add_co_u32_e32 v44, vcc, s92, v4
	s_nop 1
	v_addc_co_u32_e32 v45, vcc, 0, v5, vcc
	v_add_co_u32_e32 v4, vcc, s52, v4
	global_store_dword v[44:45], v48, off offset:64
	s_nop 0
	v_addc_co_u32_e32 v5, vcc, 0, v5, vcc
	global_store_dword v[4:5], v46, off offset:64
	v_cvt_pk_bf16_f32 v4, v48, v46
	ds_write_b32 v223, v4 offset:14048
	v_or_b32_e32 v4, 0x1c0, v2
	v_mov_b32_e32 v5, v0
	v_lshlrev_b64 v[4:5], 8, v[4:5]
	v_or_b32_e32 v4, v4, v3
	v_lshl_add_u64 v[44:45], s[40:41], 0, v[4:5]
	v_mov_b32_e32 v46, v110
	v_lshl_add_u64 v[44:45], s[42:43], 0, v[4:5]
	v_mov_b32_e32 v47, v111
	ds_read_b64 v[44:45], v218 offset:7736
	v_lshl_add_u64 v[4:5], s[86:87], 0, v[4:5]
	v_mul_f32_e32 v48, v38, v47
	v_fma_f32 v48, v43, v46, -v48
	s_waitcnt lgkmcnt(0)
; __device__ __forceinline__ unsigned cvt_pk_bf16(float lo, float hi) { unsigned r; asm volatile("v_cvt_pk_bf16_f32 %0, %1, %2" : "=v"(r) : "v"(lo), "v"(hi)); return r; }
; template <int MODE>
; __device__ __forceinline__ void s5_unit(const Params& P, unsigned char* wl, const int id) {
;     ...
;             for (int t = 0; t < 16; ++t) { const size_t si = (size_t)((sb * 16 + t) * 64 + g) * 64 + lane; const float h0r = P.in[2][si], h0i = P.in[3][si];
;                 const f32x2 bb = *(const f32x2*)(buf + t * 130 + 2 * lane);
;                 const float nr_ = ar * h0r - ai * h0i + bb.x, ni_ = ar * h0i + ai * h0r + bb.y; P.out[OUT_SRE + si] = nr_; P.out[OUT_SIM + si] = ni_; Hw[t * 68 + lane] = cvt_pk_bf16(nr_, ni_); }
	v_add_f32_e32 v48, v48, v44
	v_mul_f32_e32 v44, v43, v47
	v_fmac_f32_e32 v44, v38, v46
	v_add_f32_e32 v46, v44, v45
	v_add_co_u32_e32 v44, vcc, s92, v4
	s_nop 1
	v_addc_co_u32_e32 v45, vcc, 0, v5, vcc
	v_add_co_u32_e32 v4, vcc, s52, v4
	global_store_dword v[44:45], v48, off offset:64
	s_nop 0
	v_addc_co_u32_e32 v5, vcc, 0, v5, vcc
	global_store_dword v[4:5], v46, off offset:64
	v_cvt_pk_bf16_f32 v4, v48, v46
	ds_write_b32 v223, v4 offset:14320
	v_or_b32_e32 v4, 0x200, v2
	v_mov_b32_e32 v5, v0
	v_lshlrev_b64 v[4:5], 8, v[4:5]
	v_or_b32_e32 v4, v4, v3
	v_lshl_add_u64 v[44:45], s[40:41], 0, v[4:5]
	v_mov_b32_e32 v46, v112
	v_lshl_add_u64 v[44:45], s[42:43], 0, v[4:5]
	v_mov_b32_e32 v47, v113
	ds_read_b64 v[44:45], v218 offset:8256
	v_lshl_add_u64 v[4:5], s[86:87], 0, v[4:5]
	v_mul_f32_e32 v48, v38, v47
	v_fma_f32 v48, v43, v46, -v48
	s_waitcnt lgkmcnt(0)
	v_add_f32_e32 v48, v48, v44
	v_mul_f32_e32 v44, v43, v47
	v_fmac_f32_e32 v44, v38, v46
	v_add_f32_e32 v46, v44, v45
	v_add_co_u32_e32 v44, vcc, s92, v4
	s_nop 1
	v_addc_co_u32_e32 v45, vcc, 0, v5, vcc
	v_add_co_u32_e32 v4, vcc, s52, v4
	global_store_dword v[44:45], v48, off offset:64
	s_nop 0
	v_addc_co_u32_e32 v5, vcc, 0, v5, vcc
	global_store_dword v[4:5], v46, off offset:64
	v_cvt_pk_bf16_f32 v4, v48, v46
	ds_write_b32 v223, v4 offset:14592
	v_or_b32_e32 v4, 0x240, v2
	v_mov_b32_e32 v5, v0
	v_lshlrev_b64 v[4:5], 8, v[4:5]
	v_or_b32_e32 v4, v4, v3
	v_lshl_add_u64 v[44:45], s[40:41], 0, v[4:5]
	v_mov_b32_e32 v46, v114
	v_lshl_add_u64 v[44:45], s[42:43], 0, v[4:5]
	v_mov_b32_e32 v47, v115
	ds_read_b64 v[44:45], v218 offset:8776
	v_lshl_add_u64 v[4:5], s[86:87], 0, v[4:5]
	v_mul_f32_e32 v48, v38, v47
	v_fma_f32 v48, v43, v46, -v48
	s_waitcnt lgkmcnt(0)
	v_add_f32_e32 v48, v48, v44
	v_mul_f32_e32 v44, v43, v47
	v_fmac_f32_e32 v44, v38, v46
	v_add_f32_e32 v46, v44, v45
	v_add_co_u32_e32 v44, vcc, s92, v4
	s_nop 1
	v_addc_co_u32_e32 v45, vcc, 0, v5, vcc
	v_add_co_u32_e32 v4, vcc, s52, v4
	global_store_dword v[44:45], v48, off offset:64
	s_nop 0
	v_addc_co_u32_e32 v5, vcc, 0, v5, vcc
	global_store_dword v[4:5], v46, off offset:64
	v_cvt_pk_bf16_f32 v4, v48, v46
	ds_write_b32 v223, v4 offset:14864
	v_or_b32_e32 v4, 0x280, v2
	v_mov_b32_e32 v5, v0
	v_lshlrev_b64 v[4:5], 8, v[4:5]
	v_or_b32_e32 v4, v4, v3
	v_lshl_add_u64 v[44:45], s[40:41], 0, v[4:5]
	v_mov_b32_e32 v46, v116
	v_lshl_add_u64 v[44:45], s[42:43], 0, v[4:5]
	v_mov_b32_e32 v47, v117
	ds_read_b64 v[44:45], v218 offset:9296
	v_lshl_add_u64 v[4:5], s[86:87], 0, v[4:5]
	v_mul_f32_e32 v48, v38, v47
	v_fma_f32 v48, v43, v46, -v48
	s_waitcnt lgkmcnt(0)
	v_add_f32_e32 v48, v48, v44
	v_mul_f32_e32 v44, v43, v47
	v_fmac_f32_e32 v44, v38, v46
	v_add_f32_e32 v46, v44, v45
	v_add_co_u32_e32 v44, vcc, s92, v4
	s_nop 1
	v_addc_co_u32_e32 v45, vcc, 0, v5, vcc
	v_add_co_u32_e32 v4, vcc, s52, v4
	global_store_dword v[44:45], v48, off offset:64
	s_nop 0
	v_addc_co_u32_e32 v5, vcc, 0, v5, vcc
	global_store_dword v[4:5], v46, off offset:64
	v_cvt_pk_bf16_f32 v4, v48, v46
	ds_write_b32 v223, v4 offset:15136
	v_or_b32_e32 v4, 0x2c0, v2
	v_mov_b32_e32 v5, v0
	v_lshlrev_b64 v[4:5], 8, v[4:5]
	v_or_b32_e32 v4, v4, v3
	v_lshl_add_u64 v[44:45], s[40:41], 0, v[4:5]
	v_mov_b32_e32 v46, v118
	v_lshl_add_u64 v[44:45], s[42:43], 0, v[4:5]
	v_mov_b32_e32 v47, v119
	ds_read_b64 v[44:45], v218 offset:9816
	v_lshl_add_u64 v[4:5], s[86:87], 0, v[4:5]
	v_mul_f32_e32 v48, v38, v47
	v_fma_f32 v48, v43, v46, -v48
	s_waitcnt lgkmcnt(0)
	v_add_f32_e32 v48, v48, v44
	v_mul_f32_e32 v44, v43, v47
	v_fmac_f32_e32 v44, v38, v46
	v_add_f32_e32 v46, v44, v45
	v_add_co_u32_e32 v44, vcc, s92, v4
	s_nop 1
	v_addc_co_u32_e32 v45, vcc, 0, v5, vcc
	v_add_co_u32_e32 v4, vcc, s52, v4
	global_store_dword v[44:45], v48, off offset:64
	s_nop 0
	v_addc_co_u32_e32 v5, vcc, 0, v5, vcc
	global_store_dword v[4:5], v46, off offset:64
	v_cvt_pk_bf16_f32 v4, v48, v46
	ds_write_b32 v223, v4 offset:15408
	v_or_b32_e32 v4, 0x300, v2
	v_mov_b32_e32 v5, v0
	v_lshlrev_b64 v[4:5], 8, v[4:5]
	v_or_b32_e32 v4, v4, v3
	v_lshl_add_u64 v[44:45], s[40:41], 0, v[4:5]
	v_mov_b32_e32 v46, v120
	v_lshl_add_u64 v[44:45], s[42:43], 0, v[4:5]
	v_mov_b32_e32 v47, v121
	ds_read_b64 v[44:45], v218 offset:10336
	v_lshl_add_u64 v[4:5], s[86:87], 0, v[4:5]
	v_mul_f32_e32 v48, v38, v47
	v_fma_f32 v48, v43, v46, -v48
	s_waitcnt lgkmcnt(0)
	v_add_f32_e32 v48, v48, v44
	v_mul_f32_e32 v44, v43, v47
	v_fmac_f32_e32 v44, v38, v46
	v_add_f32_e32 v46, v44, v45
	v_add_co_u32_e32 v44, vcc, s92, v4
	s_nop 1
	v_addc_co_u32_e32 v45, vcc, 0, v5, vcc
	v_add_co_u32_e32 v4, vcc, s52, v4
	global_store_dword v[44:45], v48, off offset:64
	s_nop 0
	v_addc_co_u32_e32 v5, vcc, 0, v5, vcc
	global_store_dword v[4:5], v46, off offset:64
	v_cvt_pk_bf16_f32 v4, v48, v46
	ds_write_b32 v223, v4 offset:15680
	v_or_b32_e32 v4, 0x340, v2
	v_mov_b32_e32 v5, v0
	v_lshlrev_b64 v[4:5], 8, v[4:5]
	v_or_b32_e32 v4, v4, v3
	v_lshl_add_u64 v[44:45], s[40:41], 0, v[4:5]
	v_mov_b32_e32 v46, v122
	v_lshl_add_u64 v[44:45], s[42:43], 0, v[4:5]
	v_mov_b32_e32 v47, v123
	ds_read_b64 v[44:45], v218 offset:10856
	v_lshl_add_u64 v[4:5], s[86:87], 0, v[4:5]
	v_mul_f32_e32 v48, v38, v47
	v_fma_f32 v48, v43, v46, -v48
	s_waitcnt lgkmcnt(0)
; __device__ __forceinline__ unsigned cvt_pk_bf16(float lo, float hi) { unsigned r; asm volatile("v_cvt_pk_bf16_f32 %0, %1, %2" : "=v"(r) : "v"(lo), "v"(hi)); return r; }
; __device__ __forceinline__ bf16_t f2bf(float f) { unsigned u = __float_as_uint(f); u += 0x7FFFu + ((u >> 16) & 1u); return (bf16_t)(u >> 16); }
; __device__ __forceinline__ float bf2f(bf16_t b) { return __uint_as_float(((unsigned)b) << 16); }
; __device__ __forceinline__ float gelu_tanh(float x) { const float z = 1.5957691216057308f * (x + 0.044715f * x * x * x); return x * sigmoidf_(z); }
; __device__ __forceinline__ f32x4 mfma16(bf16x8 a, bf16x8 b, f32x4 c) { return __builtin_amdgcn_mfma_f32_16x16x32_bf16(a, b, c, 0, 0, 0); }
; template <int MODE>
; __device__ __forceinline__ void s5_unit(const Params& P, unsigned char* wl, const int id) {
;     ...
;             for (int t = 0; t < 16; ++t) { const size_t si = (size_t)((sb * 16 + t) * 64 + g) * 64 + lane; const float h0r = P.in[2][si], h0i = P.in[3][si];
;                 const f32x2 bb = *(const f32x2*)(buf + t * 130 + 2 * lane);
;                 const float nr_ = ar * h0r - ai * h0i + bb.x, ni_ = ar * h0i + ai * h0r + bb.y; P.out[OUT_SRE + si] = nr_; P.out[OUT_SIM + si] = ni_; Hw[t * 68 + lane] = cvt_pk_bf16(nr_, ni_); }
;         } else {
;             f32x2 bb[16];
; #pragma unroll
;             for (int t = 0; t < 16; ++t) bb[t] = *(const f32x2*)(buf + t * 130 + 2 * lane);
; #pragma unroll
;             for (int t = 0; t < 16; ++t) { const float nr_ = ar * hr - ai * hi + bb[t].x, ni_ = ar * hi + ai * hr + bb[t].y; hr = nr_; hi = ni_;
;                 if (MODE == 1) Hw[t * 68 + lane] = cvt_pk_bf16(hr, hi); }
;         }
;         if (MODE >= 1) {
;             asm volatile("s_waitcnt lgkmcnt(0)" ::: "memory");
;             f32x4 acc = (f32x4){0.f, 0.f, 0.f, 0.f};
; #pragma unroll
;             for (int ks = 0; ks < 4; ++ks) acc = mfma16(*(const bf16x8*)((const bf16_t*)Hw + l16 * 136 + 32 * ks + 8 * q), cf[ks], acc);
;             __builtin_amdgcn_sched_barrier(0); asm volatile("s_nop 15\n\ts_nop 15" : "+v"(acc) :: "memory"); __builtin_amdgcn_sched_barrier(0);
;             const bf16_t* up = Ub + (4 * q) * 16 + l16; bf16_t* gp = G + (size_t)(row0 + blk * 16 + 4 * q) * 1024 + g * 16 + l16;
; #pragma unroll
;             for (int r = 0; r < 4; ++r) { const float y = acc[r] + dsk * bf2f(up[r * 16]); gp[r * 1024] = f2bf(gelu_tanh(y)); }
	v_add_f32_e32 v48, v48, v44
	v_mul_f32_e32 v44, v43, v47
	v_fmac_f32_e32 v44, v38, v46
	v_add_f32_e32 v46, v44, v45
	v_add_co_u32_e32 v44, vcc, s92, v4
	s_nop 1
	v_addc_co_u32_e32 v45, vcc, 0, v5, vcc
	v_add_co_u32_e32 v4, vcc, s52, v4
	global_store_dword v[44:45], v48, off offset:64
	s_nop 0
	v_addc_co_u32_e32 v5, vcc, 0, v5, vcc
	global_store_dword v[4:5], v46, off offset:64
	v_cvt_pk_bf16_f32 v4, v48, v46
	ds_write_b32 v223, v4 offset:15952
	v_or_b32_e32 v4, 0x380, v2
	v_mov_b32_e32 v5, v0
	v_lshlrev_b64 v[4:5], 8, v[4:5]
	v_or_b32_e32 v4, v4, v3
	v_lshl_add_u64 v[44:45], s[40:41], 0, v[4:5]
	v_mov_b32_e32 v2, v124
	v_lshl_add_u64 v[44:45], s[42:43], 0, v[4:5]
	v_mov_b32_e32 v46, v125
	ds_read_b64 v[44:45], v218 offset:11376
	v_lshl_add_u64 v[4:5], s[86:87], 0, v[4:5]
	v_mul_f32_e32 v47, v38, v46
	v_fma_f32 v47, v43, v2, -v47
	s_waitcnt lgkmcnt(0)
	v_add_f32_e32 v47, v47, v44
	v_mul_f32_e32 v44, v43, v46
	v_fmac_f32_e32 v44, v38, v2
	v_add_f32_e32 v2, v44, v45
	v_add_co_u32_e32 v44, vcc, s92, v4
	s_nop 1
	v_addc_co_u32_e32 v45, vcc, 0, v5, vcc
	v_add_co_u32_e32 v4, vcc, s52, v4
	global_store_dword v[44:45], v47, off offset:64
	s_nop 0
	v_addc_co_u32_e32 v5, vcc, 0, v5, vcc
	global_store_dword v[4:5], v2, off offset:64
	v_cvt_pk_bf16_f32 v2, v47, v2
	ds_write_b32 v223, v2 offset:16224
	v_lshlrev_b32_e32 v2, 6, v40
	v_or3_b32 v4, v2, v1, s0
	v_mov_b32_e32 v5, v0
	v_lshlrev_b64 v[4:5], 8, v[4:5]
	v_or_b32_e32 v4, v4, v3
	v_lshl_add_u64 v[2:3], s[40:41], 0, v[4:5]
	v_mov_b32_e32 v1, v126
	v_lshl_add_u64 v[2:3], s[42:43], 0, v[4:5]
	v_mov_b32_e32 v40, v127
	ds_read_b64 v[2:3], v218 offset:11896
	v_mul_f32_e32 v44, v38, v40
	v_fma_f32 v44, v43, v1, -v44
	s_waitcnt lgkmcnt(0)
	v_add_f32_e32 v44, v44, v2
	v_mul_f32_e32 v2, v43, v40
	v_fmac_f32_e32 v2, v38, v1
	v_add_f32_e32 v1, v2, v3
	v_lshl_add_u64 v[2:3], s[86:87], 0, v[4:5]
	v_add_co_u32_e32 v4, vcc, s92, v2
	v_perm_b32 v43, v42, v41, s53
	s_nop 0
	v_addc_co_u32_e32 v5, vcc, 0, v3, vcc
	v_add_co_u32_e32 v2, vcc, s52, v2
	global_store_dword v[4:5], v44, off offset:64
	s_nop 0
	v_addc_co_u32_e32 v3, vcc, 0, v3, vcc
	global_store_dword v[2:3], v1, off offset:64
	v_cvt_pk_bf16_f32 v1, v44, v1
	ds_write_b32 v223, v1 offset:16496
	s_waitcnt lgkmcnt(0)
	ds_read_b128 v[2:5], v216 offset:12416
	v_perm_b32 v41, v9, v8, s53
	v_perm_b32 v40, v7, v6, s53
	ds_read_b128 v[6:9], v216 offset:12480
	v_perm_b32 v42, v37, v36, s53
	s_waitcnt lgkmcnt(1)
	s_nop 0
	v_mfma_f32_16x16x32_bf16 v[2:5], v[2:5], v[40:43], 0
	s_waitcnt lgkmcnt(0)
	v_mfma_f32_16x16x32_bf16 v[2:5], v[6:9], v[10:13], v[2:5]
	ds_read_b128 v[6:9], v216 offset:12544
	v_perm_b32 v13, v25, v21, s53
	v_perm_b32 v12, v24, v20, s53
	v_perm_b32 v11, v23, v19, s53
	v_perm_b32 v10, v22, v18, s53
	s_waitcnt lgkmcnt(0)
	s_nop 0
	v_mfma_f32_16x16x32_bf16 v[2:5], v[6:9], v[10:13], v[2:5]
	ds_read_b128 v[6:9], v216 offset:12608
	v_perm_b32 v13, v33, v29, s53
	v_perm_b32 v12, v32, v28, s53
	v_perm_b32 v11, v31, v27, s53
	v_perm_b32 v10, v30, v26, s53
	s_waitcnt lgkmcnt(0)
	s_nop 0
	v_mfma_f32_16x16x32_bf16 v[2:5], v[6:9], v[10:13], v[2:5]
	s_nop 15
	s_nop 15
	ds_read_u16 v1, v217
	ds_read_u16 v6, v217 offset:32
	s_waitcnt lgkmcnt(1)
	v_lshlrev_b32_e32 v1, 16, v1
	s_nop 3
	v_fma_f32 v1, v39, v1, v2
	v_mul_f32_e32 v2, 0x3d372713, v1
	v_mul_f32_e32 v2, v1, v2
	v_fma_f32 v2, v1, v2, v1
	v_mul_f32_e32 v2, 0x3fcc422a, v2
	v_mul_f32_e32 v2, 0xbfb8aa3b, v2
	v_exp_f32_e32 v2, v2
	s_nop 0
	v_add_f32_e32 v2, 1.0, v2
	v_rcp_f32_e32 v2, v2
	s_nop 0
	v_mul_f32_e32 v1, v1, v2
	v_bfe_u32 v2, v1, 16, 1
	v_add3_u32 v1, v1, v2, s91
	global_store_short_d16_hi v[34:35], v1, off
	s_waitcnt lgkmcnt(0)
	v_lshlrev_b32_e32 v1, 16, v6
	v_fma_f32 v1, v39, v1, v3
	v_mul_f32_e32 v2, 0x3d372713, v1
	v_mul_f32_e32 v2, v1, v2
	v_fma_f32 v2, v1, v2, v1
	v_mul_f32_e32 v2, 0x3fcc422a, v2
	v_mul_f32_e32 v2, 0xbfb8aa3b, v2
	v_exp_f32_e32 v2, v2
	s_nop 0
	v_add_f32_e32 v2, 1.0, v2
	v_rcp_f32_e32 v2, v2
	s_nop 0
	v_mul_f32_e32 v1, v1, v2
	v_bfe_u32 v2, v1, 16, 1
	v_add3_u32 v1, v1, v2, s91
	global_store_short_d16_hi v[34:35], v1, off offset:2048
	ds_read_u16 v1, v217 offset:64
	s_waitcnt lgkmcnt(0)
	v_lshlrev_b32_e32 v1, 16, v1
	v_fma_f32 v1, v39, v1, v4
	v_mul_f32_e32 v2, 0x3d372713, v1
	v_mul_f32_e32 v2, v1, v2
	v_fma_f32 v2, v1, v2, v1
	v_mul_f32_e32 v2, 0x3fcc422a, v2
	v_mul_f32_e32 v2, 0xbfb8aa3b, v2
	v_exp_f32_e32 v2, v2
	s_nop 0
	v_add_f32_e32 v2, 1.0, v2
	v_rcp_f32_e32 v2, v2
	s_nop 0
	v_mul_f32_e32 v1, v1, v2
	v_bfe_u32 v2, v1, 16, 1
	v_add3_u32 v1, v1, v2, s91
	v_add_co_u32_e32 v2, vcc, s25, v34
	s_nop 1
	v_addc_co_u32_e32 v3, vcc, 0, v35, vcc
	global_store_short_d16_hi v[2:3], v1, off
	ds_read_u16 v1, v217 offset:96
	s_waitcnt lgkmcnt(0)
	v_lshlrev_b32_e32 v1, 16, v1
	v_fmac_f32_e32 v5, v39, v1
	v_mul_f32_e32 v1, 0x3d372713, v5
	v_mul_f32_e32 v1, v5, v1
	v_fma_f32 v1, v5, v1, v5
	v_mul_f32_e32 v1, 0x3fcc422a, v1
	v_mul_f32_e32 v1, 0xbfb8aa3b, v1
	v_exp_f32_e32 v1, v1
	s_nop 0
	v_add_f32_e32 v1, 1.0, v1
	v_rcp_f32_e32 v1, v1
	s_nop 0
	v_mul_f32_e32 v1, v5, v1
	v_bfe_u32 v4, v1, 16, 1
	v_add3_u32 v1, v1, v4, s91
	global_store_short_d16_hi v[2:3], v1, off offset:2048
	s_waitcnt lgkmcnt(0)

; __device__ __forceinline__ void s5_setup(const Params& P, int g, int p, float& ar, float& ai, float (&Br)[16], float (&Bi)[16]) {
;     const int gp = g * 64 + p;
;     const float lre = P.in[10][gp], lim = P.in[11][gp], dt = expf(P.in[12][gp]);
;     const float zr = lre * dt, zi = lim * dt; const float er = expf(zr); float sn, cs; sincosf(zi, &sn, &cs);
;     ar = er * cs; ai = er * sn;
;     const float nr = ar - 1.0f, ni = ai, den = 1.0f / (lre * lre + lim * lim);
;     const float cr = (nr * lre + ni * lim) * den, ci = (ni * lre - nr * lim) * den;
;     const f32x4* bre = (const f32x4*)(P.in[13] + (size_t)gp * 16); const f32x4* bim = (const f32x4*)(P.in[14] + (size_t)gp * 16);
; #pragma unroll
;     for (int c4 = 0; c4 < 4; ++c4) { const f32x4 x = bre[c4], y = bim[c4];
; #pragma unroll
;         for (int e = 0; e < 4; ++e) { Br[c4 * 4 + e] = cr * x[e] - ci * y[e]; Bi[c4 * 4 + e] = cr * y[e] + ci * x[e]; } }
; }
.LBB0_365:
	s_or_b64 exec, exec, s[0:1]
	s_waitcnt vmcnt(0)
	v_mul_f32_e32 v6, v34, v6
	v_mul_f32_e32 v9, 0x3fb8aa3b, v6
	v_fma_f32 v10, v6, s33, -v9
	v_rndne_f32_e32 v11, v9
	v_fmac_f32_e32 v10, 0x32a5705f, v6
	v_sub_f32_e32 v9, v9, v11
	v_add_f32_e32 v9, v9, v10
	v_exp_f32_e32 v9, v9
	v_cvt_i32_f32_e32 v10, v11
	v_cmp_ngt_f32_e32 vcc, s55, v6
	v_xor_b32_e32 v5, v5, v4
	v_readlane_b32 s56, v245, 2
	v_ldexp_f32 v9, v9, v10
	v_cndmask_b32_e32 v9, 0, v9, vcc
	v_cmp_nlt_f32_e32 vcc, s50, v6
	v_lshlrev_b64 v[2:3], 6, v[2:3]
	v_readlane_b32 s66, v245, 12
	v_cndmask_b32_e32 v6, v227, v9, vcc
	v_mul_f32_e32 v9, v7, v7
	v_fmamk_f32 v10, v9, 0xb94c1982, v220
	v_fmaak_f32 v10, v9, v10, 0xbe2aaa9d
	v_mul_f32_e32 v10, v9, v10
	v_fmac_f32_e32 v7, v7, v10
	v_fmamk_f32 v10, v9, 0x37d75334, v221
	v_fmaak_f32 v10, v9, v10, 0x3d2aabf7
	v_fmaak_f32 v10, v9, v10, 0xbf000004
	v_fma_f32 v9, v9, v10, 1.0
	v_lshlrev_b32_e32 v10, 30, v8
	v_and_b32_e32 v8, 1, v8
	v_cmp_eq_u32_e32 vcc, 0, v8
	v_and_b32_e32 v10, 0x80000000, v10
	v_readlane_b32 s67, v245, 13
	v_cndmask_b32_e32 v8, v9, v7, vcc
	v_xor_b32_e32 v7, 0x80000000, v7
	v_xor_b32_e32 v5, v5, v8
	v_cndmask_b32_e32 v7, v7, v9, vcc
	v_cmp_class_f32_e64 vcc, v4, s89
	v_xor_b32_e32 v4, v5, v10
	v_xor_b32_e32 v7, v7, v10
	v_cndmask_b32_e32 v5, v230, v4, vcc
	v_cndmask_b32_e32 v4, v230, v7, vcc
	v_pk_mul_f32 v[44:45], v[6:7], v[4:5] op_sel_hi:[0,1]
	v_pk_mul_f32 v[4:5], v[34:35], v[34:35]
	v_readlane_b32 s68, v245, 14
	v_add_f32_e32 v4, v4, v5
	v_div_scale_f32 v5, s[0:1], v4, v4, 1.0
	v_rcp_f32_e32 v6, v5
	v_readlane_b32 s69, v245, 15
	v_add_f32_e32 v36, -1.0, v44
	v_pk_mov_b32 v[40:41], v[44:45], v[44:45] op_sel:[1,0]
	v_fma_f32 v7, -v5, v6, 1.0
	v_fmac_f32_e32 v6, v7, v6
	v_div_scale_f32 v7, vcc, 1.0, v4, 1.0
	v_mul_f32_e32 v8, v7, v6
	v_fma_f32 v9, -v5, v8, v7
	v_fmac_f32_e32 v8, v9, v6
	v_fma_f32 v5, -v5, v8, v7
	v_div_fmas_f32 v5, v5, v6, v8
	v_lshl_add_u64 v[6:7], s[66:67], 0, v[2:3]
	v_lshl_add_u64 v[30:31], s[68:69], 0, v[2:3]
	v_div_fixup_f32 v38, v5, v4, 1.0
	global_load_dwordx4 v[2:5], v[6:7], off offset:48
	global_load_dwordx4 v[10:13], v[6:7], off offset:32
	global_load_dwordx4 v[18:21], v[6:7], off offset:16
	global_load_dwordx4 v[26:29], v[6:7], off
	s_nop 0
	global_load_dwordx4 v[6:9], v[30:31], off offset:48
	global_load_dwordx4 v[14:17], v[30:31], off offset:32
	global_load_dwordx4 v[22:25], v[30:31], off offset:16
	s_nop 0
	global_load_dwordx4 v[30:33], v[30:31], off
	v_mov_b32_e32 v42, v35
	v_mov_b32_e32 v37, v45
	v_mov_b32_e32 v41, v36
	v_pk_mul_f32 v[36:37], v[42:43], v[36:37] op_sel_hi:[0,1]
	v_pk_fma_f32 v[42:43], v[34:35], v[44:45], v[36:37] op_sel:[0,1,0] op_sel_hi:[1,0,1] neg_lo:[0,0,1] neg_hi:[0,0,1]
	v_pk_fma_f32 v[34:35], v[34:35], v[40:41], v[36:37] op_sel_hi:[0,1,1]
	v_mov_b32_e32 v43, v35
	v_pk_mul_f32 v[34:35], v[38:39], v[42:43] op_sel_hi:[0,1]
	v_readlane_b32 s0, v245, 54
	v_readlane_b32 s1, v245, 55
	v_add_u32_e32 v1, v1, v147
	v_mov_b32_e32 v48, 0
	s_mov_b32 s10, 0
	v_pk_mov_b32 v[46:47], v[44:45], v[44:45] op_sel:[1,0]
	v_readlane_b32 s57, v245, 3
	v_readlane_b32 s58, v245, 4
	v_readlane_b32 s59, v245, 5
	v_readlane_b32 s60, v245, 6
	v_readlane_b32 s61, v245, 7
	v_readlane_b32 s62, v245, 8
	v_readlane_b32 s63, v245, 9
	v_readlane_b32 s64, v245, 10
	v_readlane_b32 s65, v245, 11
	v_readlane_b32 s70, v245, 16
	v_readlane_b32 s71, v245, 17
	s_waitcnt vmcnt(4)
	v_mov_b32_e32 v37, v26
	s_waitcnt vmcnt(0)
	v_mov_b32_e32 v36, v30
	v_pk_mul_f32 v[36:37], v[36:37], v[34:35]
	s_nop 0
	v_sub_f32_e32 v38, v37, v36
	v_mov_b32_e32 v36, v26
	v_mov_b32_e32 v37, v30
	v_pk_mul_f32 v[36:37], v[36:37], v[34:35]
	v_mov_b32_e32 v26, v31
	v_mov_b32_e32 v30, v27
	v_add_f32_e32 v39, v37, v36
	v_pk_mul_f32 v[36:37], v[26:27], v[34:35]
	v_pk_mul_f32 v[26:27], v[30:31], v[34:35]
	v_sub_f32_e32 v36, v37, v36
	v_add_f32_e32 v30, v27, v26
	v_mov_b32_e32 v26, v32
	v_mov_b32_e32 v27, v28
	v_pk_mul_f32 v[26:27], v[26:27], v[34:35]
	s_nop 0
	v_sub_f32_e32 v31, v27, v26
	v_mov_b32_e32 v26, v28
	v_mov_b32_e32 v27, v32
	v_pk_mul_f32 v[26:27], v[26:27], v[34:35]
	v_mov_b32_e32 v28, v33
	v_add_f32_e32 v37, v27, v26
	v_pk_mul_f32 v[26:27], v[28:29], v[34:35]
	v_mov_b32_e32 v32, v29
	v_sub_f32_e32 v28, v27, v26
	v_pk_mul_f32 v[26:27], v[32:33], v[34:35]
	s_nop 0
	v_add_f32_e32 v29, v27, v26
	v_mov_b32_e32 v26, v22
	v_mov_b32_e32 v27, v18
	v_pk_mul_f32 v[26:27], v[26:27], v[34:35]
	s_nop 0
	v_sub_f32_e32 v32, v27, v26
	v_mov_b32_e32 v26, v18
	v_mov_b32_e32 v27, v22
	v_pk_mul_f32 v[26:27], v[26:27], v[34:35]
	v_mov_b32_e32 v18, v23
	v_mov_b32_e32 v22, v19
	v_add_f32_e32 v33, v26, v27
	v_pk_mul_f32 v[26:27], v[18:19], v[34:35]
	v_pk_mul_f32 v[18:19], v[22:23], v[34:35]
	v_sub_f32_e32 v26, v27, v26
	v_add_f32_e32 v27, v18, v19
	v_mov_b32_e32 v18, v24
	v_mov_b32_e32 v19, v20
	v_pk_mul_f32 v[18:19], v[18:19], v[34:35]
	s_nop 0
	v_sub_f32_e32 v22, v19, v18
	v_mov_b32_e32 v18, v20
	v_mov_b32_e32 v19, v24
	v_pk_mul_f32 v[18:19], v[18:19], v[34:35]
	v_mov_b32_e32 v20, v25
	v_add_f32_e32 v40, v18, v19
	v_pk_mul_f32 v[18:19], v[20:21], v[34:35]
	v_mov_b32_e32 v24, v21
	v_sub_f32_e32 v20, v19, v18
	v_pk_mul_f32 v[18:19], v[24:25], v[34:35]
	s_nop 0
	v_add_f32_e32 v25, v18, v19
	v_mov_b32_e32 v18, v14
	v_mov_b32_e32 v19, v10
	v_pk_mul_f32 v[18:19], v[18:19], v[34:35]
	s_nop 0
	v_sub_f32_e32 v21, v19, v18
	v_mov_b32_e32 v18, v10
	v_mov_b32_e32 v19, v14
	v_pk_mul_f32 v[18:19], v[18:19], v[34:35]
	v_mov_b32_e32 v10, v15
	v_mov_b32_e32 v14, v11
	v_add_f32_e32 v41, v18, v19
	v_pk_mul_f32 v[18:19], v[10:11], v[34:35]
	v_pk_mul_f32 v[10:11], v[14:15], v[34:35]
	v_sub_f32_e32 v18, v19, v18
	v_add_f32_e32 v42, v10, v11
	v_mov_b32_e32 v10, v16
; template <int MODE>
; __device__ __forceinline__ void s5_unit(const Params& P, unsigned char* wl, const int id) {
;     ...
;     { s5_setup(P, g, lane, ar, ai, Br, Bi);
;       u32x4 w[4], v[4];
; #pragma unroll
;       for (int i = 0; i < 4; ++i) { unsigned hw[4], lw[4];
; #pragma unroll
;           for (int e = 0; e < 4; ++e) { const int c0 = (i & 1) * 8 + 2 * e; const float x0 = (i < 2) ? Br[c0] : Bi[c0], x1 = (i < 2) ? Br[c0 + 1] : Bi[c0 + 1];
;               const unsigned h = cvt_pk_bf16(x0, x1); hw[e] = h; lw[e] = cvt_pk_bf16(x0 - bflo(h), x1 - bfhi(h)); }
;           w[i] = (u32x4){hw[0], hw[1], hw[2], hw[3]}; v[i] = (u32x4){lw[0], lw[1], lw[2], lw[3]}; }
;       u32x4* bt = (u32x4*)(Btab + lane * 32); bt[0] = w[0]; bt[1] = w[1]; bt[2] = w[2]; bt[3] = w[3];
;       u32x4* lt = (u32x4*)((bf16_t*)buf + lane * 32); lt[0] = v[0]; lt[1] = v[1]; lt[2] = v[2]; lt[3] = v[3]; }
;     asm volatile("s_waitcnt lgkmcnt(0)" ::: "memory");
;     const bf16x8 zf = (bf16x8){0, 0, 0, 0, 0, 0, 0, 0};
;     bf16x8 bfr[8];
; #pragma unroll
;     for (int nn = 0; nn < 8; ++nn) bfr[nn] = *(const bf16x8*)((q < 2 ? Btab : (const bf16_t*)buf) + (16 * nn + l16) * 16 + 8 * (q & 1));
;     asm volatile("s_waitcnt lgkmcnt(0)" ::: "memory");
;     float hr = 0.f, hi = 0.f;
;     if (MODE == 1) { float pr = ar, pi = ai;
; #pragma unroll
;         for (int i = 0; i < 7; ++i) { const float t = pr * pr - pi * pi; pi = 2.0f * pr * pi; pr = t; }
;         const f32x2* E = (const f32x2*)(P.ws + O_ESSM);
;         { const f32x2 e = E[(size_t)(64 * 64 + g) * 64 + lane]; hr = e.x; hi = e.y; }
;         for (int i = 0; i < c; ++i) { const f32x2 e = E[(size_t)((b * 16 + i) * 64 + g) * 64 + lane]; const float nr_ = pr * hr - pi * hi + e.x, ni_ = pr * hi + pi * hr + e.y; hr = nr_; hi = ni_; } }
;     bf16x8 cf[4]; float dsk = 0.f;
;     if (MODE >= 1) {
; #pragma unroll
;         for (int ks = 0; ks < 4; ++ks) { const int p0 = 16 * ks + 4 * q; const f32x4 cr = *(const f32x4*)(P.in[15] + (size_t)(g * 16 + l16) * 64 + p0), ci = *(const f32x4*)(P.in[16] + (size_t)(g * 16 + l16) * 64 + p0);
;             bf16x8 f; f[0] = (short)f2bf(cr[0]); f[1] = (short)f2bf(-ci[0]); f[2] = (short)f2bf(cr[1]); f[3] = (short)f2bf(-ci[1]); f[4] = (short)f2bf(cr[2]); f[5] = (short)f2bf(-ci[2]); f[6] = (short)f2bf(cr[3]); f[7] = (short)f2bf(-ci[3]); cf[ks] = f; }
;         dsk = P.in[17][g * 16 + l16]; }
	v_mov_b32_e32 v11, v12
	v_pk_mul_f32 v[10:11], v[10:11], v[34:35]
	s_nop 0
	v_sub_f32_e32 v15, v11, v10
	v_mov_b32_e32 v10, v12
	v_mov_b32_e32 v11, v16
	v_pk_mul_f32 v[10:11], v[10:11], v[34:35]
	v_mov_b32_e32 v12, v17
	v_add_f32_e32 v43, v10, v11
	v_pk_mul_f32 v[10:11], v[12:13], v[34:35]
	v_mov_b32_e32 v16, v13
	v_sub_f32_e32 v12, v11, v10
	v_pk_mul_f32 v[10:11], v[16:17], v[34:35]
	s_nop 0
	v_add_f32_e32 v49, v10, v11
	v_mov_b32_e32 v10, v6
	v_mov_b32_e32 v11, v2
	v_pk_mul_f32 v[10:11], v[10:11], v[34:35]
	s_nop 0
	v_sub_f32_e32 v13, v11, v10
	v_mov_b32_e32 v10, v2
	v_mov_b32_e32 v11, v6
	v_pk_mul_f32 v[10:11], v[10:11], v[34:35]
	v_mov_b32_e32 v2, v7
	v_mov_b32_e32 v6, v3
	v_add_f32_e32 v50, v10, v11
	v_pk_mul_f32 v[10:11], v[2:3], v[34:35]
	v_pk_mul_f32 v[2:3], v[6:7], v[34:35]
	v_sub_f32_e32 v16, v11, v10
	v_add_f32_e32 v51, v2, v3
	v_mov_b32_e32 v2, v8
	v_mov_b32_e32 v3, v4
	v_pk_mul_f32 v[2:3], v[2:3], v[34:35]
	s_nop 0
	v_sub_f32_e32 v17, v3, v2
	v_mov_b32_e32 v2, v4
	v_mov_b32_e32 v3, v8
	v_pk_mul_f32 v[2:3], v[2:3], v[34:35]
	v_mov_b32_e32 v4, v9
	v_add_f32_e32 v55, v2, v3
	v_pk_mul_f32 v[2:3], v[4:5], v[34:35]
	v_mov_b32_e32 v8, v5
	v_sub_f32_e32 v19, v3, v2
	v_pk_mul_f32 v[2:3], v[8:9], v[34:35]
	s_nop 0
	v_add_f32_e32 v34, v2, v3
	v_cvt_pk_bf16_f32 v2, v38, v36
	s_nop 0
	v_lshlrev_b32_e32 v3, 16, v2
	v_and_b32_e32 v4, 0xffff0000, v2
	v_sub_f32_e32 v3, v38, v3
	v_sub_f32_e32 v4, v36, v4
	v_cvt_pk_bf16_f32 v6, v3, v4
	v_cvt_pk_bf16_f32 v3, v31, v28
	v_lshlrev_b32_e32 v36, 5, v52
	v_lshlrev_b32_e32 v4, 16, v3
	v_and_b32_e32 v5, 0xffff0000, v3
	v_sub_f32_e32 v4, v31, v4
	v_sub_f32_e32 v5, v28, v5
	v_cvt_pk_bf16_f32 v7, v4, v5
	v_cvt_pk_bf16_f32 v4, v32, v26
	v_lshlrev_b32_e32 v38, 1, v150
	v_lshlrev_b32_e32 v5, 16, v4
	v_and_b32_e32 v8, 0xffff0000, v4
	v_sub_f32_e32 v5, v32, v5
	v_sub_f32_e32 v8, v26, v8
	v_cvt_pk_bf16_f32 v8, v5, v8
	v_cvt_pk_bf16_f32 v5, v22, v20
	s_nop 0
	v_lshlrev_b32_e32 v9, 16, v5
	v_and_b32_e32 v10, 0xffff0000, v5
	v_sub_f32_e32 v9, v22, v9
	v_sub_f32_e32 v10, v20, v10
	v_cvt_pk_bf16_f32 v9, v9, v10
	v_cvt_pk_bf16_f32 v10, v21, v18
	s_nop 0
	v_lshlrev_b32_e32 v11, 16, v10
	v_and_b32_e32 v14, 0xffff0000, v10
	v_sub_f32_e32 v11, v21, v11
	v_sub_f32_e32 v14, v18, v14
	v_cvt_pk_bf16_f32 v14, v11, v14
	v_cvt_pk_bf16_f32 v11, v15, v12
	s_nop 0
	v_lshlrev_b32_e32 v18, 16, v11
	v_sub_f32_e32 v15, v15, v18
	v_and_b32_e32 v18, 0xffff0000, v11
	v_sub_f32_e32 v12, v12, v18
	v_cvt_pk_bf16_f32 v15, v15, v12
	v_cvt_pk_bf16_f32 v12, v13, v16
	s_nop 0
	v_lshlrev_b32_e32 v18, 16, v12
	v_sub_f32_e32 v13, v13, v18
	v_and_b32_e32 v18, 0xffff0000, v12
	v_sub_f32_e32 v16, v16, v18
	v_cvt_pk_bf16_f32 v16, v13, v16
	v_cvt_pk_bf16_f32 v13, v17, v19
	s_nop 0
	v_lshlrev_b32_e32 v18, 16, v13
	v_sub_f32_e32 v17, v17, v18
	v_and_b32_e32 v18, 0xffff0000, v13
	v_sub_f32_e32 v18, v19, v18
	v_cvt_pk_bf16_f32 v17, v17, v18
	v_cvt_pk_bf16_f32 v18, v39, v30
	s_nop 0
	v_lshlrev_b32_e32 v19, 16, v18
	v_and_b32_e32 v20, 0xffff0000, v18
	v_sub_f32_e32 v19, v39, v19
	v_sub_f32_e32 v20, v30, v20
	v_cvt_pk_bf16_f32 v22, v19, v20
	v_cvt_pk_bf16_f32 v19, v37, v29
	v_mov_b32_e32 v39, v0
	v_lshlrev_b32_e32 v20, 16, v19
	v_and_b32_e32 v21, 0xffff0000, v19
	v_sub_f32_e32 v20, v37, v20
	v_sub_f32_e32 v21, v29, v21
	v_cvt_pk_bf16_f32 v23, v20, v21
	v_cvt_pk_bf16_f32 v20, v33, v27
	v_mov_b32_e32 v37, v0
	v_lshlrev_b32_e32 v21, 16, v20
	v_and_b32_e32 v24, 0xffff0000, v20
	v_sub_f32_e32 v21, v33, v21
	v_sub_f32_e32 v24, v27, v24
	v_cvt_pk_bf16_f32 v24, v21, v24
	v_cvt_pk_bf16_f32 v21, v40, v25
	s_nop 0
	v_lshlrev_b32_e32 v26, 16, v21
	v_and_b32_e32 v27, 0xffff0000, v21
	v_sub_f32_e32 v26, v40, v26
	v_sub_f32_e32 v25, v25, v27
	v_cvt_pk_bf16_f32 v25, v26, v25
	v_cvt_pk_bf16_f32 v26, v41, v42
	s_nop 0
	v_lshlrev_b32_e32 v27, 16, v26
	v_and_b32_e32 v28, 0xffff0000, v26
	v_sub_f32_e32 v27, v41, v27
	v_sub_f32_e32 v28, v42, v28
	v_cvt_pk_bf16_f32 v30, v27, v28
	v_cvt_pk_bf16_f32 v27, v43, v49
	s_nop 0
	v_lshlrev_b32_e32 v28, 16, v27
	v_and_b32_e32 v29, 0xffff0000, v27
	v_sub_f32_e32 v28, v43, v28
	v_sub_f32_e32 v29, v49, v29
	v_cvt_pk_bf16_f32 v31, v28, v29
	v_cvt_pk_bf16_f32 v28, v50, v51
	v_mov_b32_e32 v49, v48
	v_lshlrev_b32_e32 v29, 16, v28
	v_and_b32_e32 v32, 0xffff0000, v28
	v_sub_f32_e32 v29, v50, v29
	v_sub_f32_e32 v32, v51, v32
	v_cvt_pk_bf16_f32 v32, v29, v32
	v_cvt_pk_bf16_f32 v29, v55, v34
	s_nop 0
	v_lshlrev_b32_e32 v33, 16, v29
	v_sub_f32_e32 v33, v55, v33
	v_and_b32_e32 v35, 0xffff0000, v29
	v_sub_f32_e32 v34, v34, v35
	v_cvt_pk_bf16_f32 v33, v33, v34
	ds_write_b128 v155, v[2:5]
	ds_write_b128 v155, v[10:13] offset:16
	ds_write_b128 v155, v[18:21] offset:32
	ds_write_b128 v155, v[26:29] offset:48
	ds_write_b128 v155, v[6:9] offset:4096
	ds_write_b128 v155, v[14:17] offset:4112
	ds_write_b128 v155, v[22:25] offset:4128
	ds_write_b128 v155, v[30:33] offset:4144
	v_mov_b64_e32 v[2:3], s[0:1]
	v_mad_i64_i32 v[2:3], s[0:1], v1, s90, v[2:3]
	s_waitcnt lgkmcnt(0)
	v_lshl_add_u64 v[2:3], v[2:3], 0, v[36:37]
	ds_read_b128 v[4:7], v183
	ds_read_b128 v[8:11], v183 offset:512
	ds_read_b128 v[12:15], v183 offset:1024
	ds_read_b128 v[16:19], v183 offset:1536
	ds_read_b128 v[20:23], v183 offset:2048
	ds_read_b128 v[24:27], v183 offset:2560
	ds_read_b128 v[28:31], v183 offset:3072
	ds_read_b128 v[32:35], v183 offset:3584
	s_waitcnt lgkmcnt(0)
	v_lshl_add_u64 v[2:3], v[2:3], 0, v[38:39]
	global_load_dwordx4 v[40:43], v[2:3], off
	v_mad_i64_i32 v[2:3], s[0:1], v1, s90, v[36:37]
	v_lshl_add_u64 v[50:51], v[170:171], 0, v[2:3]
	s_mov_b64 s[0:1], 0
	s_waitcnt vmcnt(0)
	s_branch .LBB0_367
; template <int MODE>
; __device__ __forceinline__ void s5_unit(const Params& P, unsigned char* wl, const int id) {
;     ...
;     for (int blk = 0; blk < nblk; ++blk) {
;         bf16x8 a_nxt = zf; if (blk + 1 < nblk) a_nxt = *(const bf16x8*)(arow + (size_t)(blk + 1) * 16 * NPROJ);
;         { float* bp = buf + (4 * q) * 130 + l16; f32x4 d[8];
; #pragma unroll
;           for (int nn = 0; nn < 8; ++nn) d[nn] = mfma16(a_cur, bfr[nn], (f32x4){0.f, 0.f, 0.f, 0.f});
;           __builtin_amdgcn_sched_barrier(0); asm volatile("s_nop 15\n\ts_nop 15" ::: "memory"); __builtin_amdgcn_sched_barrier(0);
; #pragma unroll
;           for (int nn = 0; nn < 8; ++nn) { bp[16 * nn] = d[nn][0]; bp[130 + 16 * nn] = d[nn][1]; bp[260 + 16 * nn] = d[nn][2]; bp[390 + 16 * nn] = d[nn][3]; } }
;         if (MODE >= 1 && q < 2) *(bf16x8*)(Ub + l16 * 16 + 8 * q) = a_cur;
;         asm volatile("s_waitcnt lgkmcnt(0)" ::: "memory");
;     ...
;         if (MODE == 1) { float mxd = 0.f, mxa = 0.f;
;         for (int t = 0; t < 16; ++t) { const u32x4* upp = (const u32x4*)(PROJ + (size_t)(row0 + blk * 16 + t) * NPROJ + C_U + g * 16); f32x4 ua, ub, uc, ud; unpack8(upp[0], ua, ub); unpack8(upp[1], uc, ud);
;             float br = 0.f, bi = 0.f;
; #pragma unroll
;             for (int e = 0; e < 4; ++e) { br += Br[e] * ua[e] + Br[4 + e] * ub[e] + Br[8 + e] * uc[e] + Br[12 + e] * ud[e]; bi += Bi[e] * ua[e] + Bi[4 + e] * ub[e] + Bi[8 + e] * uc[e] + Bi[12 + e] * ud[e]; }
;             const f32x2 mm = *(const f32x2*)(buf + t * 130 + 2 * lane);
;             mxd = fmaxf(mxd, fmaxf(fabsf(mm.x - br), fabsf(mm.y - bi))); mxa = fmaxf(mxa, fmaxf(fabsf(br), fabsf(bi))); }
;         mxd = wave_max(mxd); mxa = wave_max(mxa);
;         if (lane == 0) { atomicMax((unsigned*)(P.ws + O_BAR) + 0, __float_as_uint(mxd)); atomicMax((unsigned*)(P.ws + O_BAR) + 1, __float_as_uint(mxa)); } }
;     ...
;         for (int t = 0; t < 16; ++t) { const u32x4* upp = (const u32x4*)(PROJ + (size_t)(row0 + blk * 16 + t) * NPROJ + C_U + g * 16); f32x4 ua, ub, uc, ud; unpack8(upp[0], ua, ub); unpack8(upp[1], uc, ud);
;             float br = 0.f, bi = 0.f;
; #pragma unroll
;             for (int e = 0; e < 4; ++e) { br += Br[e] * ua[e] + Br[4 + e] * ub[e] + Br[8 + e] * uc[e] + Br[12 + e] * ud[e]; bi += Bi[e] * ua[e] + Bi[4 + e] * ub[e] + Bi[8 + e] * uc[e] + Bi[12 + e] * ud[e]; }
;             *(f32x2*)(buf + t * 130 + 2 * lane) = (f32x2){br, bi}; }
.LBB0_366:
	s_or_b64 exec, exec, s[8:9]
	s_waitcnt lgkmcnt(7)
	v_mfma_f32_16x16x32_bf16 v[56:59], v[40:43], v[4:7], 0
	s_waitcnt lgkmcnt(6)
	v_mfma_f32_16x16x32_bf16 v[60:63], v[40:43], v[8:11], 0
	s_waitcnt lgkmcnt(5)
	v_mfma_f32_16x16x32_bf16 v[64:67], v[40:43], v[12:15], 0
	s_waitcnt lgkmcnt(4)
	v_mfma_f32_16x16x32_bf16 v[68:71], v[40:43], v[16:19], 0
	s_waitcnt lgkmcnt(3)
	v_mfma_f32_16x16x32_bf16 v[72:75], v[40:43], v[20:23], 0
	s_waitcnt lgkmcnt(2)
	v_mfma_f32_16x16x32_bf16 v[76:79], v[40:43], v[24:27], 0
	s_waitcnt lgkmcnt(1)
	v_mfma_f32_16x16x32_bf16 v[80:83], v[40:43], v[28:31], 0
	s_waitcnt lgkmcnt(0)
	v_mfma_f32_16x16x32_bf16 v[40:43], v[40:43], v[32:35], 0
	s_nop 15
	s_nop 15
	v_add_u32_e32 v1, 0x1000, v212
	v_add_u32_e32 v2, 0x1400, v212
	ds_write2_b32 v1, v56, v60 offset1:16
	ds_write2_b32 v1, v57, v61 offset0:130 offset1:146
	ds_write2_b32 v2, v58, v62 offset0:4 offset1:20
	ds_write2_b32 v2, v59, v63 offset0:134 offset1:150
	ds_write2_b32 v1, v64, v68 offset0:32 offset1:48
	ds_write2_b32 v1, v65, v69 offset0:162 offset1:178
	ds_write2_b32 v2, v66, v70 offset0:36 offset1:52
	ds_write2_b32 v2, v67, v71 offset0:166 offset1:182
	ds_write2_b32 v1, v72, v76 offset0:64 offset1:80
	ds_write2_b32 v1, v73, v77 offset0:194 offset1:210
	ds_write2_b32 v2, v74, v78 offset0:68 offset1:84
	ds_write2_b32 v2, v75, v79 offset0:198 offset1:214
	ds_write2_b32 v1, v80, v40 offset0:96 offset1:112
	ds_write2_b32 v1, v81, v41 offset0:226 offset1:242
	ds_write2_b32 v2, v82, v42 offset0:100 offset1:116
	ds_write2_b32 v2, v83, v43 offset0:230 offset1:246
	s_waitcnt lgkmcnt(0)
	v_add_u32_e32 v1, 0x1000, v218
	ds_read2_b64 v[40:43], v1 offset1:65
	ds_read2_b64 v[56:59], v1 offset0:130 offset1:195
	v_mul_f32_e32 v2, v45, v49
	v_pk_fma_f32 v[2:3], v[44:45], v[48:49], v[2:3] op_sel_hi:[1,1,0] neg_lo:[0,0,1] neg_hi:[0,0,1]
	v_pk_mul_f32 v[48:49], v[44:45], v[48:49] op_sel:[0,1] op_sel_hi:[1,0]
	s_waitcnt lgkmcnt(1)
	v_pk_add_f32 v[2:3], v[2:3], v[40:41]
	v_add_f32_e32 v48, v48, v49
	v_pk_add_f32 v[40:41], v[48:49], v[40:41] op_sel:[0,1] op_sel_hi:[0,1]
	v_pk_mul_f32 v[40:41], v[46:47], v[40:41]
	v_add_u32_e32 v1, 0x1800, v218
	v_pk_fma_f32 v[48:49], v[44:45], v[2:3], v[40:41] neg_lo:[0,0,1] neg_hi:[0,0,1]
	v_pk_fma_f32 v[2:3], v[44:45], v[2:3], v[40:41] op_sel_hi:[1,0,1]
	ds_read2_b64 v[60:63], v1 offset0:4 offset1:69
	ds_read2_b64 v[64:67], v1 offset0:134 offset1:199
	v_mov_b32_e32 v49, v3
	v_pk_add_f32 v[2:3], v[42:43], v[48:49]
	v_add_u32_e32 v1, 0x2000, v218
	v_mul_f32_e32 v40, v45, v3
	v_pk_fma_f32 v[40:41], v[44:45], v[2:3], v[40:41] op_sel_hi:[1,1,0] neg_lo:[0,0,1] neg_hi:[0,0,1]
	v_pk_mul_f32 v[2:3], v[46:47], v[2:3]
	s_waitcnt lgkmcnt(2)
	v_pk_add_f32 v[40:41], v[56:57], v[40:41]
	v_add_f32_e32 v2, v2, v3
	v_pk_add_f32 v[2:3], v[56:57], v[2:3] op_sel:[1,0] op_sel_hi:[1,0]
	ds_read2_b64 v[68:71], v1 offset0:8 offset1:73
	ds_read2_b64 v[72:75], v1 offset0:138 offset1:203
	v_pk_mul_f32 v[2:3], v[46:47], v[2:3]
	v_add_u32_e32 v1, 0x2800, v218
	v_pk_fma_f32 v[42:43], v[44:45], v[40:41], v[2:3] neg_lo:[0,0,1] neg_hi:[0,0,1]
	v_pk_fma_f32 v[2:3], v[44:45], v[40:41], v[2:3] op_sel_hi:[1,0,1]
	ds_read2_b64 v[76:79], v1 offset0:12 offset1:77
	ds_read2_b64 v[80:83], v1 offset0:142 offset1:207
	v_mov_b32_e32 v43, v3
	v_pk_add_f32 v[2:3], v[58:59], v[42:43]
	s_waitcnt lgkmcnt(0)
	s_mov_b64 s[8:9], 0x48000
	v_mul_f32_e32 v40, v45, v3
	v_pk_fma_f32 v[40:41], v[44:45], v[2:3], v[40:41] op_sel_hi:[1,1,0] neg_lo:[0,0,1] neg_hi:[0,0,1]
	v_pk_mul_f32 v[2:3], v[46:47], v[2:3]
	s_waitcnt lgkmcnt(5)
; __device__ __forceinline__ unsigned cvt_pk_bf16(float lo, float hi) { unsigned r; asm volatile("v_cvt_pk_bf16_f32 %0, %1, %2" : "=v"(r) : "v"(lo), "v"(hi)); return r; }
; __device__ __forceinline__ bf16_t f2bf(float f) { unsigned u = __float_as_uint(f); u += 0x7FFFu + ((u >> 16) & 1u); return (bf16_t)(u >> 16); }
; __device__ __forceinline__ float bf2f(bf16_t b) { return __uint_as_float(((unsigned)b) << 16); }
; __device__ __forceinline__ float gelu_tanh(float x) { const float z = 1.5957691216057308f * (x + 0.044715f * x * x * x); return x * sigmoidf_(z); }
; __device__ __forceinline__ f32x4 mfma16(bf16x8 a, bf16x8 b, f32x4 c) { return __builtin_amdgcn_mfma_f32_16x16x32_bf16(a, b, c, 0, 0, 0); }
; template <int MODE>
; __device__ __forceinline__ void s5_unit(const Params& P, unsigned char* wl, const int id) {
;     ...
;             for (int t = 0; t < 16; ++t) bb[t] = *(const f32x2*)(buf + t * 130 + 2 * lane);
; #pragma unroll
;             for (int t = 0; t < 16; ++t) { const float nr_ = ar * hr - ai * hi + bb[t].x, ni_ = ar * hi + ai * hr + bb[t].y; hr = nr_; hi = ni_;
;                 if (MODE == 1) Hw[t * 68 + lane] = cvt_pk_bf16(hr, hi); }
;         }
;         if (MODE >= 1) {
;             asm volatile("s_waitcnt lgkmcnt(0)" ::: "memory");
;             f32x4 acc = (f32x4){0.f, 0.f, 0.f, 0.f};
; #pragma unroll
;             for (int ks = 0; ks < 4; ++ks) acc = mfma16(*(const bf16x8*)((const bf16_t*)Hw + l16 * 136 + 32 * ks + 8 * q), cf[ks], acc);
;             __builtin_amdgcn_sched_barrier(0); asm volatile("s_nop 15\n\ts_nop 15" : "+v"(acc) :: "memory"); __builtin_amdgcn_sched_barrier(0);
;             const bf16_t* up = Ub + (4 * q) * 16 + l16; bf16_t* gp = G + (size_t)(row0 + blk * 16 + 4 * q) * 1024 + g * 16 + l16;
; #pragma unroll
;             for (int r = 0; r < 4; ++r) { const float y = acc[r] + dsk * bf2f(up[r * 16]); gp[r * 1024] = f2bf(gelu_tanh(y)); }
;         }
;         asm volatile("s_waitcnt lgkmcnt(0)" ::: "memory");
;         a_cur = a_nxt;
	v_pk_add_f32 v[40:41], v[60:61], v[40:41]
	v_add_f32_e32 v2, v2, v3
	v_pk_add_f32 v[2:3], v[60:61], v[2:3] op_sel:[1,0] op_sel_hi:[1,0]
	v_cmp_eq_u32_e32 vcc, s10, v53
	v_pk_mul_f32 v[2:3], v[46:47], v[2:3]
	v_lshl_add_u64 v[50:51], v[50:51], 0, s[8:9]
	v_pk_fma_f32 v[42:43], v[44:45], v[40:41], v[2:3] neg_lo:[0,0,1] neg_hi:[0,0,1]
	v_pk_fma_f32 v[2:3], v[44:45], v[40:41], v[2:3] op_sel_hi:[1,0,1]
	s_or_b64 s[0:1], vcc, s[0:1]
	v_mov_b32_e32 v43, v3
	v_pk_add_f32 v[2:3], v[62:63], v[42:43]
	s_nop 0
	v_mul_f32_e32 v40, v45, v3
	v_pk_fma_f32 v[40:41], v[44:45], v[2:3], v[40:41] op_sel_hi:[1,1,0] neg_lo:[0,0,1] neg_hi:[0,0,1]
	v_pk_mul_f32 v[2:3], v[46:47], v[2:3]
	s_waitcnt lgkmcnt(4)
	v_pk_add_f32 v[40:41], v[64:65], v[40:41]
	v_add_f32_e32 v2, v2, v3
	v_pk_add_f32 v[2:3], v[64:65], v[2:3] op_sel:[1,0] op_sel_hi:[1,0]
	s_nop 0
	v_pk_mul_f32 v[2:3], v[46:47], v[2:3]
	s_nop 0
	v_pk_fma_f32 v[42:43], v[44:45], v[40:41], v[2:3] neg_lo:[0,0,1] neg_hi:[0,0,1]
	v_pk_fma_f32 v[2:3], v[44:45], v[40:41], v[2:3] op_sel_hi:[1,0,1]
	s_nop 0
	v_mov_b32_e32 v43, v3
	v_pk_add_f32 v[2:3], v[66:67], v[42:43]
	s_nop 0
	v_mul_f32_e32 v40, v45, v3
	v_pk_fma_f32 v[40:41], v[44:45], v[2:3], v[40:41] op_sel_hi:[1,1,0] neg_lo:[0,0,1] neg_hi:[0,0,1]
	v_pk_mul_f32 v[2:3], v[46:47], v[2:3]
	s_waitcnt lgkmcnt(3)
	v_pk_add_f32 v[40:41], v[68:69], v[40:41]
	v_add_f32_e32 v2, v2, v3
	v_pk_add_f32 v[2:3], v[68:69], v[2:3] op_sel:[1,0] op_sel_hi:[1,0]
	s_nop 0
	v_pk_mul_f32 v[2:3], v[46:47], v[2:3]
	s_nop 0
	v_pk_fma_f32 v[42:43], v[44:45], v[40:41], v[2:3] neg_lo:[0,0,1] neg_hi:[0,0,1]
	v_pk_fma_f32 v[2:3], v[44:45], v[40:41], v[2:3] op_sel_hi:[1,0,1]
	s_nop 0
	v_mov_b32_e32 v43, v3
	v_pk_add_f32 v[2:3], v[70:71], v[42:43]
	s_nop 0
	v_mul_f32_e32 v40, v45, v3
	v_pk_fma_f32 v[40:41], v[44:45], v[2:3], v[40:41] op_sel_hi:[1,1,0] neg_lo:[0,0,1] neg_hi:[0,0,1]
	v_pk_mul_f32 v[2:3], v[46:47], v[2:3]
	s_waitcnt lgkmcnt(2)
	v_pk_add_f32 v[40:41], v[72:73], v[40:41]
	v_add_f32_e32 v2, v2, v3
	v_pk_add_f32 v[2:3], v[72:73], v[2:3] op_sel:[1,0] op_sel_hi:[1,0]
	s_nop 0
	v_pk_mul_f32 v[2:3], v[46:47], v[2:3]
	s_nop 0
	v_pk_fma_f32 v[42:43], v[44:45], v[40:41], v[2:3] neg_lo:[0,0,1] neg_hi:[0,0,1]
	v_pk_fma_f32 v[2:3], v[44:45], v[40:41], v[2:3] op_sel_hi:[1,0,1]
	s_nop 0
	v_mov_b32_e32 v43, v3
	v_pk_add_f32 v[2:3], v[74:75], v[42:43]
	s_nop 0
	v_mul_f32_e32 v40, v45, v3
	v_pk_fma_f32 v[40:41], v[44:45], v[2:3], v[40:41] op_sel_hi:[1,1,0] neg_lo:[0,0,1] neg_hi:[0,0,1]
	v_pk_mul_f32 v[2:3], v[46:47], v[2:3]
	s_waitcnt lgkmcnt(1)
	v_pk_add_f32 v[40:41], v[76:77], v[40:41]
	v_add_f32_e32 v2, v2, v3
	v_pk_add_f32 v[2:3], v[76:77], v[2:3] op_sel:[1,0] op_sel_hi:[1,0]
	s_nop 0
	v_pk_mul_f32 v[2:3], v[46:47], v[2:3]
	s_nop 0
	v_pk_fma_f32 v[42:43], v[44:45], v[40:41], v[2:3] neg_lo:[0,0,1] neg_hi:[0,0,1]
	v_pk_fma_f32 v[2:3], v[44:45], v[40:41], v[2:3] op_sel_hi:[1,0,1]
	s_nop 0
	v_mov_b32_e32 v43, v3
	v_pk_add_f32 v[2:3], v[78:79], v[42:43]
	s_nop 0
	v_mul_f32_e32 v40, v45, v3
	v_pk_fma_f32 v[40:41], v[44:45], v[2:3], v[40:41] op_sel_hi:[1,1,0] neg_lo:[0,0,1] neg_hi:[0,0,1]
	v_pk_mul_f32 v[2:3], v[46:47], v[2:3]
	s_waitcnt lgkmcnt(0)
	v_pk_add_f32 v[40:41], v[80:81], v[40:41]
	v_add_f32_e32 v2, v2, v3
	v_pk_add_f32 v[2:3], v[80:81], v[2:3] op_sel:[1,0] op_sel_hi:[1,0]
	s_nop 0
	v_pk_mul_f32 v[2:3], v[46:47], v[2:3]
	s_nop 0
	v_pk_fma_f32 v[42:43], v[44:45], v[40:41], v[2:3] neg_lo:[0,0,1] neg_hi:[0,0,1]
	v_pk_fma_f32 v[2:3], v[44:45], v[40:41], v[2:3] op_sel_hi:[1,0,1]
	s_nop 0
	v_mov_b32_e32 v43, v3
	v_pk_add_f32 v[48:49], v[82:83], v[42:43]
	s_waitcnt vmcnt(0)
	v_mov_b64_e32 v[42:43], v[38:39]
	v_mov_b64_e32 v[40:41], v[36:37]
	s_andn2_b64 exec, exec, s[0:1]
	s_cbranch_execz .LBB0_375

; __global__ void __launch_bounds__(512, 2) fwd(Params P) {
;     ...
;         for (int r2 = 0; r2 < NREP(13); ++r2) for (int id = blockIdx.x * 8 + wave; id < 4352; id += gridDim.x * 8) {
;             if (id < 2048 && (id & 7) == 0) { mlstm_decode_wave(P, shm + wave * S5_WL, 256 + (id >> 3)); continue; }
;             s5_unit<1>(P, shm + wave * S5_WL, id < 2048 ? id - (id >> 3) - 1 : 1792 + (id - 2048)); }
.LBB0_439:
	s_or_b64 exec, exec, s[4:5]
	v_lshl_add_u32 v145, s94, 3, v215
	s_lshl_b32 s1, s96, 3
	s_cmpk_eq_i32 s96, 0x100
	s_cselect_b32 s0, 0x700, s1
	v_mov_b32_e32 v242, s0
	v_mov_b32_e32 v240, s94
	v_sub_u32_e32 v240, 0x7ff, v240
	v_mov_b32_e32 v241, 0x4000
	v_cmp_eq_u32_e32 vcc, 0, v215
	s_nop 1
	v_cndmask_b32_e32 v240, v240, v241, vcc
	v_mov_b32_e32 v241, s1
	s_cselect_b64 vcc, -1, 0
	s_nop 1
	v_cndmask_b32_e32 v240, v241, v240, vcc
	s_movk_i32 s0, 0x1100
	v_cmp_gt_i32_e32 vcc, s0, v145
	s_and_saveexec_b64 s[16:17], vcc
	s_cbranch_execz .LBB0_469
	s_movk_i32 s0, 0x4200
	v_mad_u32_u24 v153, v215, s0, 0
	v_and_b32_e32 v144, 63, v214
	v_add_u32_e32 v0, 0x1000, v153
	s_add_u32 s18, s12, 0x4542000
	v_cmp_gt_u32_e64 s[2:3], 32, v144
	s_addc_u32 s19, s13, 0
	v_and_b32_e32 v157, 15, v214
	v_cndmask_b32_e64 v2, v0, v153, s[2:3]
	v_lshrrev_b32_e32 v0, 1, v214
	v_and_b32_e32 v0, 8, v0
	v_mov_b32_e32 v147, 0
	s_add_u32 s20, s12, 0x1e5cb000
	v_bfe_u32 v1, v214, 4, 2
	v_lshlrev_b32_e32 v3, 1, v0
	v_lshlrev_b32_e32 v4, 5, v157
	s_addc_u32 s21, s13, 0
	v_lshlrev_b32_e32 v148, 3, v144
	v_mov_b32_e32 v149, v147
	v_add3_u32 v216, v2, v3, v4
	v_lshl_add_u64 v[150:151], s[20:21], 0, v[148:149]
	v_mul_u32_u24_e32 v2, 0x820, v1
	v_lshlrev_b32_e32 v149, 2, v157
	v_lshlrev_b32_e32 v146, 1, v157
	v_add3_u32 v217, v153, v2, v149
	v_lshl_add_u64 v[2:3], s[12:13], 0, v[146:147]
	s_mov_b64 s[0:1], 0x2100000
	v_add_u32_e32 v5, v153, v146
	v_lshl_add_u64 v[154:155], v[2:3], 0, s[0:1]
	v_mul_u32_u24_e32 v2, 30, v157
	v_and_b32_e32 v146, 48, v214
	v_readlane_b32 s52, v245, 34
	v_add3_u32 v218, v5, v2, v146
	v_mul_u32_u24_e32 v2, 0x110, v157
	v_lshlrev_b32_e32 v158, 4, v144
	v_mov_b32_e32 v159, v147
	v_readlane_b32 s53, v245, 35
	v_readlane_b32 s54, v245, 36
	v_readlane_b32 s55, v245, 37
	v_readlane_b32 s56, v245, 38
	v_readlane_b32 s57, v245, 39
	v_readlane_b32 s58, v245, 40
	v_readlane_b32 s59, v245, 41
	v_readlane_b32 s60, v245, 42
	v_readlane_b32 s61, v245, 43
	v_readlane_b32 s62, v245, 44
	v_readlane_b32 s63, v245, 45
	v_readlane_b32 s64, v245, 46
	v_readlane_b32 s65, v245, 47
	v_readlane_b32 s66, v245, 48
	v_readlane_b32 s67, v245, 49
	v_add3_u32 v219, v153, v2, v146
	v_readlane_b32 s68, v245, 18
	v_lshl_add_u64 v[2:3], s[66:67], 0, v[158:159]
	v_readlane_b32 s52, v245, 2
	s_add_u32 s22, s12, 0x4500000
	v_readlane_b32 s69, v245, 19
	s_mov_b64 s[0:1], 0xc924040
	v_readlane_b32 s66, v245, 16
	v_readlane_b32 s67, v245, 17
	s_addc_u32 s23, s13, 0
	v_lshl_add_u64 v[164:165], v[2:3], 0, s[0:1]
	v_and_b32_e32 v2, 0x1c0, v214
	v_lshl_add_u64 v[166:167], s[66:67], 0, v[146:147]
	v_lshl_add_u64 v[168:169], s[68:69], 0, v[146:147]
	v_and_b32_e32 v146, 16, v214
	v_lshlrev_b32_e32 v156, 2, v144
	s_add_u32 s24, s12, 0x12dc2000
	v_cmp_eq_u32_e64 s[6:7], 0, v2
	v_lshl_add_u64 v[2:3], s[12:13], 0, v[146:147]
	s_mov_b64 s[0:1], 0x458a000
	v_lshlrev_b32_e32 v152, 2, v1
	v_lshlrev_b32_e32 v4, 6, v157
	v_lshlrev_b32_e32 v1, 7, v1
	v_add_u32_e32 v220, v153, v156
	v_mul_u32_u24_e32 v6, 12, v144
	v_readlane_b32 s78, v245, 28
	v_readlane_b32 s79, v245, 29
	s_addc_u32 s25, s13, 0
	v_lshl_add_u64 v[170:171], v[2:3], 0, s[0:1]
	s_lshl_b32 s0, s94, 3
	s_movk_i32 s29, 0x1000
	v_lshl_add_u32 v185, v144, 6, v153
	v_lshl_add_u64 v[160:161], s[46:47], 0, v[158:159]
	v_lshl_add_u64 v[162:163], s[78:79], 0, v[158:159]
	v_cmp_eq_u32_e64 s[4:5], 0, v144
	s_lshl_b32 s33, s96, 3
	v_add_u16_e32 v221, s0, v215
	s_mov_b64 s[26:27], 0
	s_mov_b32 s42, 0x3fb8aa3b
	s_mov_b32 s43, 0xc2ce8ed0
	s_mov_b32 s46, 0x42b17218
	v_mov_b32_e32 v222, 0x3c0881c4
	v_mov_b32_e32 v223, 0xbab64f3b
	v_lshlrev_b32_e32 v224, 2, v4
	s_movk_i32 s47, 0x7fff
	s_movk_i32 s50, 0x4800
	v_lshlrev_b32_e32 v172, 1, v0
	s_mov_b32 s51, 0x7060302
	v_add_u32_e32 v225, v220, v6
	v_mov_b32_e32 v226, 0x3ecc95a3
	v_mov_b32_e32 v227, 0x3727c5ac
	v_mov_b32_e32 v228, 0xffffff00
	v_mov_b32_e32 v229, 0x7f800000
	v_not_b32_e32 v230, 63
	v_not_b32_e32 v231, 31
	v_mov_b32_e32 v232, 0x7fc00000
	v_add_u32_e32 v233, v5, v1
	v_mov_b32_e32 v174, 0x3f317218
	v_mov_b32_e32 v234, 0xff800000
	s_mov_b32 s28, 0x3d800000
	s_mov_b64 s[30:31], 0x8000
	v_readlane_b32 s70, v245, 20
	v_readlane_b32 s71, v245, 21
	v_readlane_b32 s72, v245, 22
	v_readlane_b32 s73, v245, 23
	v_readlane_b32 s74, v245, 24
	v_readlane_b32 s75, v245, 25
	v_readlane_b32 s76, v245, 26
	v_readlane_b32 s77, v245, 27
	v_readlane_b32 s80, v245, 30
	v_readlane_b32 s81, v245, 31
	v_readlane_b32 s82, v245, 32
	v_readlane_b32 s83, v245, 33
	v_readlane_b32 s53, v245, 3
	v_readlane_b32 s54, v245, 4
	v_readlane_b32 s55, v245, 5
	v_readlane_b32 s56, v245, 6
	v_readlane_b32 s57, v245, 7
	v_readlane_b32 s58, v245, 8
	v_readlane_b32 s59, v245, 9
	v_readlane_b32 s60, v245, 10
	v_readlane_b32 s61, v245, 11
	v_readlane_b32 s62, v245, 12
	v_readlane_b32 s63, v245, 13
	v_readlane_b32 s64, v245, 14
	v_readlane_b32 s65, v245, 15
	s_branch .LBB0_443

; __global__ void __launch_bounds__(512, 2) fwd(Params P) {
;     ...
;         for (int r2 = 0; r2 < NREP(13); ++r2) for (int id = blockIdx.x * 8 + wave; id < 4352; id += gridDim.x * 8) {
.LBB0_442:
	s_or_b64 exec, exec, s[0:1]
	v_cmp_gt_i32_e32 vcc, 0x800, v145
	s_nop 1
	v_cndmask_b32_e32 v241, v242, v240, vcc
	v_add_u32_e32 v145, v241, v145
	s_movk_i32 s0, 0x10ff
	v_cmp_lt_i32_e32 vcc, s0, v145
	s_or_b64 s[26:27], vcc, s[26:27]
	v_add_u16_e32 v221, v241, v221
	s_andn2_b64 exec, exec, s[26:27]
	s_cbranch_execz .LBB0_469

; __device__ __forceinline__ void s5_setup(const Params& P, int g, int p, float& ar, float& ai, float (&Br)[16], float (&Bi)[16]) {
;     const int gp = g * 64 + p;
;     const float lre = P.in[10][gp], lim = P.in[11][gp], dt = expf(P.in[12][gp]);
;     const float zr = lre * dt, zi = lim * dt; const float er = expf(zr); float sn, cs; sincosf(zi, &sn, &cs);
;     ar = er * cs; ai = er * sn;
;     const float nr = ar - 1.0f, ni = ai, den = 1.0f / (lre * lre + lim * lim);
;     const float cr = (nr * lre + ni * lim) * den, ci = (ni * lre - nr * lim) * den;
;     const f32x4* bre = (const f32x4*)(P.in[13] + (size_t)gp * 16); const f32x4* bim = (const f32x4*)(P.in[14] + (size_t)gp * 16);
; #pragma unroll
;     for (int c4 = 0; c4 < 4; ++c4) { const f32x4 x = bre[c4], y = bim[c4];
; #pragma unroll
;         for (int e = 0; e < 4; ++e) { Br[c4 * 4 + e] = cr * x[e] - ci * y[e]; Bi[c4 * 4 + e] = cr * y[e] + ci * x[e]; } }
; }
.LBB0_448:
	s_or_b64 exec, exec, s[0:1]
	v_readlane_b32 s52, v245, 2
	v_lshlrev_b32_e32 v12, 6, v34
	v_readlane_b32 s64, v245, 14
	v_readlane_b32 s65, v245, 15
	v_readlane_b32 s62, v245, 12
	v_readlane_b32 s63, v245, 13
	s_nop 2
	global_load_dwordx4 v[24:27], v12, s[64:65]
	s_nop 0
	global_load_dwordx4 v[28:31], v12, s[62:63]
	s_waitcnt vmcnt(2)
	v_mul_f32_e32 v37, v32, v1
	v_xor_b32_e32 v42, v0, v35
	v_pk_mul_f32 v[0:1], v[32:33], v[32:33]
	v_lshlrev_b32_e32 v40, 30, v2
	v_and_b32_e32 v41, 1, v2
	v_add_f32_e32 v46, v0, v1
	global_load_dwordx4 v[4:7], v12, s[62:63] offset:48
	global_load_dwordx4 v[0:3], v12, s[64:65] offset:48
	global_load_dwordx4 v[20:23], v12, s[62:63] offset:16
	global_load_dwordx4 v[16:19], v12, s[64:65] offset:16
	global_load_dwordx4 v[8:11], v12, s[62:63] offset:32
	s_nop 0
	global_load_dwordx4 v[12:15], v12, s[64:65] offset:32
	v_mul_f32_e32 v39, v36, v36
	v_mov_b32_e32 v38, v33
	v_mul_f32_e32 v33, 0x3fb8aa3b, v37
	v_fmamk_f32 v43, v39, 0xb94c1982, v222
	v_fmamk_f32 v44, v39, 0x37d75334, v223
	v_fma_f32 v47, v37, s42, -v33
	v_rndne_f32_e32 v48, v33
	v_fmaak_f32 v43, v39, v43, 0xbe2aaa9d
	v_fmaak_f32 v44, v39, v44, 0x3d2aabf7
	v_div_scale_f32 v49, s[0:1], v46, v46, 1.0
	v_fmac_f32_e32 v47, 0x32a5705f, v37
	v_sub_f32_e32 v33, v33, v48
	v_mul_f32_e32 v43, v39, v43
	v_fmaak_f32 v44, v39, v44, 0xbf000004
	v_rcp_f32_e32 v51, v49
	v_add_f32_e32 v33, v33, v47
	v_fmac_f32_e32 v36, v36, v43
	v_fma_f32 v39, v39, v44, 1.0
	v_cmp_eq_u32_e64 s[0:1], 0, v41
	v_cvt_i32_f32_e32 v48, v48
	v_exp_f32_e32 v33, v33
	v_cndmask_b32_e64 v41, v39, v36, s[0:1]
	v_xor_b32_e32 v36, 0x80000000, v36
	v_cndmask_b32_e64 v36, v36, v39, s[0:1]
	s_brev_b32 s0, 1
	v_and_b32_e32 v45, 0x80000000, v40
	v_xor_b32_e32 v41, v42, v41
	v_bitop3_b32 v36, v36, v40, s0 bitop3:0x78
	v_fma_f32 v40, -v49, v51, 1.0
	s_movk_i32 s0, 0x1f8
	v_div_scale_f32 v50, vcc, 1.0, v46, 1.0
	v_xor_b32_e32 v39, v41, v45
	v_cmp_class_f32_e64 s[0:1], v35, s0
	v_fmac_f32_e32 v51, v40, v51
	v_ldexp_f32 v33, v33, v48
	v_cndmask_b32_e64 v35, v232, v36, s[0:1]
	v_cndmask_b32_e64 v36, v232, v39, s[0:1]
	v_mul_f32_e32 v39, v50, v51
	v_cmp_ngt_f32_e64 s[0:1], s43, v37
	v_fma_f32 v40, -v49, v39, v50
	v_fmac_f32_e32 v39, v40, v51
	v_cndmask_b32_e64 v33, 0, v33, s[0:1]
	v_cmp_nlt_f32_e64 s[0:1], s46, v37
	v_lshlrev_b32_e32 v146, 3, v34
	v_bfe_u32 v67, v63, 6, 4
	v_cndmask_b32_e64 v42, v229, v33, s[0:1]
	v_mul_f32_e32 v60, v42, v36
	v_fma_f32 v61, v42, v35, -1.0
	v_fma_f32 v33, -v49, v39, v50
	v_div_fmas_f32 v33, v33, v51, v39
	v_pk_mul_f32 v[36:37], v[38:39], v[60:61] op_sel:[0,1] op_sel_hi:[0,0]
	v_div_fixup_f32 v38, v33, v46, 1.0
	v_pk_fma_f32 v[40:41], v[32:33], v[60:61], v[36:37] neg_lo:[0,0,1] neg_hi:[0,0,1]
	v_pk_fma_f32 v[32:33], v[32:33], v[60:61], v[36:37] op_sel_hi:[0,1,1]
	v_mov_b32_e32 v41, v33
	v_pk_mul_f32 v[32:33], v[38:39], v[40:41] op_sel_hi:[0,1]
	v_mul_f32_e32 v62, v42, v35
	v_readlane_b32 s53, v245, 3
	v_readlane_b32 s54, v245, 4
	v_readlane_b32 s55, v245, 5
	v_readlane_b32 s56, v245, 6
	v_readlane_b32 s57, v245, 7
	v_readlane_b32 s58, v245, 8
	v_readlane_b32 s59, v245, 9
	v_readlane_b32 s60, v245, 10
	v_readlane_b32 s61, v245, 11
	v_readlane_b32 s66, v245, 16
	v_readlane_b32 s67, v245, 17
	s_waitcnt vmcnt(7)
	v_mov_b32_e32 v36, v24
	s_waitcnt vmcnt(6)
	v_mov_b32_e32 v37, v28
	v_mov_b32_e32 v38, v28
	v_mov_b32_e32 v39, v24
	v_mov_b32_e32 v28, v25
	v_mov_b32_e32 v24, v29
	v_pk_mul_f32 v[28:29], v[28:29], v[32:33]
	v_pk_mul_f32 v[24:25], v[24:25], v[32:33]
	v_sub_f32_e32 v28, v29, v28
	v_add_f32_e32 v29, v25, v24
	v_mov_b32_e32 v24, v26
	v_mov_b32_e32 v25, v30
	v_pk_mul_f32 v[36:37], v[36:37], v[32:33]
	v_pk_mul_f32 v[38:39], v[38:39], v[32:33]
	v_pk_mul_f32 v[24:25], v[24:25], v[32:33]
	v_sub_f32_e32 v36, v37, v36
	v_add_f32_e32 v37, v39, v38
	v_sub_f32_e32 v38, v25, v24
	v_mov_b32_e32 v24, v30
	v_mov_b32_e32 v25, v26
	v_pk_mul_f32 v[24:25], v[24:25], v[32:33]
	v_mov_b32_e32 v30, v27
	v_add_f32_e32 v39, v25, v24
	v_pk_mul_f32 v[24:25], v[30:31], v[32:33]
	v_mov_b32_e32 v26, v31
	v_sub_f32_e32 v30, v25, v24
	v_pk_mul_f32 v[24:25], v[26:27], v[32:33]
	s_nop 0
	v_add_f32_e32 v26, v25, v24
	s_waitcnt vmcnt(2)
	v_mov_b32_e32 v24, v16
	v_mov_b32_e32 v25, v20
	v_pk_mul_f32 v[24:25], v[24:25], v[32:33]
	s_nop 0
	v_sub_f32_e32 v27, v25, v24
	v_mov_b32_e32 v24, v20
	v_mov_b32_e32 v25, v16
	v_pk_mul_f32 v[24:25], v[24:25], v[32:33]
	v_mov_b32_e32 v20, v17
	v_mov_b32_e32 v16, v21
	v_add_f32_e32 v31, v24, v25
	v_pk_mul_f32 v[24:25], v[20:21], v[32:33]
	v_pk_mul_f32 v[16:17], v[16:17], v[32:33]
	v_sub_f32_e32 v20, v25, v24
	v_add_f32_e32 v24, v16, v17
	v_mov_b32_e32 v16, v18
	v_mov_b32_e32 v17, v22
	v_pk_mul_f32 v[16:17], v[16:17], v[32:33]
	s_nop 0
	v_sub_f32_e32 v21, v17, v16
	v_mov_b32_e32 v16, v22
	v_mov_b32_e32 v17, v18
	v_pk_mul_f32 v[16:17], v[16:17], v[32:33]
	v_mov_b32_e32 v22, v19
	v_add_f32_e32 v25, v16, v17
	v_pk_mul_f32 v[16:17], v[22:23], v[32:33]
	v_mov_b32_e32 v18, v23
	v_sub_f32_e32 v22, v17, v16
	v_pk_mul_f32 v[16:17], v[18:19], v[32:33]
	s_nop 0
	v_add_f32_e32 v23, v16, v17
	s_waitcnt vmcnt(0)
; __device__ __forceinline__ unsigned cvt_pk_bf16(float lo, float hi) { unsigned r; asm volatile("v_cvt_pk_bf16_f32 %0, %1, %2" : "=v"(r) : "v"(lo), "v"(hi)); return r; }
; __device__ __forceinline__ float bflo(unsigned w) { return __uint_as_float(w << 16); }
; __device__ __forceinline__ float bfhi(unsigned w) { return __uint_as_float(w & 0xffff0000u); }
; template <int MODE>
; __device__ __forceinline__ void s5_unit(const Params& P, unsigned char* wl, const int id) {
;     ...
;     { s5_setup(P, g, lane, ar, ai, Br, Bi);
;       u32x4 w[4], v[4];
; #pragma unroll
;       for (int i = 0; i < 4; ++i) { unsigned hw[4], lw[4];
; #pragma unroll
;           for (int e = 0; e < 4; ++e) { const int c0 = (i & 1) * 8 + 2 * e; const float x0 = (i < 2) ? Br[c0] : Bi[c0], x1 = (i < 2) ? Br[c0 + 1] : Bi[c0 + 1];
;               const unsigned h = cvt_pk_bf16(x0, x1); hw[e] = h; lw[e] = cvt_pk_bf16(x0 - bflo(h), x1 - bfhi(h)); }
;           w[i] = (u32x4){hw[0], hw[1], hw[2], hw[3]}; v[i] = (u32x4){lw[0], lw[1], lw[2], lw[3]}; }
;       u32x4* bt = (u32x4*)(Btab + lane * 32); bt[0] = w[0]; bt[1] = w[1]; bt[2] = w[2]; bt[3] = w[3];
;       u32x4* lt = (u32x4*)((bf16_t*)buf + lane * 32); lt[0] = v[0]; lt[1] = v[1]; lt[2] = v[2]; lt[3] = v[3]; }
;     asm volatile("s_waitcnt lgkmcnt(0)" ::: "memory");
;     const bf16x8 zf = (bf16x8){0, 0, 0, 0, 0, 0, 0, 0};
;     bf16x8 bfr[8];
; #pragma unroll
;     for (int nn = 0; nn < 8; ++nn) bfr[nn] = *(const bf16x8*)((q < 2 ? Btab : (const bf16_t*)buf) + (16 * nn + l16) * 16 + 8 * (q & 1));
	v_mov_b32_e32 v16, v12
	v_mov_b32_e32 v17, v8
	v_pk_mul_f32 v[16:17], v[16:17], v[32:33]
	s_nop 0
	v_sub_f32_e32 v18, v17, v16
	v_mov_b32_e32 v16, v8
	v_mov_b32_e32 v17, v12
	v_pk_mul_f32 v[16:17], v[16:17], v[32:33]
	v_mov_b32_e32 v8, v13
	v_mov_b32_e32 v12, v9
	v_add_f32_e32 v40, v16, v17
	v_pk_mul_f32 v[16:17], v[8:9], v[32:33]
	v_pk_mul_f32 v[8:9], v[12:13], v[32:33]
	v_sub_f32_e32 v16, v17, v16
	v_add_f32_e32 v41, v8, v9
	v_mov_b32_e32 v8, v14
	v_mov_b32_e32 v9, v10
	v_pk_mul_f32 v[8:9], v[8:9], v[32:33]
	s_nop 0
	v_sub_f32_e32 v13, v9, v8
	v_mov_b32_e32 v8, v10
	v_mov_b32_e32 v9, v14
	v_pk_mul_f32 v[8:9], v[8:9], v[32:33]
	v_mov_b32_e32 v10, v15
	v_add_f32_e32 v43, v8, v9
	v_pk_mul_f32 v[8:9], v[10:11], v[32:33]
	v_mov_b32_e32 v14, v11
	v_sub_f32_e32 v10, v9, v8
	v_pk_mul_f32 v[8:9], v[14:15], v[32:33]
	s_nop 0
	v_add_f32_e32 v44, v8, v9
	v_mov_b32_e32 v8, v0
	v_mov_b32_e32 v9, v4
	v_pk_mul_f32 v[8:9], v[8:9], v[32:33]
	s_nop 0
	v_sub_f32_e32 v11, v9, v8
	v_mov_b32_e32 v9, v0
	v_mov_b32_e32 v0, v5
	v_mov_b32_e32 v8, v4
	v_mov_b32_e32 v4, v1
	v_pk_mul_f32 v[0:1], v[0:1], v[32:33]
	v_pk_mul_f32 v[8:9], v[8:9], v[32:33]
	v_add_f32_e32 v46, v0, v1
	v_mov_b32_e32 v0, v2
	v_mov_b32_e32 v1, v6
	v_pk_mul_f32 v[0:1], v[0:1], v[32:33]
	v_add_f32_e32 v45, v8, v9
	v_sub_f32_e32 v15, v1, v0
	v_mov_b32_e32 v0, v6
	v_mov_b32_e32 v1, v2
	v_pk_mul_f32 v[0:1], v[0:1], v[32:33]
	v_mov_b32_e32 v6, v3
	v_add_f32_e32 v47, v0, v1
	v_pk_mul_f32 v[0:1], v[6:7], v[32:33]
	v_mov_b32_e32 v2, v7
	v_sub_f32_e32 v17, v1, v0
	v_pk_mul_f32 v[0:1], v[2:3], v[32:33]
	v_pk_mul_f32 v[8:9], v[4:5], v[32:33]
	v_add_f32_e32 v32, v0, v1
	v_cvt_pk_bf16_f32 v0, v36, v28
	v_sub_f32_e32 v14, v9, v8
	v_lshlrev_b32_e32 v1, 16, v0
	v_and_b32_e32 v2, 0xffff0000, v0
	v_sub_f32_e32 v1, v36, v1
	v_sub_f32_e32 v2, v28, v2
	v_cvt_pk_bf16_f32 v4, v1, v2
	v_cvt_pk_bf16_f32 v1, v38, v30
	s_nop 0
	v_lshlrev_b32_e32 v2, 16, v1
	v_and_b32_e32 v3, 0xffff0000, v1
	v_sub_f32_e32 v2, v38, v2
	v_sub_f32_e32 v3, v30, v3
	v_cvt_pk_bf16_f32 v5, v2, v3
	v_cvt_pk_bf16_f32 v2, v27, v20
	s_nop 0
	v_lshlrev_b32_e32 v3, 16, v2
	v_and_b32_e32 v6, 0xffff0000, v2
	v_sub_f32_e32 v3, v27, v3
	v_sub_f32_e32 v6, v20, v6
	v_cvt_pk_bf16_f32 v6, v3, v6
	v_cvt_pk_bf16_f32 v3, v21, v22
	s_nop 0
	v_lshlrev_b32_e32 v7, 16, v3
	v_and_b32_e32 v8, 0xffff0000, v3
	v_sub_f32_e32 v7, v21, v7
	v_sub_f32_e32 v8, v22, v8
	v_cvt_pk_bf16_f32 v7, v7, v8
	v_cvt_pk_bf16_f32 v8, v18, v16
	s_nop 0
	v_lshlrev_b32_e32 v9, 16, v8
	v_and_b32_e32 v12, 0xffff0000, v8
	v_sub_f32_e32 v9, v18, v9
	v_sub_f32_e32 v12, v16, v12
	v_cvt_pk_bf16_f32 v12, v9, v12
	v_cvt_pk_bf16_f32 v9, v13, v10
	s_nop 0
	v_lshlrev_b32_e32 v16, 16, v9
	v_sub_f32_e32 v13, v13, v16
	v_and_b32_e32 v16, 0xffff0000, v9
	v_sub_f32_e32 v10, v10, v16
	v_cvt_pk_bf16_f32 v13, v13, v10
	v_cvt_pk_bf16_f32 v10, v11, v14
	s_nop 0
	v_lshlrev_b32_e32 v16, 16, v10
	v_sub_f32_e32 v11, v11, v16
	v_and_b32_e32 v16, 0xffff0000, v10
	v_sub_f32_e32 v14, v14, v16
	v_cvt_pk_bf16_f32 v14, v11, v14
	v_cvt_pk_bf16_f32 v11, v15, v17
	s_nop 0
	v_lshlrev_b32_e32 v16, 16, v11
	v_sub_f32_e32 v15, v15, v16
	v_and_b32_e32 v16, 0xffff0000, v11
	v_sub_f32_e32 v16, v17, v16
	v_cvt_pk_bf16_f32 v15, v15, v16
	v_cvt_pk_bf16_f32 v16, v37, v29
	s_nop 0
	v_lshlrev_b32_e32 v17, 16, v16
	v_and_b32_e32 v18, 0xffff0000, v16
	v_sub_f32_e32 v17, v37, v17
	v_sub_f32_e32 v18, v29, v18
	v_cvt_pk_bf16_f32 v20, v17, v18
	v_cvt_pk_bf16_f32 v17, v39, v26
	s_nop 0
	v_lshlrev_b32_e32 v18, 16, v17
	v_and_b32_e32 v19, 0xffff0000, v17
	v_sub_f32_e32 v18, v39, v18
	v_sub_f32_e32 v19, v26, v19
	v_cvt_pk_bf16_f32 v21, v18, v19
	v_cvt_pk_bf16_f32 v18, v31, v24
	s_nop 0
	v_lshlrev_b32_e32 v19, 16, v18
	v_and_b32_e32 v22, 0xffff0000, v18
	v_sub_f32_e32 v19, v31, v19
	v_sub_f32_e32 v22, v24, v22
	v_cvt_pk_bf16_f32 v22, v19, v22
	v_cvt_pk_bf16_f32 v19, v25, v23
	s_nop 0
	v_lshlrev_b32_e32 v24, 16, v19
	v_sub_f32_e32 v24, v25, v24
	v_and_b32_e32 v25, 0xffff0000, v19
	v_sub_f32_e32 v23, v23, v25
	v_cvt_pk_bf16_f32 v23, v24, v23
	v_cvt_pk_bf16_f32 v24, v40, v41
	s_nop 0
	v_lshlrev_b32_e32 v25, 16, v24
	v_and_b32_e32 v26, 0xffff0000, v24
	v_sub_f32_e32 v25, v40, v25
	v_sub_f32_e32 v26, v41, v26
	v_cvt_pk_bf16_f32 v28, v25, v26
	v_cvt_pk_bf16_f32 v25, v43, v44
	s_nop 0
	v_lshlrev_b32_e32 v26, 16, v25
	v_and_b32_e32 v27, 0xffff0000, v25
	v_sub_f32_e32 v26, v43, v26
	v_sub_f32_e32 v27, v44, v27
	v_cvt_pk_bf16_f32 v29, v26, v27
	v_cvt_pk_bf16_f32 v26, v45, v46
	s_nop 0
	v_lshlrev_b32_e32 v27, 16, v26
	v_and_b32_e32 v30, 0xffff0000, v26
	v_sub_f32_e32 v27, v45, v27
	v_sub_f32_e32 v30, v46, v30
	v_cvt_pk_bf16_f32 v30, v27, v30
	v_cvt_pk_bf16_f32 v27, v47, v32
	s_nop 0
	v_lshlrev_b32_e32 v31, 16, v27
	v_and_b32_e32 v33, 0xffff0000, v27
	v_sub_f32_e32 v31, v47, v31
	v_sub_f32_e32 v32, v32, v33
	v_cvt_pk_bf16_f32 v31, v31, v32
	ds_write_b128 v185, v[0:3]
	ds_write_b128 v185, v[8:11] offset:16
	ds_write_b128 v185, v[16:19] offset:32
	ds_write_b128 v185, v[24:27] offset:48
	ds_write_b128 v185, v[4:7] offset:4096
	ds_write_b128 v185, v[12:15] offset:4112
	ds_write_b128 v185, v[20:23] offset:4128
	ds_write_b128 v185, v[28:31] offset:4144
	v_lshl_add_u64 v[32:33], s[20:21], 0, v[146:147]
	s_waitcnt lgkmcnt(0)
	v_add_co_u32_e32 v32, vcc, 0x200000, v32
	ds_read_b128 v[0:3], v216
	ds_read_b128 v[4:7], v216 offset:512
	ds_read_b128 v[8:11], v216 offset:1024
	ds_read_b128 v[12:15], v216 offset:1536
	ds_read_b128 v[16:19], v216 offset:2048
	ds_read_b128 v[20:23], v216 offset:2560
	ds_read_b128 v[24:27], v216 offset:3072
	ds_read_b128 v[28:31], v216 offset:3584
	s_waitcnt lgkmcnt(0)
; template <int MODE>
; __device__ __forceinline__ void s5_unit(const Params& P, unsigned char* wl, const int id) {
;     ...
;     if (MODE == 1) { float pr = ar, pi = ai;
; #pragma unroll
;         for (int i = 0; i < 7; ++i) { const float t = pr * pr - pi * pi; pi = 2.0f * pr * pi; pr = t; }
;         const f32x2* E = (const f32x2*)(P.ws + O_ESSM);
;         { const f32x2 e = E[(size_t)(64 * 64 + g) * 64 + lane]; hr = e.x; hi = e.y; }
;         for (int i = 0; i < c; ++i) { const f32x2 e = E[(size_t)((b * 16 + i) * 64 + g) * 64 + lane]; const float nr_ = pr * hr - pi * hi + e.x, ni_ = pr * hi + pi * hr + e.y; hr = nr_; hi = ni_; } }
	v_addc_co_u32_e32 v33, vcc, 0, v33, vcc
	global_load_dwordx2 v[64:65], v[32:33], off
	v_mul_f32_e32 v33, v60, v60
	v_add_f32_e32 v32, v62, v62
	v_fma_f32 v33, v62, v62, -v33
	v_mul_f32_e32 v32, v60, v32
	v_add_f32_e32 v34, v33, v33
	v_mul_f32_e32 v34, v32, v34
	v_mul_f32_e32 v32, v32, v32
	v_fma_f32 v32, v33, v33, -v32
	v_add_f32_e32 v33, v32, v32
	v_mul_f32_e32 v33, v34, v33
	v_mul_f32_e32 v34, v34, v34
	v_fma_f32 v32, v32, v32, -v34
	v_add_f32_e32 v34, v32, v32
	v_mul_f32_e32 v34, v33, v34
	v_mul_f32_e32 v33, v33, v33
	v_fma_f32 v32, v32, v32, -v33
	v_add_f32_e32 v33, v32, v32
	v_mul_f32_e32 v33, v34, v33
	v_mul_f32_e32 v34, v34, v34
	v_fma_f32 v32, v32, v32, -v34
	v_add_f32_e32 v34, v32, v32
	v_mul_f32_e32 v34, v33, v34
	v_mul_f32_e32 v33, v33, v33
	v_fma_f32 v33, v32, v32, -v33
	v_add_f32_e32 v32, v33, v33
	v_mul_f32_e32 v32, v34, v32
	v_mul_f32_e32 v34, v34, v34
	v_fma_f32 v34, v33, v33, -v34
	v_bfe_u32 v72, v63, 6, 4
	v_and_b32_e32 v36, 0xfffffc3f, v63
	v_mov_b32_e32 v35, v34
	v_mov_b32_e32 v33, v32
	v_ashrrev_i32_e32 v37, 31, v36
	v_lshlrev_b64 v[40:41], 9, v[36:37]
	v_lshl_add_u64 v[40:41], v[150:151], 0, v[40:41]
	v_readfirstlane_b32 s8, v72
	global_load_dwordx2 v[74:75], v[40:41], off
	v_add_co_u32_e32 v40, vcc, 0x8000, v40
	s_nop 1
	v_addc_co_u32_e32 v41, vcc, 0, v41, vcc
	global_load_dwordx2 v[76:77], v[40:41], off
	v_add_co_u32_e32 v40, vcc, 0x8000, v40
	s_nop 1
	v_addc_co_u32_e32 v41, vcc, 0, v41, vcc
	global_load_dwordx2 v[78:79], v[40:41], off
	v_add_co_u32_e32 v40, vcc, 0x8000, v40
	s_nop 1
	v_addc_co_u32_e32 v41, vcc, 0, v41, vcc
	global_load_dwordx2 v[80:81], v[40:41], off
	v_add_co_u32_e32 v40, vcc, 0x8000, v40
	s_nop 1
	v_addc_co_u32_e32 v41, vcc, 0, v41, vcc
	global_load_dwordx2 v[82:83], v[40:41], off
	v_add_co_u32_e32 v40, vcc, 0x8000, v40
	s_nop 1
	v_addc_co_u32_e32 v41, vcc, 0, v41, vcc
	global_load_dwordx2 v[84:85], v[40:41], off
	v_add_co_u32_e32 v40, vcc, 0x8000, v40
	s_nop 1
	v_addc_co_u32_e32 v41, vcc, 0, v41, vcc
	global_load_dwordx2 v[86:87], v[40:41], off
	v_add_co_u32_e32 v40, vcc, 0x8000, v40
	s_nop 1
	v_addc_co_u32_e32 v41, vcc, 0, v41, vcc
	global_load_dwordx2 v[88:89], v[40:41], off
	v_add_co_u32_e32 v40, vcc, 0x8000, v40
	s_nop 1
	v_addc_co_u32_e32 v41, vcc, 0, v41, vcc
	global_load_dwordx2 v[90:91], v[40:41], off
	v_add_co_u32_e32 v40, vcc, 0x8000, v40
	s_nop 1
	v_addc_co_u32_e32 v41, vcc, 0, v41, vcc
	global_load_dwordx2 v[92:93], v[40:41], off
	v_add_co_u32_e32 v40, vcc, 0x8000, v40
	s_nop 1
	v_addc_co_u32_e32 v41, vcc, 0, v41, vcc
	global_load_dwordx2 v[94:95], v[40:41], off
	v_add_co_u32_e32 v40, vcc, 0x8000, v40
	s_nop 1
	v_addc_co_u32_e32 v41, vcc, 0, v41, vcc
	global_load_dwordx2 v[96:97], v[40:41], off
	v_add_co_u32_e32 v40, vcc, 0x8000, v40
	s_nop 1
	v_addc_co_u32_e32 v41, vcc, 0, v41, vcc
	global_load_dwordx2 v[98:99], v[40:41], off
	v_add_co_u32_e32 v40, vcc, 0x8000, v40
	s_nop 1
	v_addc_co_u32_e32 v41, vcc, 0, v41, vcc
	global_load_dwordx2 v[100:101], v[40:41], off
	v_add_co_u32_e32 v40, vcc, 0x8000, v40
	s_nop 1
	v_addc_co_u32_e32 v41, vcc, 0, v41, vcc
	global_load_dwordx2 v[102:103], v[40:41], off
	s_waitcnt vmcnt(0)
	s_cmp_le_u32 s8, 0
	s_cbranch_scc1 .Lch3_done
	v_pk_mul_f32 v[42:43], v[32:33], v[64:65] op_sel:[0,1] op_sel_hi:[1,0]
	v_pk_fma_f32 v[44:45], v[34:35], v[64:65], v[42:43] neg_lo:[0,0,1] neg_hi:[0,0,1]
	v_pk_fma_f32 v[42:43], v[34:35], v[64:65], v[42:43]
	v_mov_b32_e32 v45, v43
	v_pk_add_f32 v[64:65], v[44:45], v[74:75]
	s_cmp_le_u32 s8, 1
	s_cbranch_scc1 .Lch3_done
	v_pk_mul_f32 v[42:43], v[32:33], v[64:65] op_sel:[0,1] op_sel_hi:[1,0]
	v_pk_fma_f32 v[44:45], v[34:35], v[64:65], v[42:43] neg_lo:[0,0,1] neg_hi:[0,0,1]
	v_pk_fma_f32 v[42:43], v[34:35], v[64:65], v[42:43]
	v_mov_b32_e32 v45, v43
	v_pk_add_f32 v[64:65], v[44:45], v[76:77]
	s_cmp_le_u32 s8, 2
	s_cbranch_scc1 .Lch3_done
	v_pk_mul_f32 v[42:43], v[32:33], v[64:65] op_sel:[0,1] op_sel_hi:[1,0]
	v_pk_fma_f32 v[44:45], v[34:35], v[64:65], v[42:43] neg_lo:[0,0,1] neg_hi:[0,0,1]
	v_pk_fma_f32 v[42:43], v[34:35], v[64:65], v[42:43]
	v_mov_b32_e32 v45, v43
	v_pk_add_f32 v[64:65], v[44:45], v[78:79]
	s_cmp_le_u32 s8, 3
	s_cbranch_scc1 .Lch3_done
	v_pk_mul_f32 v[42:43], v[32:33], v[64:65] op_sel:[0,1] op_sel_hi:[1,0]
	v_pk_fma_f32 v[44:45], v[34:35], v[64:65], v[42:43] neg_lo:[0,0,1] neg_hi:[0,0,1]
	v_pk_fma_f32 v[42:43], v[34:35], v[64:65], v[42:43]
	v_mov_b32_e32 v45, v43
	v_pk_add_f32 v[64:65], v[44:45], v[80:81]
	s_cmp_le_u32 s8, 4
	s_cbranch_scc1 .Lch3_done
	v_pk_mul_f32 v[42:43], v[32:33], v[64:65] op_sel:[0,1] op_sel_hi:[1,0]
	v_pk_fma_f32 v[44:45], v[34:35], v[64:65], v[42:43] neg_lo:[0,0,1] neg_hi:[0,0,1]
	v_pk_fma_f32 v[42:43], v[34:35], v[64:65], v[42:43]
	v_mov_b32_e32 v45, v43
	v_pk_add_f32 v[64:65], v[44:45], v[82:83]
	s_cmp_le_u32 s8, 5
	s_cbranch_scc1 .Lch3_done
	v_pk_mul_f32 v[42:43], v[32:33], v[64:65] op_sel:[0,1] op_sel_hi:[1,0]
	v_pk_fma_f32 v[44:45], v[34:35], v[64:65], v[42:43] neg_lo:[0,0,1] neg_hi:[0,0,1]
	v_pk_fma_f32 v[42:43], v[34:35], v[64:65], v[42:43]
	v_mov_b32_e32 v45, v43
	v_pk_add_f32 v[64:65], v[44:45], v[84:85]
	s_cmp_le_u32 s8, 6
	s_cbranch_scc1 .Lch3_done
	v_pk_mul_f32 v[42:43], v[32:33], v[64:65] op_sel:[0,1] op_sel_hi:[1,0]
	v_pk_fma_f32 v[44:45], v[34:35], v[64:65], v[42:43] neg_lo:[0,0,1] neg_hi:[0,0,1]
	v_pk_fma_f32 v[42:43], v[34:35], v[64:65], v[42:43]
	v_mov_b32_e32 v45, v43
	v_pk_add_f32 v[64:65], v[44:45], v[86:87]
	s_cmp_le_u32 s8, 7
	s_cbranch_scc1 .Lch3_done
	v_pk_mul_f32 v[42:43], v[32:33], v[64:65] op_sel:[0,1] op_sel_hi:[1,0]
	v_pk_fma_f32 v[44:45], v[34:35], v[64:65], v[42:43] neg_lo:[0,0,1] neg_hi:[0,0,1]
	v_pk_fma_f32 v[42:43], v[34:35], v[64:65], v[42:43]
	v_mov_b32_e32 v45, v43
	v_pk_add_f32 v[64:65], v[44:45], v[88:89]
	s_cmp_le_u32 s8, 8
	s_cbranch_scc1 .Lch3_done
; __device__ __forceinline__ bf16_t f2bf(float f) { unsigned u = __float_as_uint(f); u += 0x7FFFu + ((u >> 16) & 1u); return (bf16_t)(u >> 16); }
; template <int MODE>
; __device__ __forceinline__ void s5_unit(const Params& P, unsigned char* wl, const int id) {
;     ...
;         const f32x2* E = (const f32x2*)(P.ws + O_ESSM);
;         { const f32x2 e = E[(size_t)(64 * 64 + g) * 64 + lane]; hr = e.x; hi = e.y; }
;         for (int i = 0; i < c; ++i) { const f32x2 e = E[(size_t)((b * 16 + i) * 64 + g) * 64 + lane]; const float nr_ = pr * hr - pi * hi + e.x, ni_ = pr * hi + pi * hr + e.y; hr = nr_; hi = ni_; } }
;     bf16x8 cf[4]; float dsk = 0.f;
;     if (MODE >= 1) {
; #pragma unroll
;         for (int ks = 0; ks < 4; ++ks) { const int p0 = 16 * ks + 4 * q; const f32x4 cr = *(const f32x4*)(P.in[15] + (size_t)(g * 16 + l16) * 64 + p0), ci = *(const f32x4*)(P.in[16] + (size_t)(g * 16 + l16) * 64 + p0);
;             bf16x8 f; f[0] = (short)f2bf(cr[0]); f[1] = (short)f2bf(-ci[0]); f[2] = (short)f2bf(cr[1]); f[3] = (short)f2bf(-ci[1]); f[4] = (short)f2bf(cr[2]); f[5] = (short)f2bf(-ci[2]); f[6] = (short)f2bf(cr[3]); f[7] = (short)f2bf(-ci[3]); cf[ks] = f; }
;         dsk = P.in[17][g * 16 + l16]; }
;     const bf16_t* arow = PROJ + (size_t)(row0 + l16) * NPROJ + C_U + g * 16 + 8 * (q & 1);
;     bf16x8 a_cur = *(const bf16x8*)arow;
	v_pk_mul_f32 v[42:43], v[32:33], v[64:65] op_sel:[0,1] op_sel_hi:[1,0]
	v_pk_fma_f32 v[44:45], v[34:35], v[64:65], v[42:43] neg_lo:[0,0,1] neg_hi:[0,0,1]
	v_pk_fma_f32 v[42:43], v[34:35], v[64:65], v[42:43]
	v_mov_b32_e32 v45, v43
	v_pk_add_f32 v[64:65], v[44:45], v[90:91]
	s_cmp_le_u32 s8, 9
	s_cbranch_scc1 .Lch3_done
	v_pk_mul_f32 v[42:43], v[32:33], v[64:65] op_sel:[0,1] op_sel_hi:[1,0]
	v_pk_fma_f32 v[44:45], v[34:35], v[64:65], v[42:43] neg_lo:[0,0,1] neg_hi:[0,0,1]
	v_pk_fma_f32 v[42:43], v[34:35], v[64:65], v[42:43]
	v_mov_b32_e32 v45, v43
	v_pk_add_f32 v[64:65], v[44:45], v[92:93]
	s_cmp_le_u32 s8, 10
	s_cbranch_scc1 .Lch3_done
	v_pk_mul_f32 v[42:43], v[32:33], v[64:65] op_sel:[0,1] op_sel_hi:[1,0]
	v_pk_fma_f32 v[44:45], v[34:35], v[64:65], v[42:43] neg_lo:[0,0,1] neg_hi:[0,0,1]
	v_pk_fma_f32 v[42:43], v[34:35], v[64:65], v[42:43]
	v_mov_b32_e32 v45, v43
	v_pk_add_f32 v[64:65], v[44:45], v[94:95]
	s_cmp_le_u32 s8, 11
	s_cbranch_scc1 .Lch3_done
	v_pk_mul_f32 v[42:43], v[32:33], v[64:65] op_sel:[0,1] op_sel_hi:[1,0]
	v_pk_fma_f32 v[44:45], v[34:35], v[64:65], v[42:43] neg_lo:[0,0,1] neg_hi:[0,0,1]
	v_pk_fma_f32 v[42:43], v[34:35], v[64:65], v[42:43]
	v_mov_b32_e32 v45, v43
	v_pk_add_f32 v[64:65], v[44:45], v[96:97]
	s_cmp_le_u32 s8, 12
	s_cbranch_scc1 .Lch3_done
	v_pk_mul_f32 v[42:43], v[32:33], v[64:65] op_sel:[0,1] op_sel_hi:[1,0]
	v_pk_fma_f32 v[44:45], v[34:35], v[64:65], v[42:43] neg_lo:[0,0,1] neg_hi:[0,0,1]
	v_pk_fma_f32 v[42:43], v[34:35], v[64:65], v[42:43]
	v_mov_b32_e32 v45, v43
	v_pk_add_f32 v[64:65], v[44:45], v[98:99]
	s_cmp_le_u32 s8, 13
	s_cbranch_scc1 .Lch3_done
	v_pk_mul_f32 v[42:43], v[32:33], v[64:65] op_sel:[0,1] op_sel_hi:[1,0]
	v_pk_fma_f32 v[44:45], v[34:35], v[64:65], v[42:43] neg_lo:[0,0,1] neg_hi:[0,0,1]
	v_pk_fma_f32 v[42:43], v[34:35], v[64:65], v[42:43]
	v_mov_b32_e32 v45, v43
	v_pk_add_f32 v[64:65], v[44:45], v[100:101]
	s_cmp_le_u32 s8, 14
	s_cbranch_scc1 .Lch3_done
	v_pk_mul_f32 v[42:43], v[32:33], v[64:65] op_sel:[0,1] op_sel_hi:[1,0]
	v_pk_fma_f32 v[44:45], v[34:35], v[64:65], v[42:43] neg_lo:[0,0,1] neg_hi:[0,0,1]
	v_pk_fma_f32 v[42:43], v[34:35], v[64:65], v[42:43]
	v_mov_b32_e32 v45, v43
	v_pk_add_f32 v[64:65], v[44:45], v[102:103]
.Lch3_done:
	v_lshl_or_b32 v146, v66, 12, v224
	v_lshl_add_u64 v[52:53], v[168:169], 0, v[146:147]
	global_load_dwordx4 v[36:39], v[52:53], off
	v_lshl_add_u64 v[54:55], v[166:167], 0, v[146:147]
	v_ashrrev_i32_e32 v68, 10, v63
	global_load_dwordx4 v[32:35], v[54:55], off
	global_load_dwordx4 v[44:47], v[52:53], off offset:64
	global_load_dwordx4 v[40:43], v[54:55], off offset:64
	global_load_dwordx4 v[56:59], v[52:53], off offset:128
	global_load_dwordx4 v[48:51], v[54:55], off offset:128
	global_load_dwordx4 v[74:77], v[52:53], off offset:192
	global_load_dwordx4 v[78:81], v[54:55], off offset:192
	v_lshlrev_b32_e32 v73, 11, v68
	v_readlane_b32 s52, v245, 18
	v_lshl_or_b32 v54, v66, 6, v149
	v_readlane_b32 s54, v245, 20
	v_readlane_b32 s55, v245, 21
	v_lshl_or_b32 v71, v67, 7, v73
	v_mov_b64_e32 v[52:53], s[18:19]
	v_lshlrev_b32_e32 v146, 5, v66
	v_mov_b32_e32 v173, v147
	s_mov_b32 s8, 0
	global_load_dword v70, v54, s[54:55]
	v_or_b32_e32 v54, v71, v157
	v_mad_i64_i32 v[52:53], s[0:1], v54, s50, v[52:53]
	v_lshl_add_u64 v[52:53], v[52:53], 0, v[146:147]
	v_lshl_add_u64 v[52:53], v[52:53], 0, v[172:173]
	global_load_dwordx4 v[52:55], v[52:53], off
	v_readlane_b32 s53, v245, 19
	v_readlane_b32 s56, v245, 22
	v_readlane_b32 s57, v245, 23
	v_readlane_b32 s58, v245, 24
	v_readlane_b32 s59, v245, 25
	v_readlane_b32 s60, v245, 26
	v_readlane_b32 s61, v245, 27
	v_readlane_b32 s62, v245, 28
	v_readlane_b32 s63, v245, 29
	v_readlane_b32 s64, v245, 30
	v_readlane_b32 s65, v245, 31
	v_readlane_b32 s66, v245, 32
	v_readlane_b32 s67, v245, 33
	s_waitcnt vmcnt(8)
	v_bfe_u32 v61, v35, 16, 1
	v_bfe_u32 v63, v34, 16, 1
	v_bfe_u32 v82, v33, 16, 1
	v_xor_b32_e32 v36, 0x80000000, v36
	v_xor_b32_e32 v37, 0x80000000, v37
	v_bfe_u32 v83, v32, 16, 1
	s_waitcnt vmcnt(7)
	v_xor_b32_e32 v44, 0x80000000, v44
	v_xor_b32_e32 v45, 0x80000000, v45
	v_xor_b32_e32 v46, 0x80000000, v46
	v_xor_b32_e32 v47, 0x80000000, v47
	s_waitcnt vmcnt(6)
	v_bfe_u32 v86, v41, 16, 1
	v_bfe_u32 v87, v40, 16, 1
	s_waitcnt vmcnt(5)
	v_xor_b32_e32 v56, 0x80000000, v56
	v_xor_b32_e32 v57, 0x80000000, v57
	s_waitcnt vmcnt(4)
	v_bfe_u32 v90, v49, 16, 1
	v_bfe_u32 v91, v48, 16, 1
	v_bfe_u32 v94, v37, 16, 1
	v_bfe_u32 v95, v36, 16, 1
	v_add3_u32 v32, v32, v83, s47
	v_add3_u32 v33, v33, v82, s47
	v_add3_u32 v34, v34, v63, s47
	v_add3_u32 v35, v35, v61, s47
	v_bfe_u32 v61, v47, 16, 1
	v_bfe_u32 v63, v46, 16, 1
	v_bfe_u32 v82, v45, 16, 1
	v_bfe_u32 v83, v44, 16, 1
	v_add3_u32 v40, v40, v87, s47
	v_add3_u32 v41, v41, v86, s47
	v_bfe_u32 v86, v57, 16, 1
	v_bfe_u32 v87, v56, 16, 1
	v_xor_b32_e32 v38, 0x80000000, v38
	v_bfe_u32 v85, v42, 16, 1
	v_xor_b32_e32 v58, 0x80000000, v58
	v_add3_u32 v48, v48, v91, s47
	v_add3_u32 v49, v49, v90, s47
	v_add3_u32 v36, v36, v95, s47
	v_add3_u32 v37, v37, v94, s47
	v_add3_u32 v44, v44, v83, s47
	v_add3_u32 v45, v45, v82, s47
	v_add3_u32 v46, v46, v63, s47
	v_add3_u32 v47, v47, v61, s47
	v_add3_u32 v61, v56, v87, s47
	v_add3_u32 v63, v57, v86, s47
	v_bfe_u32 v89, v50, 16, 1
	v_bfe_u32 v93, v38, 16, 1
	v_add3_u32 v42, v42, v85, s47
	v_bfe_u32 v85, v58, 16, 1
	v_perm_b32 v33, v37, v33, s51
	v_perm_b32 v32, v36, v32, s51
	v_perm_b32 v37, v45, v41, s51
	v_perm_b32 v36, v44, v40, s51
	v_perm_b32 v41, v63, v49, s51
	v_perm_b32 v40, v61, v48, s51
	v_or_b32_e32 v48, v152, v73
	v_lshlrev_b32_e32 v49, 7, v72
	v_bfe_u32 v84, v43, 16, 1
	v_xor_b32_e32 v59, 0x80000000, v59
	v_add3_u32 v50, v50, v89, s47
	v_add3_u32 v38, v38, v93, s47
	v_add3_u32 v58, v58, v85, s47
	v_add_u32_e32 v72, v48, v49
	v_or_b32_e32 v48, v157, v73
	v_xor_b32_e32 v39, 0x80000000, v39
	v_add3_u32 v43, v43, v84, s47
	v_bfe_u32 v84, v59, 16, 1
	s_waitcnt vmcnt(3)
; __device__ __forceinline__ unsigned cvt_pk_bf16(float lo, float hi) { unsigned r; asm volatile("v_cvt_pk_bf16_f32 %0, %1, %2" : "=v"(r) : "v"(lo), "v"(hi)); return r; }
; __device__ __forceinline__ f32x4 mfma16(bf16x8 a, bf16x8 b, f32x4 c) { return __builtin_amdgcn_mfma_f32_16x16x32_bf16(a, b, c, 0, 0, 0); }
; template <int MODE>
; __device__ __forceinline__ void s5_unit(const Params& P, unsigned char* wl, const int id) {
;     ...
;     for (int blk = 0; blk < nblk; ++blk) {
;         bf16x8 a_nxt = zf; if (blk + 1 < nblk) a_nxt = *(const bf16x8*)(arow + (size_t)(blk + 1) * 16 * NPROJ);
;         { float* bp = buf + (4 * q) * 130 + l16; f32x4 d[8];
; #pragma unroll
;           for (int nn = 0; nn < 8; ++nn) d[nn] = mfma16(a_cur, bfr[nn], (f32x4){0.f, 0.f, 0.f, 0.f});
;           __builtin_amdgcn_sched_barrier(0); asm volatile("s_nop 15\n\ts_nop 15" ::: "memory"); __builtin_amdgcn_sched_barrier(0);
; #pragma unroll
;           for (int nn = 0; nn < 8; ++nn) { bp[16 * nn] = d[nn][0]; bp[130 + 16 * nn] = d[nn][1]; bp[260 + 16 * nn] = d[nn][2]; bp[390 + 16 * nn] = d[nn][3]; } }
;         if (MODE >= 1 && q < 2) *(bf16x8*)(Ub + l16 * 16 + 8 * q) = a_cur;
;     ...
;             f32x2 bb[16];
; #pragma unroll
;             for (int t = 0; t < 16; ++t) bb[t] = *(const f32x2*)(buf + t * 130 + 2 * lane);
; #pragma unroll
;             for (int t = 0; t < 16; ++t) { const float nr_ = ar * hr - ai * hi + bb[t].x, ni_ = ar * hi + ai * hr + bb[t].y; hr = nr_; hi = ni_;
;                 if (MODE == 1) Hw[t * 68 + lane] = cvt_pk_bf16(hr, hi); }
	v_xor_b32_e32 v56, 0x80000000, v74
	v_xor_b32_e32 v57, 0x80000000, v75
	v_xor_b32_e32 v74, 0x80000000, v76
	v_xor_b32_e32 v75, 0x80000000, v77
	v_perm_b32 v34, v38, v34, s51
	v_perm_b32 v38, v46, v42, s51
	v_perm_b32 v42, v58, v50, s51
	v_add_u32_e32 v48, v48, v49
	v_add_u16_e32 v50, v221, v69
	v_bfe_u32 v88, v51, 16, 1
	v_bfe_u32 v92, v39, 16, 1
	v_add3_u32 v59, v59, v84, s47
	v_bfe_u32 v76, v75, 16, 1
	s_waitcnt vmcnt(2)
	v_bfe_u32 v77, v81, 16, 1
	v_bfe_u32 v82, v74, 16, 1
	v_bfe_u32 v83, v80, 16, 1
	v_bfe_u32 v84, v57, 16, 1
	v_bfe_u32 v85, v79, 16, 1
	v_bfe_u32 v86, v56, 16, 1
	v_bfe_u32 v87, v78, 16, 1
	v_mad_i64_i32 v[48:49], s[0:1], v48, s50, 0
	v_and_b32_e32 v50, 63, v50
	v_add3_u32 v51, v51, v88, s47
	v_add3_u32 v39, v39, v92, s47
	v_add3_u32 v78, v78, v87, s47
	v_add3_u32 v86, v56, v86, s47
	v_add3_u32 v79, v79, v85, s47
	v_add3_u32 v84, v57, v84, s47
	v_add3_u32 v80, v80, v83, s47
	v_add3_u32 v74, v74, v82, s47
	v_add3_u32 v77, v81, v77, s47
	v_add3_u32 v75, v75, v76, s47
	v_lshl_or_b32 v48, v50, 5, v48
	v_lshl_add_u64 v[56:57], v[154:155], 0, v[146:147]
	v_perm_b32 v35, v39, v35, s51
	v_perm_b32 v39, v47, v43, s51
	v_perm_b32 v43, v59, v51, s51
	v_perm_b32 v47, v75, v77, s51
	v_perm_b32 v46, v74, v80, s51
	v_perm_b32 v45, v84, v79, s51
	v_perm_b32 v44, v86, v78, s51
	v_mov_b32_e32 v63, v62
	v_mov_b32_e32 v61, v60
	v_lshl_add_u64 v[58:59], v[170:171], 0, v[48:49]
	s_waitcnt vmcnt(0)
.LBB0_455:
	global_load_dwordx4 v[48:51], v[58:59], off
	s_waitcnt lgkmcnt(7)
	v_mfma_f32_16x16x32_bf16 v[74:77], v[52:55], v[0:3], 0
	s_waitcnt lgkmcnt(6)
	v_mfma_f32_16x16x32_bf16 v[78:81], v[52:55], v[4:7], 0
	s_waitcnt lgkmcnt(5)
	v_mfma_f32_16x16x32_bf16 v[82:85], v[52:55], v[8:11], 0
	s_waitcnt lgkmcnt(4)
	v_mfma_f32_16x16x32_bf16 v[86:89], v[52:55], v[12:15], 0
	s_waitcnt lgkmcnt(3)
	v_mfma_f32_16x16x32_bf16 v[90:93], v[52:55], v[16:19], 0
	s_waitcnt lgkmcnt(2)
	v_mfma_f32_16x16x32_bf16 v[94:97], v[52:55], v[20:23], 0
	s_waitcnt lgkmcnt(1)
	v_mfma_f32_16x16x32_bf16 v[98:101], v[52:55], v[24:27], 0
	s_waitcnt lgkmcnt(0)
	v_mfma_f32_16x16x32_bf16 v[102:105], v[52:55], v[28:31], 0
	s_nop 15
	s_nop 15
	v_add_u32_e32 v69, 0x1000, v217
	v_add_u32_e32 v73, 0x1400, v217
	ds_write2_b32 v69, v74, v78 offset1:16
	ds_write2_b32 v69, v75, v79 offset0:130 offset1:146
	ds_write2_b32 v73, v76, v80 offset0:4 offset1:20
	ds_write2_b32 v73, v77, v81 offset0:134 offset1:150
	ds_write2_b32 v69, v82, v86 offset0:32 offset1:48
	ds_write2_b32 v69, v83, v87 offset0:162 offset1:178
	ds_write2_b32 v73, v84, v88 offset0:36 offset1:52
	ds_write2_b32 v73, v85, v89 offset0:166 offset1:182
	ds_write2_b32 v69, v90, v94 offset0:64 offset1:80
	ds_write2_b32 v69, v91, v95 offset0:194 offset1:210
	ds_write2_b32 v73, v92, v96 offset0:68 offset1:84
	ds_write2_b32 v73, v93, v97 offset0:198 offset1:214
	ds_write2_b32 v69, v98, v102 offset0:96 offset1:112
	ds_write2_b32 v69, v99, v103 offset0:226 offset1:242
	ds_write2_b32 v73, v100, v104 offset0:100 offset1:116
	ds_write2_b32 v73, v101, v105 offset0:230 offset1:246
	s_and_saveexec_b64 s[0:1], s[2:3]
	ds_write_b128 v218, v[52:55]
	s_or_b64 exec, exec, s[0:1]
	v_add_u32_e32 v77, v153, v148
	s_waitcnt lgkmcnt(0)
	v_add_u32_e32 v74, 0x1000, v77
	ds_read2_b64 v[52:55], v74 offset1:65
	ds_read2_b64 v[78:81], v74 offset0:130 offset1:195
	v_mul_f32_e32 v106, v60, v65
	v_mul_f32_e32 v65, v62, v65
	v_add_u32_e32 v75, 0x1800, v77
	v_add_u32_e32 v76, 0x2000, v77
	v_add_u32_e32 v77, 0x2800, v77
	v_fma_f32 v106, v62, v64, -v106
	v_fmac_f32_e32 v65, v60, v64
	ds_read2_b64 v[82:85], v75 offset0:4 offset1:69
	ds_read2_b64 v[86:89], v75 offset0:134 offset1:199
	ds_read2_b64 v[90:93], v76 offset0:8 offset1:73
	ds_read2_b64 v[94:97], v76 offset0:138 offset1:203
	ds_read2_b64 v[98:101], v77 offset0:12 offset1:77
	ds_read2_b64 v[102:105], v77 offset0:142 offset1:207
	s_waitcnt lgkmcnt(7)
	v_add_f32_e32 v52, v106, v52
	v_add_f32_e32 v53, v65, v53
	v_cvt_pk_bf16_f32 v64, v52, v53
	ds_write_b32 v220, v64 offset:12416
	v_mul_f32_e32 v64, v60, v53
	v_fma_f32 v64, v62, v52, -v64
	v_mul_f32_e32 v52, v60, v52
	v_fmac_f32_e32 v52, v62, v53
	v_add_f32_e32 v54, v54, v64
	v_add_f32_e32 v52, v55, v52
	v_cvt_pk_bf16_f32 v53, v54, v52
	ds_write_b32 v220, v53 offset:12688
	v_mul_f32_e32 v53, v60, v52
	v_fma_f32 v53, v62, v54, -v53
	v_mul_f32_e32 v54, v60, v54
	v_fmac_f32_e32 v54, v62, v52
	s_waitcnt lgkmcnt(8)
	v_add_f32_e32 v53, v78, v53
	v_add_f32_e32 v52, v79, v54
	v_cvt_pk_bf16_f32 v54, v53, v52
	ds_write_b32 v220, v54 offset:12960
	v_mul_f32_e32 v54, v60, v52
	v_fma_f32 v54, v62, v53, -v54
	v_mul_f32_e32 v53, v60, v53
	v_fmac_f32_e32 v53, v62, v52
	v_add_f32_e32 v54, v80, v54
	v_add_f32_e32 v52, v81, v53
	v_cvt_pk_bf16_f32 v53, v54, v52
	ds_write_b32 v220, v53 offset:13232
	v_mul_f32_e32 v53, v60, v52
	v_fma_f32 v53, v62, v54, -v53
	v_mul_f32_e32 v54, v60, v54
	v_fmac_f32_e32 v54, v62, v52
	s_waitcnt lgkmcnt(9)
	v_add_f32_e32 v53, v82, v53
	v_add_f32_e32 v52, v83, v54
	v_cvt_pk_bf16_f32 v54, v53, v52
	ds_write_b32 v220, v54 offset:13504
	v_mul_f32_e32 v54, v60, v52
	v_fma_f32 v54, v62, v53, -v54
	v_mul_f32_e32 v53, v60, v53
	v_fmac_f32_e32 v53, v62, v52
	v_add_f32_e32 v54, v84, v54
	v_add_f32_e32 v52, v85, v53
	v_cvt_pk_bf16_f32 v53, v54, v52
	ds_write_b32 v220, v53 offset:13776
	v_mul_f32_e32 v53, v60, v52
	v_fma_f32 v53, v62, v54, -v53
	v_mul_f32_e32 v54, v60, v54
	v_fmac_f32_e32 v54, v62, v52
	s_waitcnt lgkmcnt(10)
; __device__ __forceinline__ unsigned cvt_pk_bf16(float lo, float hi) { unsigned r; asm volatile("v_cvt_pk_bf16_f32 %0, %1, %2" : "=v"(r) : "v"(lo), "v"(hi)); return r; }
; __device__ __forceinline__ bf16_t f2bf(float f) { unsigned u = __float_as_uint(f); u += 0x7FFFu + ((u >> 16) & 1u); return (bf16_t)(u >> 16); }
; __device__ __forceinline__ float bf2f(bf16_t b) { return __uint_as_float(((unsigned)b) << 16); }
; __device__ __forceinline__ float gelu_tanh(float x) { const float z = 1.5957691216057308f * (x + 0.044715f * x * x * x); return x * sigmoidf_(z); }
; __device__ __forceinline__ f32x4 mfma16(bf16x8 a, bf16x8 b, f32x4 c) { return __builtin_amdgcn_mfma_f32_16x16x32_bf16(a, b, c, 0, 0, 0); }
; template <int MODE>
; __device__ __forceinline__ void s5_unit(const Params& P, unsigned char* wl, const int id) {
;     ...
;             f32x2 bb[16];
; #pragma unroll
;             for (int t = 0; t < 16; ++t) bb[t] = *(const f32x2*)(buf + t * 130 + 2 * lane);
; #pragma unroll
;             for (int t = 0; t < 16; ++t) { const float nr_ = ar * hr - ai * hi + bb[t].x, ni_ = ar * hi + ai * hr + bb[t].y; hr = nr_; hi = ni_;
;                 if (MODE == 1) Hw[t * 68 + lane] = cvt_pk_bf16(hr, hi); }
;         }
;         if (MODE >= 1) {
;             asm volatile("s_waitcnt lgkmcnt(0)" ::: "memory");
;             f32x4 acc = (f32x4){0.f, 0.f, 0.f, 0.f};
; #pragma unroll
;             for (int ks = 0; ks < 4; ++ks) acc = mfma16(*(const bf16x8*)((const bf16_t*)Hw + l16 * 136 + 32 * ks + 8 * q), cf[ks], acc);
;             __builtin_amdgcn_sched_barrier(0); asm volatile("s_nop 15\n\ts_nop 15" : "+v"(acc) :: "memory"); __builtin_amdgcn_sched_barrier(0);
;             const bf16_t* up = Ub + (4 * q) * 16 + l16; bf16_t* gp = G + (size_t)(row0 + blk * 16 + 4 * q) * 1024 + g * 16 + l16;
; #pragma unroll
;             for (int r = 0; r < 4; ++r) { const float y = acc[r] + dsk * bf2f(up[r * 16]); gp[r * 1024] = f2bf(gelu_tanh(y)); }
;         }
;         asm volatile("s_waitcnt lgkmcnt(0)" ::: "memory");
;         a_cur = a_nxt;
	v_add_f32_e32 v53, v86, v53
	v_add_f32_e32 v52, v87, v54
	v_cvt_pk_bf16_f32 v54, v53, v52
	ds_write_b32 v220, v54 offset:14048
	v_mul_f32_e32 v54, v60, v52
	v_fma_f32 v54, v62, v53, -v54
	v_mul_f32_e32 v53, v60, v53
	v_fmac_f32_e32 v53, v62, v52
	v_add_f32_e32 v54, v88, v54
	v_add_f32_e32 v52, v89, v53
	v_cvt_pk_bf16_f32 v53, v54, v52
	ds_write_b32 v220, v53 offset:14320
	v_mul_f32_e32 v53, v60, v52
	v_fma_f32 v53, v62, v54, -v53
	v_mul_f32_e32 v54, v60, v54
	v_fmac_f32_e32 v54, v62, v52
	s_waitcnt lgkmcnt(11)
	v_add_f32_e32 v53, v90, v53
	v_add_f32_e32 v52, v91, v54
	v_cvt_pk_bf16_f32 v54, v53, v52
	ds_write_b32 v220, v54 offset:14592
	v_mul_f32_e32 v54, v60, v52
	v_fma_f32 v54, v62, v53, -v54
	v_mul_f32_e32 v53, v60, v53
	v_fmac_f32_e32 v53, v62, v52
	v_add_f32_e32 v54, v92, v54
	v_add_f32_e32 v52, v93, v53
	v_cvt_pk_bf16_f32 v53, v54, v52
	ds_write_b32 v220, v53 offset:14864
	v_mul_f32_e32 v53, v60, v52
	v_fma_f32 v53, v62, v54, -v53
	v_mul_f32_e32 v54, v60, v54
	v_fmac_f32_e32 v54, v62, v52
	s_waitcnt lgkmcnt(12)
	v_add_f32_e32 v53, v94, v53
	v_add_f32_e32 v52, v95, v54
	v_cvt_pk_bf16_f32 v54, v53, v52
	ds_write_b32 v220, v54 offset:15136
	v_mul_f32_e32 v54, v60, v52
	v_fma_f32 v54, v62, v53, -v54
	v_mul_f32_e32 v53, v60, v53
	v_fmac_f32_e32 v53, v62, v52
	v_add_f32_e32 v54, v96, v54
	v_add_f32_e32 v55, v97, v53
	v_cvt_pk_bf16_f32 v52, v54, v55
	ds_write_b32 v220, v52 offset:15408
	v_mul_f32_e32 v52, v60, v55
	v_mul_f32_e32 v53, v60, v54
	v_fma_f32 v52, v62, v54, -v52
	v_fmac_f32_e32 v53, v62, v55
	s_waitcnt lgkmcnt(13)
	v_pk_add_f32 v[52:53], v[98:99], v[52:53]
	s_nop 0
	v_cvt_pk_bf16_f32 v54, v52, v53
	ds_write_b32 v220, v54 offset:15680
	v_pk_mul_f32 v[54:55], v[60:61], v[52:53]
	s_nop 0
	v_pk_fma_f32 v[64:65], v[62:63], v[52:53], v[54:55] op_sel:[0,0,1] op_sel_hi:[1,1,0] neg_lo:[0,0,1] neg_hi:[0,0,1]
	v_pk_fma_f32 v[52:53], v[62:63], v[52:53], v[54:55] op_sel:[0,0,1] op_sel_hi:[1,1,0]
	s_nop 0
	v_mov_b32_e32 v65, v53
	v_pk_add_f32 v[52:53], v[100:101], v[64:65]
	s_nop 0
	v_cvt_pk_bf16_f32 v54, v52, v53
	ds_write_b32 v220, v54 offset:15952
	v_pk_mul_f32 v[54:55], v[60:61], v[52:53]
	s_nop 0
	v_pk_fma_f32 v[64:65], v[62:63], v[52:53], v[54:55] op_sel:[0,0,1] op_sel_hi:[1,1,0] neg_lo:[0,0,1] neg_hi:[0,0,1]
	v_pk_fma_f32 v[52:53], v[62:63], v[52:53], v[54:55] op_sel:[0,0,1] op_sel_hi:[1,1,0]
	s_nop 0
	v_mov_b32_e32 v65, v53
	s_waitcnt lgkmcnt(14)
	v_pk_add_f32 v[52:53], v[102:103], v[64:65]
	s_nop 0
	v_cvt_pk_bf16_f32 v54, v52, v53
	ds_write_b32 v220, v54 offset:16224
	v_pk_mul_f32 v[54:55], v[60:61], v[52:53]
	s_nop 0
	v_pk_fma_f32 v[64:65], v[62:63], v[52:53], v[54:55] op_sel:[0,0,1] op_sel_hi:[1,1,0] neg_lo:[0,0,1] neg_hi:[0,0,1]
	v_pk_fma_f32 v[52:53], v[62:63], v[52:53], v[54:55] op_sel:[0,0,1] op_sel_hi:[1,1,0]
	s_nop 0
	v_mov_b32_e32 v65, v53
	v_pk_add_f32 v[64:65], v[104:105], v[64:65]
	s_nop 0
	v_cvt_pk_bf16_f32 v52, v64, v65
	ds_write_b32 v220, v52 offset:16496
	s_waitcnt lgkmcnt(0)
	ds_read_b128 v[52:55], v219 offset:12416
	ds_read_b128 v[78:81], v219 offset:12480
	s_waitcnt lgkmcnt(1)
	v_mfma_f32_16x16x32_bf16 v[52:55], v[52:55], v[32:35], 0
	ds_read_b128 v[82:85], v219 offset:12544
	s_waitcnt lgkmcnt(1)
	v_mfma_f32_16x16x32_bf16 v[52:55], v[78:81], v[36:39], v[52:55]
	ds_read_b128 v[78:81], v219 offset:12608
	s_waitcnt lgkmcnt(1)
	v_mfma_f32_16x16x32_bf16 v[52:55], v[82:85], v[40:43], v[52:55]
	s_waitcnt lgkmcnt(0)
	v_mfma_f32_16x16x32_bf16 v[52:55], v[78:81], v[44:47], v[52:55]
	s_nop 15
	s_nop 15
	ds_read_u16 v80, v233
	ds_read_u16 v81, v233 offset:32
	v_add_u32_e32 v78, s8, v72
	v_ashrrev_i32_e32 v79, 31, v78
	v_lshlrev_b64 v[78:79], 11, v[78:79]
	s_waitcnt lgkmcnt(1)
	v_lshlrev_b32_e32 v80, 16, v80
	s_nop 0
	v_fma_f32 v52, v70, v80, v52
	v_mul_f32_e32 v80, 0x3d372713, v52
	v_mul_f32_e32 v80, v52, v80
	v_fma_f32 v80, v52, v80, v52
	v_mul_f32_e32 v80, 0x3fcc422a, v80
	v_mul_f32_e32 v80, 0xbfb8aa3b, v80
	v_exp_f32_e32 v80, v80
	v_lshl_add_u64 v[78:79], v[56:57], 0, v[78:79]
	s_add_i32 s8, s8, 16
	s_mov_b64 s[0:1], 0x48000
	v_add_f32_e32 v80, 1.0, v80
	v_rcp_f32_e32 v80, v80
	v_lshl_add_u64 v[58:59], v[58:59], 0, s[0:1]
	s_cmpk_eq_i32 s8, 0x70
	v_mul_f32_e32 v52, v52, v80
	v_bfe_u32 v80, v52, 16, 1
	v_add3_u32 v52, v52, v80, s47
	global_store_short_d16_hi v[78:79], v52, off
	s_waitcnt lgkmcnt(0)
	v_lshlrev_b32_e32 v52, 16, v81
	v_fma_f32 v52, v70, v52, v53
	v_mul_f32_e32 v53, 0x3d372713, v52
	v_mul_f32_e32 v53, v52, v53
	v_fma_f32 v53, v52, v53, v52
	v_mul_f32_e32 v53, 0x3fcc422a, v53
	v_mul_f32_e32 v53, 0xbfb8aa3b, v53
	v_exp_f32_e32 v53, v53
	s_nop 0
	v_add_f32_e32 v53, 1.0, v53
	v_rcp_f32_e32 v53, v53
	s_nop 0
	v_mul_f32_e32 v52, v52, v53
	v_bfe_u32 v53, v52, 16, 1
	v_add3_u32 v52, v52, v53, s47
	global_store_short_d16_hi v[78:79], v52, off offset:2048
	ds_read_u16 v52, v233 offset:64
	s_waitcnt lgkmcnt(0)
	v_lshlrev_b32_e32 v52, 16, v52
	v_fma_f32 v52, v70, v52, v54
	v_mul_f32_e32 v53, 0x3d372713, v52
	v_mul_f32_e32 v53, v52, v53
	v_fma_f32 v53, v52, v53, v52
	v_mul_f32_e32 v53, 0x3fcc422a, v53
	v_mul_f32_e32 v53, 0xbfb8aa3b, v53
	v_exp_f32_e32 v53, v53
	s_nop 0
	v_add_f32_e32 v53, 1.0, v53
	v_rcp_f32_e32 v53, v53
	s_nop 0
	v_mul_f32_e32 v52, v52, v53
	v_bfe_u32 v53, v52, 16, 1
	v_add3_u32 v54, v52, v53, s47
	v_add_co_u32_e32 v52, vcc, s29, v78
	s_nop 1
	v_addc_co_u32_e32 v53, vcc, 0, v79, vcc
	global_store_short_d16_hi v[52:53], v54, off
	ds_read_u16 v54, v233 offset:96
	s_waitcnt lgkmcnt(0)
	v_lshlrev_b32_e32 v54, 16, v54
	v_fmac_f32_e32 v55, v70, v54
	v_mul_f32_e32 v54, 0x3d372713, v55
	v_mul_f32_e32 v54, v55, v54
	v_fma_f32 v54, v55, v54, v55
	v_mul_f32_e32 v54, 0x3fcc422a, v54
	v_mul_f32_e32 v54, 0xbfb8aa3b, v54
	v_exp_f32_e32 v54, v54
	s_nop 0
	v_add_f32_e32 v54, 1.0, v54
	v_rcp_f32_e32 v54, v54
	s_nop 0
	v_mul_f32_e32 v54, v55, v54
	v_bfe_u32 v55, v54, 16, 1
	v_add3_u32 v54, v54, v55, s47
	global_store_short_d16_hi v[52:53], v54, off offset:2048
	s_waitcnt lgkmcnt(0)
	s_cbranch_scc1 .LBB0_459
	s_waitcnt vmcnt(4)
	v_mov_b64_e32 v[54:55], v[50:51]
	v_mov_b64_e32 v[52:53], v[48:49]
	s_branch .LBB0_455
